# attention loop: DMA via SGPR base (no address VALU, m0 fillers), position base reuse, control flow with fewer taken branches; GEMM loops: duplicate lgkmcnt(0) dropped
# speedup vs baseline: 1.0152x; 1.0109x over previous
.LBB0_35:
	s_add_u32 s0, s8, 0xfff80080
	s_addc_u32 s1, s9, -1
	s_add_i32 s2, 0, 0x10000
	v_add_u32_e32 v138, s2, v182
	ds_read_b128 v[154:157], v138
	ds_read_b128 v[158:161], v138 offset:1024
	ds_read_b128 v[162:165], v138 offset:2048
	ds_read_b128 v[166:169], v138 offset:3072
	s_cmp_eq_u32 s15, 28
	s_cselect_b32 s65, s67, s1
	s_cselect_b32 s64, s66, s0
	s_cselect_b32 s1, s45, s13
	s_cselect_b32 s0, s44, s11
	s_add_i32 m0, s17, 0xc000
	ds_read_b128 v[170:173], v183
	ds_read_b128 v[174:177], v183 offset:1024
	ds_read_b128 v[178:181], v183 offset:2048
	ds_read_b128 v[184:187], v183 offset:3072
	ds_read_b128 v[188:191], v183 offset:4096
	ds_read_b128 v[192:195], v183 offset:5120
	ds_read_b128 v[196:199], v183 offset:6144
	ds_read_b128 v[200:203], v183 offset:7168
	global_load_lds_dwordx4 v136, s[8:9]
	s_add_i32 m0, s17, 0xe000
	s_nop 0
	global_load_lds_dwordx4 v134, s[8:9]
	s_waitcnt lgkmcnt(8)
	s_barrier
	s_waitcnt lgkmcnt(0)
	s_setprio 1
	v_mfma_f32_16x16x32_bf16 v[124:127], v[154:157], v[170:173], v[124:127]
	v_mfma_f32_16x16x32_bf16 v[92:95], v[162:165], v[170:173], v[92:95]
	v_mfma_f32_16x16x32_bf16 v[120:123], v[154:157], v[178:181], v[120:123]
	v_mfma_f32_16x16x32_bf16 v[88:91], v[162:165], v[178:181], v[88:91]
	v_mfma_f32_16x16x32_bf16 v[116:119], v[154:157], v[188:191], v[116:119]
	v_mfma_f32_16x16x32_bf16 v[84:87], v[162:165], v[188:191], v[84:87]
	v_mfma_f32_16x16x32_bf16 v[112:115], v[154:157], v[196:199], v[112:115]
	v_mfma_f32_16x16x32_bf16 v[80:83], v[162:165], v[196:199], v[80:83]
	v_mfma_f32_16x16x32_bf16 v[124:127], v[158:161], v[174:177], v[124:127]
	v_mfma_f32_16x16x32_bf16 v[92:95], v[166:169], v[174:177], v[92:95]
	v_mfma_f32_16x16x32_bf16 v[120:123], v[158:161], v[184:187], v[120:123]
	v_mfma_f32_16x16x32_bf16 v[88:91], v[166:169], v[184:187], v[88:91]
	v_mfma_f32_16x16x32_bf16 v[116:119], v[158:161], v[192:195], v[116:119]
	v_mfma_f32_16x16x32_bf16 v[84:87], v[166:169], v[192:195], v[84:87]
	v_mfma_f32_16x16x32_bf16 v[112:115], v[158:161], v[200:203], v[112:115]
	v_mfma_f32_16x16x32_bf16 v[80:83], v[166:169], v[200:203], v[80:83]
	s_setprio 0
	s_barrier
	s_add_i32 s20, 0, 0x14000
	v_add_u32_e32 v138, s20, v182
	s_add_i32 s2, s2, s69
	ds_read_b128 v[204:207], v138
	ds_read_b128 v[208:211], v138 offset:1024
	ds_read_b128 v[228:231], v138 offset:2048
	ds_read_b128 v[232:235], v138 offset:3072
	s_mov_b32 m0, s2
	s_nop 0
	global_load_lds_dwordx4 v140, s[0:1]
	s_add_i32 m0, s2, 0x2000
	s_nop 0
	global_load_lds_dwordx4 v132, s[0:1]
	s_barrier
	s_waitcnt lgkmcnt(0)
	s_setprio 1
	v_mfma_f32_16x16x32_bf16 v[60:63], v[204:207], v[170:173], v[60:63]
	v_mfma_f32_16x16x32_bf16 v[28:31], v[228:231], v[170:173], v[28:31]
	v_mfma_f32_16x16x32_bf16 v[56:59], v[204:207], v[178:181], v[56:59]
	v_mfma_f32_16x16x32_bf16 v[24:27], v[228:231], v[178:181], v[24:27]
	v_mfma_f32_16x16x32_bf16 v[52:55], v[204:207], v[188:191], v[52:55]
	v_mfma_f32_16x16x32_bf16 v[20:23], v[228:231], v[188:191], v[20:23]
	v_mfma_f32_16x16x32_bf16 v[48:51], v[204:207], v[196:199], v[48:51]
	v_mfma_f32_16x16x32_bf16 v[16:19], v[228:231], v[196:199], v[16:19]
	v_mfma_f32_16x16x32_bf16 v[60:63], v[208:211], v[174:177], v[60:63]
	v_mfma_f32_16x16x32_bf16 v[28:31], v[232:235], v[174:177], v[28:31]
	v_mfma_f32_16x16x32_bf16 v[56:59], v[208:211], v[184:187], v[56:59]
	v_mfma_f32_16x16x32_bf16 v[24:27], v[232:235], v[184:187], v[24:27]
	v_mfma_f32_16x16x32_bf16 v[52:55], v[208:211], v[192:195], v[52:55]
	v_mfma_f32_16x16x32_bf16 v[20:23], v[232:235], v[192:195], v[20:23]
	v_mfma_f32_16x16x32_bf16 v[48:51], v[208:211], v[200:203], v[48:51]
	v_mfma_f32_16x16x32_bf16 v[16:19], v[232:235], v[200:203], v[16:19]
	s_setprio 0
	s_mov_b32 m0, s17
	s_barrier
	ds_read_b128 v[170:173], v183 offset:16384
	ds_read_b128 v[174:177], v183 offset:17408
	ds_read_b128 v[178:181], v183 offset:18432
	ds_read_b128 v[184:187], v183 offset:19456
	ds_read_b128 v[188:191], v183 offset:20480
	ds_read_b128 v[192:195], v183 offset:21504
	ds_read_b128 v[196:199], v183 offset:22528
	ds_read_b128 v[200:203], v183 offset:23552
	global_load_lds_dwordx4 v128, s[64:65]
	s_mov_b32 m0, s71
	s_nop 0
	global_load_lds_dwordx4 v130, s[64:65]
	s_barrier
	s_waitcnt lgkmcnt(0)
	s_setprio 1
	v_mfma_f32_16x16x32_bf16 v[108:111], v[154:157], v[170:173], v[108:111]
	v_mfma_f32_16x16x32_bf16 v[76:79], v[162:165], v[170:173], v[76:79]
	v_mfma_f32_16x16x32_bf16 v[104:107], v[154:157], v[178:181], v[104:107]
	v_mfma_f32_16x16x32_bf16 v[72:75], v[162:165], v[178:181], v[72:75]
	v_mfma_f32_16x16x32_bf16 v[100:103], v[154:157], v[188:191], v[100:103]
	v_mfma_f32_16x16x32_bf16 v[68:71], v[162:165], v[188:191], v[68:71]
	v_mfma_f32_16x16x32_bf16 v[96:99], v[154:157], v[196:199], v[96:99]
	v_mfma_f32_16x16x32_bf16 v[64:67], v[162:165], v[196:199], v[64:67]
	v_mfma_f32_16x16x32_bf16 v[108:111], v[158:161], v[174:177], v[108:111]
	v_mfma_f32_16x16x32_bf16 v[76:79], v[166:169], v[174:177], v[76:79]
	v_mfma_f32_16x16x32_bf16 v[104:107], v[158:161], v[184:187], v[104:107]
	v_mfma_f32_16x16x32_bf16 v[72:75], v[166:169], v[184:187], v[72:75]
	v_mfma_f32_16x16x32_bf16 v[100:103], v[158:161], v[192:195], v[100:103]
	v_mfma_f32_16x16x32_bf16 v[68:71], v[166:169], v[192:195], v[68:71]
	v_mfma_f32_16x16x32_bf16 v[96:99], v[158:161], v[200:203], v[96:99]
	v_mfma_f32_16x16x32_bf16 v[64:67], v[166:169], v[200:203], v[64:67]
	s_setprio 0
	s_barrier
	s_add_u32 s18, s0, 0x100000
	s_addc_u32 s19, s1, 0
	s_add_i32 s2, s20, s69
	s_mov_b32 m0, s2
	s_nop 0
	global_load_lds_dwordx4 v140, s[18:19]
	s_add_i32 m0, s2, 0x2000
	s_nop 0
	global_load_lds_dwordx4 v132, s[18:19]
	s_waitcnt vmcnt(6)
	s_barrier
	s_setprio 1
	v_mfma_f32_16x16x32_bf16 v[44:47], v[204:207], v[170:173], v[44:47]
	v_mfma_f32_16x16x32_bf16 v[12:15], v[228:231], v[170:173], v[12:15]
	v_mfma_f32_16x16x32_bf16 v[40:43], v[204:207], v[178:181], v[40:43]
	v_mfma_f32_16x16x32_bf16 v[8:11], v[228:231], v[178:181], v[8:11]
	v_mfma_f32_16x16x32_bf16 v[36:39], v[204:207], v[188:191], v[36:39]
	v_mfma_f32_16x16x32_bf16 v[4:7], v[228:231], v[188:191], v[4:7]
	v_mfma_f32_16x16x32_bf16 v[32:35], v[204:207], v[196:199], v[32:35]
	v_mfma_f32_16x16x32_bf16 v[0:3], v[228:231], v[196:199], v[0:3]
	v_mfma_f32_16x16x32_bf16 v[44:47], v[208:211], v[174:177], v[44:47]
	v_mfma_f32_16x16x32_bf16 v[12:15], v[232:235], v[174:177], v[12:15]
	v_mfma_f32_16x16x32_bf16 v[40:43], v[208:211], v[184:187], v[40:43]
	v_mfma_f32_16x16x32_bf16 v[8:11], v[232:235], v[184:187], v[8:11]
	v_mfma_f32_16x16x32_bf16 v[36:39], v[208:211], v[192:195], v[36:39]
	v_mfma_f32_16x16x32_bf16 v[4:7], v[232:235], v[192:195], v[4:7]
	v_mfma_f32_16x16x32_bf16 v[32:35], v[208:211], v[200:203], v[32:35]
	v_mfma_f32_16x16x32_bf16 v[0:3], v[232:235], v[200:203], v[0:3]
	s_setprio 0
	s_add_i32 s2, 0, 0x18000
	v_add_u32_e32 v166, s2, v182
	s_barrier
	ds_read_b128 v[154:157], v166
	ds_read_b128 v[158:161], v166 offset:1024
	ds_read_b128 v[162:165], v166 offset:2048
	ds_read_b128 v[166:169], v166 offset:3072
	s_add_u32 s18, s64, 0x80000
	s_addc_u32 s19, s65, 0
	s_mov_b32 m0, s72
	ds_read_b128 v[170:173], v183 offset:32768
	ds_read_b128 v[174:177], v183 offset:33792
	ds_read_b128 v[178:181], v183 offset:34816
	ds_read_b128 v[184:187], v183 offset:35840
	ds_read_b128 v[188:191], v183 offset:36864
	ds_read_b128 v[192:195], v183 offset:37888
	ds_read_b128 v[196:199], v183 offset:38912
	ds_read_b128 v[200:203], v183 offset:39936
	global_load_lds_dwordx4 v128, s[18:19]
	s_mov_b32 m0, s73
	s_nop 0
	global_load_lds_dwordx4 v130, s[18:19]
	s_waitcnt lgkmcnt(8)
	s_barrier
	s_waitcnt lgkmcnt(0)
	s_setprio 1
	v_mfma_f32_16x16x32_bf16 v[124:127], v[154:157], v[170:173], v[124:127]
	v_mfma_f32_16x16x32_bf16 v[92:95], v[162:165], v[170:173], v[92:95]
	v_mfma_f32_16x16x32_bf16 v[120:123], v[154:157], v[178:181], v[120:123]
	v_mfma_f32_16x16x32_bf16 v[88:91], v[162:165], v[178:181], v[88:91]
	v_mfma_f32_16x16x32_bf16 v[116:119], v[154:157], v[188:191], v[116:119]
	v_mfma_f32_16x16x32_bf16 v[84:87], v[162:165], v[188:191], v[84:87]
	v_mfma_f32_16x16x32_bf16 v[112:115], v[154:157], v[196:199], v[112:115]
	v_mfma_f32_16x16x32_bf16 v[80:83], v[162:165], v[196:199], v[80:83]
	v_mfma_f32_16x16x32_bf16 v[124:127], v[158:161], v[174:177], v[124:127]
	v_mfma_f32_16x16x32_bf16 v[92:95], v[166:169], v[174:177], v[92:95]
	v_mfma_f32_16x16x32_bf16 v[120:123], v[158:161], v[184:187], v[120:123]
	v_mfma_f32_16x16x32_bf16 v[88:91], v[166:169], v[184:187], v[88:91]
	v_mfma_f32_16x16x32_bf16 v[116:119], v[158:161], v[192:195], v[116:119]
	v_mfma_f32_16x16x32_bf16 v[84:87], v[166:169], v[192:195], v[84:87]
	v_mfma_f32_16x16x32_bf16 v[112:115], v[158:161], v[200:203], v[112:115]
	v_mfma_f32_16x16x32_bf16 v[80:83], v[166:169], v[200:203], v[80:83]
	s_setprio 0
	s_barrier
	s_add_i32 s18, 0, 0x1c000
	s_add_i32 s2, s2, s69
	v_add_u32_e32 v232, s18, v182
	s_mov_b32 m0, s2
	ds_read_b128 v[204:207], v232
	ds_read_b128 v[208:211], v232 offset:1024
	ds_read_b128 v[228:231], v232 offset:2048
	ds_read_b128 v[232:235], v232 offset:3072
	s_add_u32 s100, s0, 0x80
	s_addc_u32 s101, s1, 0
	global_load_lds_dwordx4 v140, s[100:101]
	s_add_i32 m0, s2, 0x2000
	s_nop 0
	global_load_lds_dwordx4 v132, s[100:101]
	s_barrier
	s_waitcnt lgkmcnt(0)
	s_setprio 1
	v_mfma_f32_16x16x32_bf16 v[60:63], v[204:207], v[170:173], v[60:63]
	v_mfma_f32_16x16x32_bf16 v[28:31], v[228:231], v[170:173], v[28:31]
	v_mfma_f32_16x16x32_bf16 v[56:59], v[204:207], v[178:181], v[56:59]
	v_mfma_f32_16x16x32_bf16 v[24:27], v[228:231], v[178:181], v[24:27]
	v_mfma_f32_16x16x32_bf16 v[52:55], v[204:207], v[188:191], v[52:55]
	v_mfma_f32_16x16x32_bf16 v[20:23], v[228:231], v[188:191], v[20:23]
	v_mfma_f32_16x16x32_bf16 v[48:51], v[204:207], v[196:199], v[48:51]
	v_mfma_f32_16x16x32_bf16 v[16:19], v[228:231], v[196:199], v[16:19]
	v_mfma_f32_16x16x32_bf16 v[60:63], v[208:211], v[174:177], v[60:63]
	v_mfma_f32_16x16x32_bf16 v[28:31], v[232:235], v[174:177], v[28:31]
	v_mfma_f32_16x16x32_bf16 v[56:59], v[208:211], v[184:187], v[56:59]
	v_mfma_f32_16x16x32_bf16 v[24:27], v[232:235], v[184:187], v[24:27]
	v_mfma_f32_16x16x32_bf16 v[52:55], v[208:211], v[192:195], v[52:55]
	v_mfma_f32_16x16x32_bf16 v[20:23], v[232:235], v[192:195], v[20:23]
	v_mfma_f32_16x16x32_bf16 v[48:51], v[208:211], v[200:203], v[48:51]
	v_mfma_f32_16x16x32_bf16 v[16:19], v[232:235], v[200:203], v[16:19]
	s_setprio 0
	s_mov_b32 m0, s77
	s_barrier
	ds_read_b128 v[170:173], v183 offset:49152
	ds_read_b128 v[174:177], v183 offset:50176
	ds_read_b128 v[178:181], v183 offset:51200
	ds_read_b128 v[184:187], v183 offset:52224
	ds_read_b128 v[188:191], v183 offset:53248
	ds_read_b128 v[192:195], v183 offset:54272
	ds_read_b128 v[196:199], v183 offset:55296
	ds_read_b128 v[200:203], v183 offset:56320
	s_add_u32 s100, s64, 0x80
	s_addc_u32 s101, s65, 0
	global_load_lds_dwordx4 v128, s[100:101]
	s_mov_b32 m0, s80
	s_nop 0
	global_load_lds_dwordx4 v130, s[100:101]
	s_barrier
	s_waitcnt lgkmcnt(0)
	s_setprio 1
	v_mfma_f32_16x16x32_bf16 v[108:111], v[154:157], v[170:173], v[108:111]
	v_mfma_f32_16x16x32_bf16 v[76:79], v[162:165], v[170:173], v[76:79]
	v_mfma_f32_16x16x32_bf16 v[104:107], v[154:157], v[178:181], v[104:107]
	v_mfma_f32_16x16x32_bf16 v[72:75], v[162:165], v[178:181], v[72:75]
	v_mfma_f32_16x16x32_bf16 v[100:103], v[154:157], v[188:191], v[100:103]
	v_mfma_f32_16x16x32_bf16 v[68:71], v[162:165], v[188:191], v[68:71]
	v_mfma_f32_16x16x32_bf16 v[96:99], v[154:157], v[196:199], v[96:99]
	v_mfma_f32_16x16x32_bf16 v[64:67], v[162:165], v[196:199], v[64:67]
	v_mfma_f32_16x16x32_bf16 v[108:111], v[158:161], v[174:177], v[108:111]
	v_mfma_f32_16x16x32_bf16 v[76:79], v[166:169], v[174:177], v[76:79]
	v_mfma_f32_16x16x32_bf16 v[104:107], v[158:161], v[184:187], v[104:107]
	v_mfma_f32_16x16x32_bf16 v[72:75], v[166:169], v[184:187], v[72:75]
	v_mfma_f32_16x16x32_bf16 v[100:103], v[158:161], v[192:195], v[100:103]
	v_mfma_f32_16x16x32_bf16 v[68:71], v[166:169], v[192:195], v[68:71]
	v_mfma_f32_16x16x32_bf16 v[96:99], v[158:161], v[200:203], v[96:99]
	v_mfma_f32_16x16x32_bf16 v[64:67], v[166:169], v[200:203], v[64:67]
	s_setprio 0
	s_barrier
	s_add_u32 s0, s0, 0x100080
	s_addc_u32 s1, s1, 0
	s_add_i32 s2, s18, s69
	s_mov_b32 m0, s2
	s_nop 0
	global_load_lds_dwordx4 v140, s[0:1]
	s_add_i32 m0, s2, 0x2000
	s_nop 0
	global_load_lds_dwordx4 v132, s[0:1]
	s_waitcnt vmcnt(6)
	s_barrier
	s_setprio 1
	v_mfma_f32_16x16x32_bf16 v[44:47], v[204:207], v[170:173], v[44:47]
	v_mfma_f32_16x16x32_bf16 v[12:15], v[228:231], v[170:173], v[12:15]
	v_mfma_f32_16x16x32_bf16 v[40:43], v[204:207], v[178:181], v[40:43]
	v_mfma_f32_16x16x32_bf16 v[8:11], v[228:231], v[178:181], v[8:11]
	v_mfma_f32_16x16x32_bf16 v[36:39], v[204:207], v[188:191], v[36:39]
	v_mfma_f32_16x16x32_bf16 v[4:7], v[228:231], v[188:191], v[4:7]
	v_mfma_f32_16x16x32_bf16 v[32:35], v[204:207], v[196:199], v[32:35]
	v_mfma_f32_16x16x32_bf16 v[0:3], v[228:231], v[196:199], v[0:3]
	v_mfma_f32_16x16x32_bf16 v[44:47], v[208:211], v[174:177], v[44:47]
	v_mfma_f32_16x16x32_bf16 v[12:15], v[232:235], v[174:177], v[12:15]
	v_mfma_f32_16x16x32_bf16 v[40:43], v[208:211], v[184:187], v[40:43]
	v_mfma_f32_16x16x32_bf16 v[8:11], v[232:235], v[184:187], v[8:11]
	v_mfma_f32_16x16x32_bf16 v[36:39], v[208:211], v[192:195], v[36:39]
	v_mfma_f32_16x16x32_bf16 v[4:7], v[232:235], v[192:195], v[4:7]
	v_mfma_f32_16x16x32_bf16 v[32:35], v[208:211], v[200:203], v[32:35]
	v_mfma_f32_16x16x32_bf16 v[0:3], v[232:235], v[200:203], v[0:3]
	s_setprio 0
	s_add_i32 s15, s15, 2
	s_add_u32 s11, s11, 0x100
	s_addc_u32 s13, s13, 0
	s_add_u32 s8, s8, 0x100
	s_addc_u32 s9, s9, 0
	s_cmp_gt_u32 s15, 29
	s_barrier
	s_cbranch_scc0 .LBB0_35
	v_mbcnt_lo_u32_b32 v170, -1, 0
	v_mbcnt_hi_u32_b32 v170, -1, v170
	s_lshl_b32 s0, s16, 8
	v_ashrrev_i32_e32 v138, 2, v170
	v_and_b32_e32 v138, -4, v138
	s_or_b32 s0, s0, s75
	v_add_u32_e32 v138, s0, v138
	s_lshl_b32 s0, s88, 10
	s_ashr_i32 s1, s0, 31
	s_lshl_b32 s13, s88, 12
	s_lshl_b32 s15, s88, 11
	s_addk_i32 s13, 0x1000
	s_lshl_b64 s[0:1], s[0:1], 2
	v_and_or_b32 v154, v170, 15, s74
	s_add_u32 s0, s49, s0
	v_ashrrev_i32_e32 v139, 31, v138
	v_lshl_add_u32 v184, s10, 8, v154
	s_addc_u32 s1, s76, s1
	v_lshlrev_b64 v[172:173], 2, v[138:139]
	v_add_u32_e32 v156, s15, v184
	v_lshl_add_u64 v[160:161], s[0:1], 0, v[172:173]
	v_ashrrev_i32_e32 v157, 31, v156
	flat_load_dwordx4 v[162:165], v[160:161]
	v_lshlrev_b64 v[154:155], 12, v[156:157]
	v_lshl_add_u64 v[154:155], s[26:27], 0, v[154:155]
	v_lshl_add_u64 v[158:159], v[154:155], 0, v[172:173]
	flat_load_dwordx4 v[166:169], v[158:159] nt
	s_mov_b32 s0, 0x3c800000
	v_and_b32_e32 v155, 1, v170
	v_add_u32_e32 v156, s15, v156
	v_cmp_eq_u32_e64 s[8:9], 0, v155
	v_ashrrev_i32_e32 v157, 31, v156
	v_lshlrev_b64 v[156:157], 11, v[156:157]
	v_sub_u32_e32 v154, s13, v184
	v_lshl_add_u64 v[156:157], s[24:25], 0, v[156:157]
	v_cmp_ne_u32_e32 vcc, 0, v184
	v_lshl_add_u64 v[156:157], v[138:139], 1, v[156:157]
	s_waitcnt vmcnt(0) lgkmcnt(0)
	v_pk_mul_f32 v[164:165], v[164:165], s[0:1] op_sel_hi:[1,0]
	v_pk_mul_f32 v[162:163], v[162:163], s[0:1] op_sel_hi:[1,0]
	v_xor_b32_e32 v170, 0x80000000, v164
	v_xor_b32_e32 v171, 0x80000000, v165
	v_xor_b32_e32 v174, 0x80000000, v162
	v_xor_b32_e32 v175, 0x80000000, v163
	v_cndmask_b32_e64 v177, v171, v165, s[8:9]
	v_cndmask_b32_e64 v176, v170, v164, s[8:9]
	v_cndmask_b32_e64 v179, v175, v163, s[8:9]
	v_cndmask_b32_e64 v178, v174, v162, s[8:9]
	v_pk_add_f32 v[162:163], v[168:169], v[176:177]
	v_pk_add_f32 v[164:165], v[166:167], v[178:179]
	v_sub_f32_e32 v155, v162, v126
	v_sub_f32_e32 v167, v163, v127
	v_sub_f32_e32 v166, v164, v124
	v_cvt_pk_bf16_f32 v167, v155, v167
	v_ashrrev_i32_e32 v155, 31, v154
	v_sub_f32_e32 v168, v165, v125
	v_cvt_pk_bf16_f32 v166, v166, v168
	flat_store_dwordx2 v[156:157], v[166:167]
	s_and_saveexec_b64 s[0:1], vcc
	s_cbranch_execz .LBB0_38
	v_pk_add_f32 v[126:127], v[126:127], v[162:163]
	v_pk_add_f32 v[124:125], v[124:125], v[164:165]
	s_nop 0
	v_cvt_pk_bf16_f32 v124, v124, v125
	v_cvt_pk_bf16_f32 v125, v126, v127
	v_lshlrev_b64 v[126:127], 11, v[154:155]
	v_lshl_add_u64 v[126:127], s[24:25], 0, v[126:127]
	v_lshl_add_u64 v[126:127], v[138:139], 1, v[126:127]
	flat_store_dwordx2 v[126:127], v[124:125]

.LBB0_96:
	s_add_u32 s0, s40, 0xfffc0080
	s_addc_u32 s1, s41, -1
	s_add_i32 s2, 0, 0x10000
	v_add_u32_e32 v138, s2, v154
	ds_read_b128 v[156:159], v138
	ds_read_b128 v[160:163], v138 offset:1024
	ds_read_b128 v[164:167], v138 offset:2048
	ds_read_b128 v[168:171], v138 offset:3072
	s_cmp_eq_u32 s72, 12
	s_cselect_b32 s45, s13, s1
	s_cselect_b32 s44, s12, s0
	s_cselect_b32 s1, s15, s11
	s_cselect_b32 s0, s14, s9
	s_add_i32 m0, s17, 0xc000
	ds_read_b128 v[172:175], v155
	ds_read_b128 v[176:179], v155 offset:1024
	ds_read_b128 v[180:183], v155 offset:2048
	ds_read_b128 v[184:187], v155 offset:3072
	ds_read_b128 v[188:191], v155 offset:4096
	ds_read_b128 v[192:195], v155 offset:5120
	ds_read_b128 v[196:199], v155 offset:6144
	ds_read_b128 v[200:203], v155 offset:7168
	global_load_lds_dwordx4 v136, s[40:41]
	s_add_i32 m0, s17, 0xe000
	s_nop 0
	global_load_lds_dwordx4 v134, s[40:41]
	s_waitcnt lgkmcnt(8)
	s_barrier
	s_waitcnt lgkmcnt(0)
	s_setprio 1
	v_mfma_f32_16x16x32_bf16 v[124:127], v[156:159], v[172:175], v[124:127]
	v_mfma_f32_16x16x32_bf16 v[120:123], v[164:167], v[172:175], v[120:123]
	v_mfma_f32_16x16x32_bf16 v[116:119], v[156:159], v[180:183], v[116:119]
	v_mfma_f32_16x16x32_bf16 v[108:111], v[164:167], v[180:183], v[108:111]
	v_mfma_f32_16x16x32_bf16 v[100:103], v[156:159], v[188:191], v[100:103]
	v_mfma_f32_16x16x32_bf16 v[92:95], v[164:167], v[188:191], v[92:95]
	v_mfma_f32_16x16x32_bf16 v[84:87], v[156:159], v[196:199], v[84:87]
	v_mfma_f32_16x16x32_bf16 v[76:79], v[164:167], v[196:199], v[76:79]
	v_mfma_f32_16x16x32_bf16 v[124:127], v[160:163], v[176:179], v[124:127]
	v_mfma_f32_16x16x32_bf16 v[120:123], v[168:171], v[176:179], v[120:123]
	v_mfma_f32_16x16x32_bf16 v[116:119], v[160:163], v[184:187], v[116:119]
	v_mfma_f32_16x16x32_bf16 v[108:111], v[168:171], v[184:187], v[108:111]
	v_mfma_f32_16x16x32_bf16 v[100:103], v[160:163], v[192:195], v[100:103]
	v_mfma_f32_16x16x32_bf16 v[92:95], v[168:171], v[192:195], v[92:95]
	v_mfma_f32_16x16x32_bf16 v[84:87], v[160:163], v[200:203], v[84:87]
	v_mfma_f32_16x16x32_bf16 v[76:79], v[168:171], v[200:203], v[76:79]
	s_setprio 0
	s_barrier
	s_add_i32 s30, 0, 0x14000
	v_add_u32_e32 v138, s30, v154
	s_add_i32 s2, s2, s59
	ds_read_b128 v[204:207], v138
	ds_read_b128 v[208:211], v138 offset:1024
	ds_read_b128 v[228:231], v138 offset:2048
	ds_read_b128 v[232:235], v138 offset:3072
	s_mov_b32 m0, s2
	s_nop 0
	global_load_lds_dwordx4 v140, s[0:1]
	s_add_i32 m0, s2, 0x2000
	s_nop 0
	global_load_lds_dwordx4 v132, s[0:1]
	s_barrier
	s_waitcnt lgkmcnt(0)
	s_setprio 1
	v_mfma_f32_16x16x32_bf16 v[112:115], v[204:207], v[172:175], v[112:115]
	v_mfma_f32_16x16x32_bf16 v[104:107], v[228:231], v[172:175], v[104:107]
	v_mfma_f32_16x16x32_bf16 v[96:99], v[204:207], v[180:183], v[96:99]
	v_mfma_f32_16x16x32_bf16 v[88:91], v[228:231], v[180:183], v[88:91]
	v_mfma_f32_16x16x32_bf16 v[80:83], v[204:207], v[188:191], v[80:83]
	v_mfma_f32_16x16x32_bf16 v[72:75], v[228:231], v[188:191], v[72:75]
	v_mfma_f32_16x16x32_bf16 v[68:71], v[204:207], v[196:199], v[68:71]
	v_mfma_f32_16x16x32_bf16 v[64:67], v[228:231], v[196:199], v[64:67]
	v_mfma_f32_16x16x32_bf16 v[112:115], v[208:211], v[176:179], v[112:115]
	v_mfma_f32_16x16x32_bf16 v[104:107], v[232:235], v[176:179], v[104:107]
	v_mfma_f32_16x16x32_bf16 v[96:99], v[208:211], v[184:187], v[96:99]
	v_mfma_f32_16x16x32_bf16 v[88:91], v[232:235], v[184:187], v[88:91]
	v_mfma_f32_16x16x32_bf16 v[80:83], v[208:211], v[192:195], v[80:83]
	v_mfma_f32_16x16x32_bf16 v[72:75], v[232:235], v[192:195], v[72:75]
	v_mfma_f32_16x16x32_bf16 v[68:71], v[208:211], v[200:203], v[68:71]
	v_mfma_f32_16x16x32_bf16 v[64:67], v[232:235], v[200:203], v[64:67]
	s_setprio 0
	s_mov_b32 m0, s17
	s_barrier
	ds_read_b128 v[172:175], v155 offset:16384
	ds_read_b128 v[176:179], v155 offset:17408
	ds_read_b128 v[180:183], v155 offset:18432
	ds_read_b128 v[184:187], v155 offset:19456
	ds_read_b128 v[188:191], v155 offset:20480
	ds_read_b128 v[192:195], v155 offset:21504
	ds_read_b128 v[196:199], v155 offset:22528
	ds_read_b128 v[200:203], v155 offset:23552
	global_load_lds_dwordx4 v128, s[44:45]
	s_mov_b32 m0, s64
	s_nop 0
	global_load_lds_dwordx4 v130, s[44:45]
	s_barrier
	s_waitcnt lgkmcnt(0)
	s_setprio 1
	v_mfma_f32_16x16x32_bf16 v[60:63], v[156:159], v[172:175], v[60:63]
	v_mfma_f32_16x16x32_bf16 v[56:59], v[164:167], v[172:175], v[56:59]
	v_mfma_f32_16x16x32_bf16 v[52:55], v[156:159], v[180:183], v[52:55]
	v_mfma_f32_16x16x32_bf16 v[44:47], v[164:167], v[180:183], v[44:47]
	v_mfma_f32_16x16x32_bf16 v[36:39], v[156:159], v[188:191], v[36:39]
	v_mfma_f32_16x16x32_bf16 v[28:31], v[164:167], v[188:191], v[28:31]
	v_mfma_f32_16x16x32_bf16 v[20:23], v[156:159], v[196:199], v[20:23]
	v_mfma_f32_16x16x32_bf16 v[12:15], v[164:167], v[196:199], v[12:15]
	v_mfma_f32_16x16x32_bf16 v[60:63], v[160:163], v[176:179], v[60:63]
	v_mfma_f32_16x16x32_bf16 v[56:59], v[168:171], v[176:179], v[56:59]
	v_mfma_f32_16x16x32_bf16 v[52:55], v[160:163], v[184:187], v[52:55]
	v_mfma_f32_16x16x32_bf16 v[44:47], v[168:171], v[184:187], v[44:47]
	v_mfma_f32_16x16x32_bf16 v[36:39], v[160:163], v[192:195], v[36:39]
	v_mfma_f32_16x16x32_bf16 v[28:31], v[168:171], v[192:195], v[28:31]
	v_mfma_f32_16x16x32_bf16 v[20:23], v[160:163], v[200:203], v[20:23]
	v_mfma_f32_16x16x32_bf16 v[12:15], v[168:171], v[200:203], v[12:15]
	s_setprio 0
	s_barrier
	s_add_u32 s18, s0, 0x40000
	s_addc_u32 s19, s1, 0
	s_add_i32 s2, s30, s59
	s_mov_b32 m0, s2
	s_nop 0
	global_load_lds_dwordx4 v140, s[18:19]
	s_add_i32 m0, s2, 0x2000
	s_nop 0
	global_load_lds_dwordx4 v132, s[18:19]
	s_waitcnt vmcnt(6)
	s_barrier
	s_setprio 1
	v_mfma_f32_16x16x32_bf16 v[48:51], v[204:207], v[172:175], v[48:51]
	v_mfma_f32_16x16x32_bf16 v[40:43], v[228:231], v[172:175], v[40:43]
	v_mfma_f32_16x16x32_bf16 v[32:35], v[204:207], v[180:183], v[32:35]
	v_mfma_f32_16x16x32_bf16 v[24:27], v[228:231], v[180:183], v[24:27]
	v_mfma_f32_16x16x32_bf16 v[16:19], v[204:207], v[188:191], v[16:19]
	v_mfma_f32_16x16x32_bf16 v[8:11], v[228:231], v[188:191], v[8:11]
	v_mfma_f32_16x16x32_bf16 v[4:7], v[204:207], v[196:199], v[4:7]
	v_mfma_f32_16x16x32_bf16 v[0:3], v[228:231], v[196:199], v[0:3]
	v_mfma_f32_16x16x32_bf16 v[48:51], v[208:211], v[176:179], v[48:51]
	v_mfma_f32_16x16x32_bf16 v[40:43], v[232:235], v[176:179], v[40:43]
	v_mfma_f32_16x16x32_bf16 v[32:35], v[208:211], v[184:187], v[32:35]
	v_mfma_f32_16x16x32_bf16 v[24:27], v[232:235], v[184:187], v[24:27]
	v_mfma_f32_16x16x32_bf16 v[16:19], v[208:211], v[192:195], v[16:19]
	v_mfma_f32_16x16x32_bf16 v[8:11], v[232:235], v[192:195], v[8:11]
	v_mfma_f32_16x16x32_bf16 v[4:7], v[208:211], v[200:203], v[4:7]
	v_mfma_f32_16x16x32_bf16 v[0:3], v[232:235], v[200:203], v[0:3]
	s_setprio 0
	s_add_i32 s2, 0, 0x18000
	v_add_u32_e32 v168, s2, v154
	s_barrier
	ds_read_b128 v[156:159], v168
	ds_read_b128 v[160:163], v168 offset:1024
	ds_read_b128 v[164:167], v168 offset:2048
	ds_read_b128 v[168:171], v168 offset:3072
	s_add_u32 s18, s44, 0x40000
	s_addc_u32 s19, s45, 0
	s_mov_b32 m0, s65
	ds_read_b128 v[172:175], v155 offset:32768
	ds_read_b128 v[176:179], v155 offset:33792
	ds_read_b128 v[180:183], v155 offset:34816
	ds_read_b128 v[184:187], v155 offset:35840
	ds_read_b128 v[188:191], v155 offset:36864
	ds_read_b128 v[192:195], v155 offset:37888
	ds_read_b128 v[196:199], v155 offset:38912
	ds_read_b128 v[200:203], v155 offset:39936
	global_load_lds_dwordx4 v128, s[18:19]
	s_mov_b32 m0, s66
	s_nop 0
	global_load_lds_dwordx4 v130, s[18:19]
	s_waitcnt lgkmcnt(8)
	s_barrier
	s_waitcnt lgkmcnt(0)
	s_setprio 1
	v_mfma_f32_16x16x32_bf16 v[124:127], v[156:159], v[172:175], v[124:127]
	v_mfma_f32_16x16x32_bf16 v[120:123], v[164:167], v[172:175], v[120:123]
	v_mfma_f32_16x16x32_bf16 v[116:119], v[156:159], v[180:183], v[116:119]
	v_mfma_f32_16x16x32_bf16 v[108:111], v[164:167], v[180:183], v[108:111]
	v_mfma_f32_16x16x32_bf16 v[100:103], v[156:159], v[188:191], v[100:103]
	v_mfma_f32_16x16x32_bf16 v[92:95], v[164:167], v[188:191], v[92:95]
	v_mfma_f32_16x16x32_bf16 v[84:87], v[156:159], v[196:199], v[84:87]
	v_mfma_f32_16x16x32_bf16 v[76:79], v[164:167], v[196:199], v[76:79]
	v_mfma_f32_16x16x32_bf16 v[124:127], v[160:163], v[176:179], v[124:127]
	v_mfma_f32_16x16x32_bf16 v[120:123], v[168:171], v[176:179], v[120:123]
	v_mfma_f32_16x16x32_bf16 v[116:119], v[160:163], v[184:187], v[116:119]
	v_mfma_f32_16x16x32_bf16 v[108:111], v[168:171], v[184:187], v[108:111]
	v_mfma_f32_16x16x32_bf16 v[100:103], v[160:163], v[192:195], v[100:103]
	v_mfma_f32_16x16x32_bf16 v[92:95], v[168:171], v[192:195], v[92:95]
	v_mfma_f32_16x16x32_bf16 v[84:87], v[160:163], v[200:203], v[84:87]
	v_mfma_f32_16x16x32_bf16 v[76:79], v[168:171], v[200:203], v[76:79]
	s_setprio 0
	s_barrier
	s_add_i32 s18, 0, 0x1c000
	s_add_i32 s2, s2, s59
	v_add_u32_e32 v232, s18, v154
	s_mov_b32 m0, s2
	ds_read_b128 v[204:207], v232
	ds_read_b128 v[208:211], v232 offset:1024
	ds_read_b128 v[228:231], v232 offset:2048
	ds_read_b128 v[232:235], v232 offset:3072
	s_add_u32 s100, s0, 0x80
	s_addc_u32 s101, s1, 0
	global_load_lds_dwordx4 v140, s[100:101]
	s_add_i32 m0, s2, 0x2000
	s_nop 0
	global_load_lds_dwordx4 v132, s[100:101]
	s_barrier
	s_waitcnt lgkmcnt(0)
	s_setprio 1
	v_mfma_f32_16x16x32_bf16 v[112:115], v[204:207], v[172:175], v[112:115]
	v_mfma_f32_16x16x32_bf16 v[104:107], v[228:231], v[172:175], v[104:107]
	v_mfma_f32_16x16x32_bf16 v[96:99], v[204:207], v[180:183], v[96:99]
	v_mfma_f32_16x16x32_bf16 v[88:91], v[228:231], v[180:183], v[88:91]
	v_mfma_f32_16x16x32_bf16 v[80:83], v[204:207], v[188:191], v[80:83]
	v_mfma_f32_16x16x32_bf16 v[72:75], v[228:231], v[188:191], v[72:75]
	v_mfma_f32_16x16x32_bf16 v[68:71], v[204:207], v[196:199], v[68:71]
	v_mfma_f32_16x16x32_bf16 v[64:67], v[228:231], v[196:199], v[64:67]
	v_mfma_f32_16x16x32_bf16 v[112:115], v[208:211], v[176:179], v[112:115]
	v_mfma_f32_16x16x32_bf16 v[104:107], v[232:235], v[176:179], v[104:107]
	v_mfma_f32_16x16x32_bf16 v[96:99], v[208:211], v[184:187], v[96:99]
	v_mfma_f32_16x16x32_bf16 v[88:91], v[232:235], v[184:187], v[88:91]
	v_mfma_f32_16x16x32_bf16 v[80:83], v[208:211], v[192:195], v[80:83]
	v_mfma_f32_16x16x32_bf16 v[72:75], v[232:235], v[192:195], v[72:75]
	v_mfma_f32_16x16x32_bf16 v[68:71], v[208:211], v[200:203], v[68:71]
	v_mfma_f32_16x16x32_bf16 v[64:67], v[232:235], v[200:203], v[64:67]
	s_setprio 0
	s_mov_b32 m0, s69
	s_barrier
	ds_read_b128 v[172:175], v155 offset:49152
	ds_read_b128 v[176:179], v155 offset:50176
	ds_read_b128 v[180:183], v155 offset:51200
	ds_read_b128 v[184:187], v155 offset:52224
	ds_read_b128 v[188:191], v155 offset:53248
	ds_read_b128 v[192:195], v155 offset:54272
	ds_read_b128 v[196:199], v155 offset:55296
	ds_read_b128 v[200:203], v155 offset:56320
	s_add_u32 s100, s44, 0x80
	s_addc_u32 s101, s45, 0
	global_load_lds_dwordx4 v128, s[100:101]
	s_mov_b32 m0, s71
	s_nop 0
	global_load_lds_dwordx4 v130, s[100:101]
	s_barrier
	s_waitcnt lgkmcnt(0)
	s_setprio 1
	v_mfma_f32_16x16x32_bf16 v[60:63], v[156:159], v[172:175], v[60:63]
	v_mfma_f32_16x16x32_bf16 v[56:59], v[164:167], v[172:175], v[56:59]
	v_mfma_f32_16x16x32_bf16 v[52:55], v[156:159], v[180:183], v[52:55]
	v_mfma_f32_16x16x32_bf16 v[44:47], v[164:167], v[180:183], v[44:47]
	v_mfma_f32_16x16x32_bf16 v[36:39], v[156:159], v[188:191], v[36:39]
	v_mfma_f32_16x16x32_bf16 v[28:31], v[164:167], v[188:191], v[28:31]
	v_mfma_f32_16x16x32_bf16 v[20:23], v[156:159], v[196:199], v[20:23]
	v_mfma_f32_16x16x32_bf16 v[12:15], v[164:167], v[196:199], v[12:15]
	v_mfma_f32_16x16x32_bf16 v[60:63], v[160:163], v[176:179], v[60:63]
	v_mfma_f32_16x16x32_bf16 v[56:59], v[168:171], v[176:179], v[56:59]
	v_mfma_f32_16x16x32_bf16 v[52:55], v[160:163], v[184:187], v[52:55]
	v_mfma_f32_16x16x32_bf16 v[44:47], v[168:171], v[184:187], v[44:47]
	v_mfma_f32_16x16x32_bf16 v[36:39], v[160:163], v[192:195], v[36:39]
	v_mfma_f32_16x16x32_bf16 v[28:31], v[168:171], v[192:195], v[28:31]
	v_mfma_f32_16x16x32_bf16 v[20:23], v[160:163], v[200:203], v[20:23]
	v_mfma_f32_16x16x32_bf16 v[12:15], v[168:171], v[200:203], v[12:15]
	s_setprio 0
	s_barrier
	s_add_u32 s0, s0, 0x40080
	s_addc_u32 s1, s1, 0
	s_add_i32 s2, s18, s59
	s_mov_b32 m0, s2
	s_nop 0
	global_load_lds_dwordx4 v140, s[0:1]
	s_add_i32 m0, s2, 0x2000
	s_nop 0
	global_load_lds_dwordx4 v132, s[0:1]
	s_waitcnt vmcnt(6)
	s_barrier
	s_setprio 1
	v_mfma_f32_16x16x32_bf16 v[48:51], v[204:207], v[172:175], v[48:51]
	v_mfma_f32_16x16x32_bf16 v[40:43], v[228:231], v[172:175], v[40:43]
	v_mfma_f32_16x16x32_bf16 v[32:35], v[204:207], v[180:183], v[32:35]
	v_mfma_f32_16x16x32_bf16 v[24:27], v[228:231], v[180:183], v[24:27]
	v_mfma_f32_16x16x32_bf16 v[16:19], v[204:207], v[188:191], v[16:19]
	v_mfma_f32_16x16x32_bf16 v[8:11], v[228:231], v[188:191], v[8:11]
	v_mfma_f32_16x16x32_bf16 v[4:7], v[204:207], v[196:199], v[4:7]
	v_mfma_f32_16x16x32_bf16 v[0:3], v[228:231], v[196:199], v[0:3]
	v_mfma_f32_16x16x32_bf16 v[48:51], v[208:211], v[176:179], v[48:51]
	v_mfma_f32_16x16x32_bf16 v[40:43], v[232:235], v[176:179], v[40:43]
	v_mfma_f32_16x16x32_bf16 v[32:35], v[208:211], v[184:187], v[32:35]
	v_mfma_f32_16x16x32_bf16 v[24:27], v[232:235], v[184:187], v[24:27]
	v_mfma_f32_16x16x32_bf16 v[16:19], v[208:211], v[192:195], v[16:19]
	v_mfma_f32_16x16x32_bf16 v[8:11], v[232:235], v[192:195], v[8:11]
	v_mfma_f32_16x16x32_bf16 v[4:7], v[208:211], v[200:203], v[4:7]
	v_mfma_f32_16x16x32_bf16 v[0:3], v[232:235], v[200:203], v[0:3]
	s_setprio 0
	s_add_i32 s72, s72, 2
	s_add_u32 s9, s9, 0x100
	s_addc_u32 s11, s11, 0
	s_add_u32 s40, s40, 0x100
	s_addc_u32 s41, s41, 0
	s_cmp_gt_u32 s72, 13
	s_barrier
	s_cbranch_scc0 .LBB0_96
	s_lshl_b32 s0, s16, 8
	v_mbcnt_lo_u32_b32 v139, -1, 0
	v_mbcnt_hi_u32_b32 v139, -1, v139
	s_lshl_b32 s1, s21, 8
	v_ashrrev_i32_e32 v138, 1, v139
	s_add_i32 s0, s0, s67
	v_and_b32_e32 v138, -8, v138
	s_or_b32 s1, s1, s68
	v_and_or_b32 v156, v139, 15, s0
	v_add_u32_e32 v138, s1, v138
	v_ashrrev_i32_e32 v157, 31, v156
	v_ashrrev_i32_e32 v139, 31, v138
	v_lshlrev_b64 v[158:159], 11, v[156:157]
	v_lshl_add_u64 v[158:159], s[26:27], 0, v[158:159]
	v_lshlrev_b64 v[160:161], 1, v[138:139]
	v_lshl_add_u64 v[138:139], v[158:159], 0, v[160:161]
	v_cvt_pk_bf16_f32 v60, v60, v61
	v_cvt_pk_bf16_f32 v61, v62, v63
	v_cvt_pk_bf16_f32 v62, v56, v57
	v_add_co_u32_e32 v56, vcc, s31, v138
	v_cvt_pk_bf16_f32 v112, v112, v113
	v_cvt_pk_bf16_f32 v113, v114, v115
	v_cvt_pk_bf16_f32 v114, v104, v105
	v_or_b32_e32 v104, 16, v156
	s_nop 0
	v_addc_co_u32_e32 v57, vcc, 0, v139, vcc
	v_cvt_pk_bf16_f32 v48, v48, v49
	v_cvt_pk_bf16_f32 v49, v50, v51
	v_cvt_pk_bf16_f32 v51, v42, v43
	v_cvt_pk_bf16_f32 v42, v44, v45
	v_add_co_u32_e32 v44, vcc, s42, v138
	v_ashrrev_i32_e32 v105, 31, v104
	v_cvt_pk_bf16_f32 v96, v96, v97
	v_cvt_pk_bf16_f32 v97, v98, v99
	v_cvt_pk_bf16_f32 v98, v88, v89
	v_or_b32_e32 v88, 32, v156
	v_addc_co_u32_e32 v45, vcc, 0, v139, vcc
	v_lshlrev_b64 v[104:105], 11, v[104:105]
	v_ashrrev_i32_e32 v89, 31, v88
	v_cvt_pk_bf16_f32 v80, v80, v81
	v_cvt_pk_bf16_f32 v81, v82, v83
	v_cvt_pk_bf16_f32 v82, v72, v73
	v_or_b32_e32 v72, 48, v156
	s_mov_b64 s[0:1], 0x40000
	v_cvt_pk_bf16_f32 v32, v32, v33
	v_cvt_pk_bf16_f32 v33, v34, v35
	v_cvt_pk_bf16_f32 v35, v26, v27
	v_cvt_pk_bf16_f32 v26, v28, v29
	v_add_co_u32_e32 v28, vcc, s43, v138
	v_lshl_add_u64 v[104:105], s[26:27], 0, v[104:105]
	v_lshlrev_b64 v[88:89], 11, v[88:89]
	v_ashrrev_i32_e32 v73, 31, v72
	v_cvt_pk_bf16_f32 v68, v68, v69
	v_cvt_pk_bf16_f32 v69, v70, v71
	v_cvt_pk_bf16_f32 v70, v64, v65
	v_lshl_add_u64 v[64:65], v[138:139], 0, s[0:1]
	s_mov_b64 s[0:1], 0x48000
	v_addc_co_u32_e32 v29, vcc, 0, v139, vcc
	v_cvt_pk_bf16_f32 v115, v106, v107
	flat_store_dwordx4 v[138:139], v[112:115] offset:256
	v_lshl_add_u64 v[88:89], s[26:27], 0, v[88:89]
	v_lshlrev_b64 v[72:73], 11, v[72:73]
	v_lshl_add_u64 v[112:113], v[104:105], 0, v[160:161]
	v_cvt_pk_bf16_f32 v50, v40, v41
	flat_store_dwordx4 v[64:65], v[48:51] offset:256
	v_cvt_pk_bf16_f32 v16, v16, v17
	v_cvt_pk_bf16_f32 v17, v18, v19
	v_cvt_pk_bf16_f32 v19, v10, v11
	v_cvt_pk_bf16_f32 v10, v12, v13
	v_add_co_u32_e32 v12, vcc, s47, v138
	s_nop 0
	v_lshl_add_u64 v[48:49], v[138:139], 0, s[0:1]
	s_mov_b64 s[0:1], 0x50000
	v_cvt_pk_bf16_f32 v99, v90, v91
	flat_store_dwordx4 v[112:113], v[96:99] offset:256
	v_lshl_add_u64 v[72:73], s[26:27], 0, v[72:73]
	v_cvt_pk_bf16_f32 v34, v24, v25
	flat_store_dwordx4 v[48:49], v[32:35] offset:256
	v_lshl_add_u64 v[96:97], v[88:89], 0, v[160:161]
	v_addc_co_u32_e32 v13, vcc, 0, v139, vcc
	v_lshl_add_u64 v[32:33], v[138:139], 0, s[0:1]
	s_mov_b64 s[0:1], 0x58000
	v_cvt_pk_bf16_f32 v83, v74, v75
	flat_store_dwordx4 v[96:97], v[80:83] offset:256
	v_cvt_pk_bf16_f32 v18, v8, v9
	flat_store_dwordx4 v[32:33], v[16:19] offset:256
	s_and_b64 vcc, exec, s[6:7]
	v_lshl_add_u64 v[80:81], v[72:73], 0, v[160:161]
	v_lshl_add_u64 v[16:17], v[138:139], 0, s[0:1]
	s_mov_b32 s21, s10
	s_mov_b32 s16, s8
	s_mov_b64 s[40:41], s[14:15]
	s_mov_b64 s[0:1], s[12:13]
	v_cvt_pk_bf16_f32 v124, v124, v125
	v_cvt_pk_bf16_f32 v125, v126, v127
	v_cvt_pk_bf16_f32 v126, v120, v121
	v_cvt_pk_bf16_f32 v127, v122, v123
	flat_store_dwordx4 v[138:139], v[124:127]
	v_cvt_pk_bf16_f32 v104, v116, v117
	v_cvt_pk_bf16_f32 v105, v118, v119
	v_cvt_pk_bf16_f32 v106, v108, v109
	v_cvt_pk_bf16_f32 v107, v110, v111
	flat_store_dwordx4 v[112:113], v[104:107]
	v_cvt_pk_bf16_f32 v88, v100, v101
	v_cvt_pk_bf16_f32 v89, v102, v103
	v_cvt_pk_bf16_f32 v90, v92, v93
	v_cvt_pk_bf16_f32 v91, v94, v95
	flat_store_dwordx4 v[96:97], v[88:91]
	v_cvt_pk_bf16_f32 v72, v84, v85
	v_cvt_pk_bf16_f32 v73, v86, v87
	v_cvt_pk_bf16_f32 v74, v76, v77
	v_cvt_pk_bf16_f32 v75, v78, v79
	flat_store_dwordx4 v[80:81], v[72:75]
	v_cvt_pk_bf16_f32 v71, v66, v67
	flat_store_dwordx4 v[80:81], v[68:71] offset:256
	v_cvt_pk_bf16_f32 v63, v58, v59
	flat_store_dwordx4 v[56:57], v[60:63]
	v_cvt_pk_bf16_f32 v40, v52, v53
	v_cvt_pk_bf16_f32 v41, v54, v55
	v_cvt_pk_bf16_f32 v43, v46, v47
	flat_store_dwordx4 v[44:45], v[40:43]
	v_cvt_pk_bf16_f32 v24, v36, v37
	v_cvt_pk_bf16_f32 v25, v38, v39
	v_cvt_pk_bf16_f32 v27, v30, v31
	flat_store_dwordx4 v[28:29], v[24:27]
	v_cvt_pk_bf16_f32 v8, v20, v21
	v_cvt_pk_bf16_f32 v9, v22, v23
	v_cvt_pk_bf16_f32 v11, v14, v15
	flat_store_dwordx4 v[12:13], v[8:11]
	v_cvt_pk_bf16_f32 v4, v4, v5
	v_cvt_pk_bf16_f32 v5, v6, v7
	v_cvt_pk_bf16_f32 v6, v0, v1
	v_cvt_pk_bf16_f32 v7, v2, v3
	flat_store_dwordx4 v[16:17], v[4:7] offset:256
	s_cbranch_vccz .LBB0_89
	s_waitcnt vmcnt(0)
	s_cmpk_gt_u32 s51, 0xff
	s_cbranch_scc1 .LBB0_100
	s_barrier

.LBB0_126:
	s_add_u32 s0, s8, 0xfff80080
	s_addc_u32 s1, s9, -1
	s_add_i32 s2, 0, 0x10000
	v_add_u32_e32 v138, s2, v238
	ds_read_b128 v[154:157], v138
	ds_read_b128 v[158:161], v138 offset:1024
	ds_read_b128 v[162:165], v138 offset:2048
	ds_read_b128 v[166:169], v138 offset:3072
	s_cmp_eq_u32 s20, 28
	s_cselect_b32 s11, s45, s1
	s_cselect_b32 s10, s44, s0
	s_cselect_b32 s1, s67, s15
	s_cselect_b32 s0, s66, s13
	s_add_i32 m0, s17, 0xc000
	ds_read_b128 v[170:173], v239
	ds_read_b128 v[174:177], v239 offset:1024
	ds_read_b128 v[178:181], v239 offset:2048
	ds_read_b128 v[182:185], v239 offset:3072
	ds_read_b128 v[186:189], v239 offset:4096
	ds_read_b128 v[190:193], v239 offset:5120
	ds_read_b128 v[194:197], v239 offset:6144
	ds_read_b128 v[198:201], v239 offset:7168
	global_load_lds_dwordx4 v136, s[8:9]
	s_add_i32 m0, s17, 0xe000
	s_nop 0
	global_load_lds_dwordx4 v134, s[8:9]
	s_waitcnt lgkmcnt(8)
	s_barrier
	s_waitcnt lgkmcnt(0)
	s_setprio 1
	v_mfma_f32_16x16x32_bf16 v[124:127], v[154:157], v[170:173], v[124:127]
	v_mfma_f32_16x16x32_bf16 v[120:123], v[162:165], v[170:173], v[120:123]
	v_mfma_f32_16x16x32_bf16 v[116:119], v[154:157], v[178:181], v[116:119]
	v_mfma_f32_16x16x32_bf16 v[112:115], v[162:165], v[178:181], v[112:115]
	v_mfma_f32_16x16x32_bf16 v[104:107], v[154:157], v[186:189], v[104:107]
	v_mfma_f32_16x16x32_bf16 v[96:99], v[162:165], v[186:189], v[96:99]
	v_mfma_f32_16x16x32_bf16 v[88:91], v[154:157], v[194:197], v[88:91]
	v_mfma_f32_16x16x32_bf16 v[80:83], v[162:165], v[194:197], v[80:83]
	v_mfma_f32_16x16x32_bf16 v[124:127], v[158:161], v[174:177], v[124:127]
	v_mfma_f32_16x16x32_bf16 v[120:123], v[166:169], v[174:177], v[120:123]
	v_mfma_f32_16x16x32_bf16 v[116:119], v[158:161], v[182:185], v[116:119]
	v_mfma_f32_16x16x32_bf16 v[112:115], v[166:169], v[182:185], v[112:115]
	v_mfma_f32_16x16x32_bf16 v[104:107], v[158:161], v[190:193], v[104:107]
	v_mfma_f32_16x16x32_bf16 v[96:99], v[166:169], v[190:193], v[96:99]
	v_mfma_f32_16x16x32_bf16 v[88:91], v[158:161], v[198:201], v[88:91]
	v_mfma_f32_16x16x32_bf16 v[80:83], v[166:169], v[198:201], v[80:83]
	s_setprio 0
	s_barrier
	s_add_i32 s21, 0, 0x14000
	v_add_u32_e32 v138, s21, v238
	s_add_i32 s2, s2, s58
	ds_read_b128 v[202:205], v138
	ds_read_b128 v[206:209], v138 offset:1024
	ds_read_b128 v[240:243], v138 offset:2048
	ds_read_b128 v[244:247], v138 offset:3072
	s_mov_b32 m0, s2
	s_nop 0
	global_load_lds_dwordx4 v140, s[0:1]
	s_add_i32 m0, s2, 0x2000
	s_nop 0
	global_load_lds_dwordx4 v132, s[0:1]
	s_barrier
	s_waitcnt lgkmcnt(0)
	s_setprio 1
	v_mfma_f32_16x16x32_bf16 v[108:111], v[202:205], v[170:173], v[108:111]
	v_mfma_f32_16x16x32_bf16 v[100:103], v[240:243], v[170:173], v[100:103]
	v_mfma_f32_16x16x32_bf16 v[92:95], v[202:205], v[178:181], v[92:95]
	v_mfma_f32_16x16x32_bf16 v[84:87], v[240:243], v[178:181], v[84:87]
	v_mfma_f32_16x16x32_bf16 v[76:79], v[202:205], v[186:189], v[76:79]
	v_mfma_f32_16x16x32_bf16 v[72:75], v[240:243], v[186:189], v[72:75]
	v_mfma_f32_16x16x32_bf16 v[68:71], v[202:205], v[194:197], v[68:71]
	v_mfma_f32_16x16x32_bf16 v[64:67], v[240:243], v[194:197], v[64:67]
	v_mfma_f32_16x16x32_bf16 v[108:111], v[206:209], v[174:177], v[108:111]
	v_mfma_f32_16x16x32_bf16 v[100:103], v[244:247], v[174:177], v[100:103]
	v_mfma_f32_16x16x32_bf16 v[92:95], v[206:209], v[182:185], v[92:95]
	v_mfma_f32_16x16x32_bf16 v[84:87], v[244:247], v[182:185], v[84:87]
	v_mfma_f32_16x16x32_bf16 v[76:79], v[206:209], v[190:193], v[76:79]
	v_mfma_f32_16x16x32_bf16 v[72:75], v[244:247], v[190:193], v[72:75]
	v_mfma_f32_16x16x32_bf16 v[68:71], v[206:209], v[198:201], v[68:71]
	v_mfma_f32_16x16x32_bf16 v[64:67], v[244:247], v[198:201], v[64:67]
	s_setprio 0
	s_mov_b32 m0, s17
	v_lshl_add_u64 v[248:249], s[10:11], 0, v[128:129]
	s_barrier
	ds_read_b128 v[170:173], v239 offset:16384
	ds_read_b128 v[174:177], v239 offset:17408
	ds_read_b128 v[178:181], v239 offset:18432
	ds_read_b128 v[182:185], v239 offset:19456
	ds_read_b128 v[186:189], v239 offset:20480
	ds_read_b128 v[190:193], v239 offset:21504
	ds_read_b128 v[194:197], v239 offset:22528
	ds_read_b128 v[198:201], v239 offset:23552
	global_load_lds_dwordx4 v128, s[10:11]
	v_lshl_add_u64 v[250:251], s[10:11], 0, v[130:131]
	s_mov_b32 m0, s59
	s_nop 0
	global_load_lds_dwordx4 v130, s[10:11]
	s_barrier
	s_waitcnt lgkmcnt(0)
	s_setprio 1
	v_mfma_f32_16x16x32_bf16 v[60:63], v[154:157], v[170:173], v[60:63]
	v_mfma_f32_16x16x32_bf16 v[56:59], v[162:165], v[170:173], v[56:59]
	v_mfma_f32_16x16x32_bf16 v[52:55], v[154:157], v[178:181], v[52:55]
	v_mfma_f32_16x16x32_bf16 v[48:51], v[162:165], v[178:181], v[48:51]
	v_mfma_f32_16x16x32_bf16 v[36:39], v[154:157], v[186:189], v[36:39]
	v_mfma_f32_16x16x32_bf16 v[32:35], v[162:165], v[186:189], v[32:35]
	v_mfma_f32_16x16x32_bf16 v[20:23], v[154:157], v[194:197], v[20:23]
	v_mfma_f32_16x16x32_bf16 v[16:19], v[162:165], v[194:197], v[16:19]
	v_mfma_f32_16x16x32_bf16 v[60:63], v[158:161], v[174:177], v[60:63]
	v_mfma_f32_16x16x32_bf16 v[56:59], v[166:169], v[174:177], v[56:59]
	v_mfma_f32_16x16x32_bf16 v[52:55], v[158:161], v[182:185], v[52:55]
	v_mfma_f32_16x16x32_bf16 v[48:51], v[166:169], v[182:185], v[48:51]
	v_mfma_f32_16x16x32_bf16 v[36:39], v[158:161], v[190:193], v[36:39]
	v_mfma_f32_16x16x32_bf16 v[32:35], v[166:169], v[190:193], v[32:35]
	v_mfma_f32_16x16x32_bf16 v[20:23], v[158:161], v[198:201], v[20:23]
	v_mfma_f32_16x16x32_bf16 v[16:19], v[166:169], v[198:201], v[16:19]
	s_setprio 0
	s_barrier
	s_add_u32 s18, s0, 0x100000
	s_addc_u32 s19, s1, 0
	s_add_i32 s2, s21, s58
	s_mov_b32 m0, s2
	s_nop 0
	global_load_lds_dwordx4 v140, s[18:19]
	s_add_i32 m0, s2, 0x2000
	s_nop 0
	global_load_lds_dwordx4 v132, s[18:19]
	s_waitcnt vmcnt(6)
	s_barrier
	s_setprio 1
	v_mfma_f32_16x16x32_bf16 v[44:47], v[202:205], v[170:173], v[44:47]
	v_mfma_f32_16x16x32_bf16 v[40:43], v[240:243], v[170:173], v[40:43]
	v_mfma_f32_16x16x32_bf16 v[28:31], v[202:205], v[178:181], v[28:31]
	v_mfma_f32_16x16x32_bf16 v[24:27], v[240:243], v[178:181], v[24:27]
	v_mfma_f32_16x16x32_bf16 v[12:15], v[202:205], v[186:189], v[12:15]
	v_mfma_f32_16x16x32_bf16 v[8:11], v[240:243], v[186:189], v[8:11]
	v_mfma_f32_16x16x32_bf16 v[4:7], v[202:205], v[194:197], v[4:7]
	v_mfma_f32_16x16x32_bf16 v[0:3], v[240:243], v[194:197], v[0:3]
	v_mfma_f32_16x16x32_bf16 v[44:47], v[206:209], v[174:177], v[44:47]
	v_mfma_f32_16x16x32_bf16 v[40:43], v[244:247], v[174:177], v[40:43]
	v_mfma_f32_16x16x32_bf16 v[28:31], v[206:209], v[182:185], v[28:31]
	v_mfma_f32_16x16x32_bf16 v[24:27], v[244:247], v[182:185], v[24:27]
	v_mfma_f32_16x16x32_bf16 v[12:15], v[206:209], v[190:193], v[12:15]
	v_mfma_f32_16x16x32_bf16 v[8:11], v[244:247], v[190:193], v[8:11]
	v_mfma_f32_16x16x32_bf16 v[4:7], v[206:209], v[198:201], v[4:7]
	v_mfma_f32_16x16x32_bf16 v[0:3], v[244:247], v[198:201], v[0:3]
	s_setprio 0
	s_add_i32 s2, 0, 0x18000
	v_add_u32_e32 v166, s2, v238
	s_barrier
	ds_read_b128 v[154:157], v166
	ds_read_b128 v[158:161], v166 offset:1024
	ds_read_b128 v[162:165], v166 offset:2048
	ds_read_b128 v[166:169], v166 offset:3072
	s_add_u32 s10, s10, 0x80000
	s_addc_u32 s11, s11, 0
	s_mov_b32 m0, s65
	ds_read_b128 v[170:173], v239 offset:32768
	ds_read_b128 v[174:177], v239 offset:33792
	ds_read_b128 v[178:181], v239 offset:34816
	ds_read_b128 v[182:185], v239 offset:35840
	ds_read_b128 v[186:189], v239 offset:36864
	ds_read_b128 v[190:193], v239 offset:37888
	ds_read_b128 v[194:197], v239 offset:38912
	ds_read_b128 v[198:201], v239 offset:39936
	global_load_lds_dwordx4 v128, s[10:11]
	s_mov_b32 m0, s72
	s_nop 0
	global_load_lds_dwordx4 v130, s[10:11]
	s_waitcnt lgkmcnt(8)
	s_barrier
	s_waitcnt lgkmcnt(0)
	s_setprio 1
	v_mfma_f32_16x16x32_bf16 v[124:127], v[154:157], v[170:173], v[124:127]
	v_mfma_f32_16x16x32_bf16 v[120:123], v[162:165], v[170:173], v[120:123]
	v_mfma_f32_16x16x32_bf16 v[116:119], v[154:157], v[178:181], v[116:119]
	v_mfma_f32_16x16x32_bf16 v[112:115], v[162:165], v[178:181], v[112:115]
	v_mfma_f32_16x16x32_bf16 v[104:107], v[154:157], v[186:189], v[104:107]
	v_mfma_f32_16x16x32_bf16 v[96:99], v[162:165], v[186:189], v[96:99]
	v_mfma_f32_16x16x32_bf16 v[88:91], v[154:157], v[194:197], v[88:91]
	v_mfma_f32_16x16x32_bf16 v[80:83], v[162:165], v[194:197], v[80:83]
	v_mfma_f32_16x16x32_bf16 v[124:127], v[158:161], v[174:177], v[124:127]
	v_mfma_f32_16x16x32_bf16 v[120:123], v[166:169], v[174:177], v[120:123]
	v_mfma_f32_16x16x32_bf16 v[116:119], v[158:161], v[182:185], v[116:119]
	v_mfma_f32_16x16x32_bf16 v[112:115], v[166:169], v[182:185], v[112:115]
	v_mfma_f32_16x16x32_bf16 v[104:107], v[158:161], v[190:193], v[104:107]
	v_mfma_f32_16x16x32_bf16 v[96:99], v[166:169], v[190:193], v[96:99]
	v_mfma_f32_16x16x32_bf16 v[88:91], v[158:161], v[198:201], v[88:91]
	v_mfma_f32_16x16x32_bf16 v[80:83], v[166:169], v[198:201], v[80:83]
	s_setprio 0
	s_barrier
	s_add_i32 s10, 0, 0x1c000
	s_add_i32 s2, s2, s58
	v_add_u32_e32 v244, s10, v238
	s_mov_b32 m0, s2
	ds_read_b128 v[202:205], v244
	ds_read_b128 v[206:209], v244 offset:1024
	ds_read_b128 v[240:243], v244 offset:2048
	ds_read_b128 v[244:247], v244 offset:3072
	s_add_u32 s100, s0, 0x80
	s_addc_u32 s101, s1, 0
	global_load_lds_dwordx4 v140, s[100:101]
	s_add_i32 m0, s2, 0x2000
	s_nop 0
	global_load_lds_dwordx4 v132, s[100:101]
	s_barrier
	s_waitcnt lgkmcnt(0)
	s_setprio 1
	v_mfma_f32_16x16x32_bf16 v[108:111], v[202:205], v[170:173], v[108:111]
	v_mfma_f32_16x16x32_bf16 v[100:103], v[240:243], v[170:173], v[100:103]
	v_mfma_f32_16x16x32_bf16 v[92:95], v[202:205], v[178:181], v[92:95]
	v_mfma_f32_16x16x32_bf16 v[84:87], v[240:243], v[178:181], v[84:87]
	v_mfma_f32_16x16x32_bf16 v[76:79], v[202:205], v[186:189], v[76:79]
	v_mfma_f32_16x16x32_bf16 v[72:75], v[240:243], v[186:189], v[72:75]
	v_mfma_f32_16x16x32_bf16 v[68:71], v[202:205], v[194:197], v[68:71]
	v_mfma_f32_16x16x32_bf16 v[64:67], v[240:243], v[194:197], v[64:67]
	v_mfma_f32_16x16x32_bf16 v[108:111], v[206:209], v[174:177], v[108:111]
	v_mfma_f32_16x16x32_bf16 v[100:103], v[244:247], v[174:177], v[100:103]
	v_mfma_f32_16x16x32_bf16 v[92:95], v[206:209], v[182:185], v[92:95]
	v_mfma_f32_16x16x32_bf16 v[84:87], v[244:247], v[182:185], v[84:87]
	v_mfma_f32_16x16x32_bf16 v[76:79], v[206:209], v[190:193], v[76:79]
	v_mfma_f32_16x16x32_bf16 v[72:75], v[244:247], v[190:193], v[72:75]
	v_mfma_f32_16x16x32_bf16 v[68:71], v[206:209], v[198:201], v[68:71]
	v_mfma_f32_16x16x32_bf16 v[64:67], v[244:247], v[198:201], v[64:67]
	s_setprio 0
	s_mov_b32 m0, s75
	v_lshl_add_u64 v[138:139], v[248:249], 0, s[82:83]
	s_barrier
	ds_read_b128 v[170:173], v239 offset:49152
	ds_read_b128 v[174:177], v239 offset:50176
	ds_read_b128 v[178:181], v239 offset:51200
	ds_read_b128 v[182:185], v239 offset:52224
	ds_read_b128 v[186:189], v239 offset:53248
	ds_read_b128 v[190:193], v239 offset:54272
	ds_read_b128 v[194:197], v239 offset:55296
	ds_read_b128 v[198:201], v239 offset:56320
	global_load_lds_dwordx4 v[138:139], off
	v_lshl_add_u64 v[138:139], v[250:251], 0, s[82:83]
	s_mov_b32 m0, s77
	s_nop 0
	global_load_lds_dwordx4 v[138:139], off
	s_barrier
	s_waitcnt lgkmcnt(0)
	s_setprio 1
	v_mfma_f32_16x16x32_bf16 v[60:63], v[154:157], v[170:173], v[60:63]
	v_mfma_f32_16x16x32_bf16 v[56:59], v[162:165], v[170:173], v[56:59]
	v_mfma_f32_16x16x32_bf16 v[52:55], v[154:157], v[178:181], v[52:55]
	v_mfma_f32_16x16x32_bf16 v[48:51], v[162:165], v[178:181], v[48:51]
	v_mfma_f32_16x16x32_bf16 v[36:39], v[154:157], v[186:189], v[36:39]
	v_mfma_f32_16x16x32_bf16 v[32:35], v[162:165], v[186:189], v[32:35]
	v_mfma_f32_16x16x32_bf16 v[20:23], v[154:157], v[194:197], v[20:23]
	v_mfma_f32_16x16x32_bf16 v[16:19], v[162:165], v[194:197], v[16:19]
	v_mfma_f32_16x16x32_bf16 v[60:63], v[158:161], v[174:177], v[60:63]
	v_mfma_f32_16x16x32_bf16 v[56:59], v[166:169], v[174:177], v[56:59]
	v_mfma_f32_16x16x32_bf16 v[52:55], v[158:161], v[182:185], v[52:55]
	v_mfma_f32_16x16x32_bf16 v[48:51], v[166:169], v[182:185], v[48:51]
	v_mfma_f32_16x16x32_bf16 v[36:39], v[158:161], v[190:193], v[36:39]
	v_mfma_f32_16x16x32_bf16 v[32:35], v[166:169], v[190:193], v[32:35]
	v_mfma_f32_16x16x32_bf16 v[20:23], v[158:161], v[198:201], v[20:23]
	v_mfma_f32_16x16x32_bf16 v[16:19], v[166:169], v[198:201], v[16:19]
	s_setprio 0
	s_barrier
	s_add_u32 s0, s0, 0x100080
	s_addc_u32 s1, s1, 0
	s_add_i32 s2, s10, s58
	s_mov_b32 m0, s2
	s_nop 0
	global_load_lds_dwordx4 v140, s[0:1]
	s_add_i32 m0, s2, 0x2000
	s_nop 0
	global_load_lds_dwordx4 v132, s[0:1]
	s_waitcnt vmcnt(6)
	s_barrier
	s_setprio 1
	v_mfma_f32_16x16x32_bf16 v[44:47], v[202:205], v[170:173], v[44:47]
	v_mfma_f32_16x16x32_bf16 v[40:43], v[240:243], v[170:173], v[40:43]
	v_mfma_f32_16x16x32_bf16 v[28:31], v[202:205], v[178:181], v[28:31]
	v_mfma_f32_16x16x32_bf16 v[24:27], v[240:243], v[178:181], v[24:27]
	v_mfma_f32_16x16x32_bf16 v[12:15], v[202:205], v[186:189], v[12:15]
	v_mfma_f32_16x16x32_bf16 v[8:11], v[240:243], v[186:189], v[8:11]
	v_mfma_f32_16x16x32_bf16 v[4:7], v[202:205], v[194:197], v[4:7]
	v_mfma_f32_16x16x32_bf16 v[0:3], v[240:243], v[194:197], v[0:3]
	v_mfma_f32_16x16x32_bf16 v[44:47], v[206:209], v[174:177], v[44:47]
	v_mfma_f32_16x16x32_bf16 v[40:43], v[244:247], v[174:177], v[40:43]
	v_mfma_f32_16x16x32_bf16 v[28:31], v[206:209], v[182:185], v[28:31]
	v_mfma_f32_16x16x32_bf16 v[24:27], v[244:247], v[182:185], v[24:27]
	v_mfma_f32_16x16x32_bf16 v[12:15], v[206:209], v[190:193], v[12:15]
	v_mfma_f32_16x16x32_bf16 v[8:11], v[244:247], v[190:193], v[8:11]
	v_mfma_f32_16x16x32_bf16 v[4:7], v[206:209], v[198:201], v[4:7]
	v_mfma_f32_16x16x32_bf16 v[0:3], v[244:247], v[198:201], v[0:3]
	s_setprio 0
	s_add_i32 s20, s20, 2
	s_add_u32 s13, s13, 0x100
	s_addc_u32 s15, s15, 0
	s_add_u32 s8, s8, 0x100
	s_addc_u32 s9, s9, 0
	s_cmp_gt_u32 s20, 29
	s_barrier
	s_cbranch_scc0 .LBB0_126
	v_mbcnt_lo_u32_b32 v154, -1, 0
	v_mbcnt_hi_u32_b32 v154, -1, v154
	s_lshl_b32 s0, s16, 8
	v_ashrrev_i32_e32 v138, 2, v154
	s_or_b32 s0, s0, s74
	v_and_b32_e32 v138, -4, v138
	s_lshl_b32 s13, s64, 8
	v_add_u32_e32 v138, s0, v138
	v_and_b32_e32 v240, 15, v154
	s_cmp_gt_i32 s71, 7
	s_mov_b64 s[0:1], -1
	v_ashrrev_i32_e32 v139, 31, v138
	s_cbranch_scc0 .LBB0_145
	s_add_i32 s0, s71, -8
	s_lshl_b32 s52, s0, 10
	s_lshl_b32 s15, s0, 12
	s_lshl_b32 s16, s0, 11
	s_addk_i32 s15, 0x1000
	s_lshl_b64 s[0:1], s[52:53], 2
	v_or_b32_e32 v155, s73, v240
	s_add_u32 s0, s49, s0
	v_add_u32_e32 v206, s13, v155
	s_addc_u32 s1, s76, s1
	v_lshlrev_b64 v[198:199], 2, v[138:139]
	v_add_u32_e32 v156, s16, v206
	v_lshl_add_u64 v[160:161], s[0:1], 0, v[198:199]
	v_ashrrev_i32_e32 v157, 31, v156
	flat_load_dwordx4 v[162:165], v[160:161]
	v_lshlrev_b64 v[158:159], 12, v[156:157]
	v_lshl_add_u64 v[158:159], s[26:27], 0, v[158:159]
	v_lshl_add_u64 v[158:159], v[158:159], 0, v[198:199]
	flat_load_dwordx4 v[166:169], v[158:159] nt
	s_mov_b32 s0, 0x3c800000
	v_and_b32_e32 v155, 1, v154
	v_add_u32_e32 v156, s16, v156
	v_cmp_eq_u32_e64 s[8:9], 0, v155
	v_ashrrev_i32_e32 v157, 31, v156
	v_lshlrev_b64 v[156:157], 11, v[156:157]
	v_sub_u32_e32 v154, s15, v206
	v_lshl_add_u64 v[156:157], s[24:25], 0, v[156:157]
	v_cmp_ne_u32_e32 vcc, 0, v206
	v_lshl_add_u64 v[156:157], v[138:139], 1, v[156:157]
	s_waitcnt vmcnt(0) lgkmcnt(0)
	v_or_b32_e32 v236, 16, v206
	v_add_u32_e32 v236, s16, v236
	v_ashrrev_i32_e32 v237, 31, v236
	v_lshlrev_b64 v[236:237], 12, v[236:237]
	v_lshl_add_u64 v[236:237], s[26:27], 0, v[236:237]
	v_lshl_add_u64 v[236:237], v[236:237], 0, v[198:199]
	global_load_dwordx4 v[232:235], v[236:237], off nt
	v_or_b32_e32 v236, 32, v206
	v_add_u32_e32 v236, s16, v236
	v_ashrrev_i32_e32 v237, 31, v236
	v_lshlrev_b64 v[236:237], 12, v[236:237]
	v_lshl_add_u64 v[236:237], s[26:27], 0, v[236:237]
	v_lshl_add_u64 v[236:237], v[236:237], 0, v[198:199]
	global_load_dwordx4 v[246:249], v[236:237], off nt
	v_pk_mul_f32 v[164:165], v[164:165], s[0:1] op_sel_hi:[1,0]
	v_pk_mul_f32 v[162:163], v[162:163], s[0:1] op_sel_hi:[1,0]
	v_xor_b32_e32 v170, 0x80000000, v164
	v_xor_b32_e32 v171, 0x80000000, v165
	v_xor_b32_e32 v172, 0x80000000, v162
	v_xor_b32_e32 v173, 0x80000000, v163
	v_cndmask_b32_e64 v201, v171, v165, s[8:9]
	v_cndmask_b32_e64 v200, v170, v164, s[8:9]
	v_cndmask_b32_e64 v205, v173, v163, s[8:9]
	v_cndmask_b32_e64 v204, v172, v162, s[8:9]
	v_pk_add_f32 v[162:163], v[168:169], v[200:201]
	v_pk_add_f32 v[164:165], v[166:167], v[204:205]
	v_sub_f32_e32 v155, v162, v126
	v_sub_f32_e32 v167, v163, v127
	v_sub_f32_e32 v166, v164, v124
	v_cvt_pk_bf16_f32 v167, v155, v167
	v_ashrrev_i32_e32 v155, 31, v154
	v_sub_f32_e32 v168, v165, v125
	v_cvt_pk_bf16_f32 v166, v166, v168
	global_store_dwordx2 v[156:157], v[166:167], off
	s_and_saveexec_b64 s[0:1], vcc
	s_cbranch_execz .LBB0_130
	v_pk_add_f32 v[162:163], v[126:127], v[162:163]
	v_pk_add_f32 v[164:165], v[124:125], v[164:165]
	s_nop 0
	v_cvt_pk_bf16_f32 v164, v164, v165
	v_cvt_pk_bf16_f32 v165, v162, v163
	v_lshlrev_b64 v[162:163], 11, v[154:155]
	v_lshl_add_u64 v[162:163], s[24:25], 0, v[162:163]
	v_lshl_add_u64 v[162:163], v[138:139], 1, v[162:163]
	global_store_dwordx2 v[162:163], v[164:165], off

.LBB0_169:
	s_add_u32 s0, s66, 0xfff80080
	s_addc_u32 s1, s67, -1
	s_add_i32 s2, 0, 0x10000
	v_add_u32_e32 v166, s2, v138
	ds_read_b128 v[154:157], v166
	ds_read_b128 v[158:161], v166 offset:1024
	ds_read_b128 v[162:165], v166 offset:2048
	ds_read_b128 v[166:169], v166 offset:3072
	s_cmp_eq_u32 s45, 28
	s_cselect_b32 s69, s9, s1
	s_cselect_b32 s68, s8, s0
	s_cselect_b32 s1, s65, s41
	s_cselect_b32 s0, s64, s17
	s_add_i32 m0, s11, 0xc000
	ds_read_b128 v[170:173], v139
	ds_read_b128 v[174:177], v139 offset:1024
	ds_read_b128 v[178:181], v139 offset:2048
	ds_read_b128 v[182:185], v139 offset:3072
	ds_read_b128 v[186:189], v139 offset:4096
	ds_read_b128 v[190:193], v139 offset:5120
	ds_read_b128 v[194:197], v139 offset:6144
	ds_read_b128 v[198:201], v139 offset:7168
	global_load_lds_dwordx4 v136, s[66:67]
	s_add_i32 m0, s11, 0xe000
	s_nop 0
	global_load_lds_dwordx4 v134, s[66:67]
	s_waitcnt lgkmcnt(8)
	s_barrier
	s_waitcnt lgkmcnt(0)
	s_setprio 1
	v_mfma_f32_16x16x32_bf16 v[124:127], v[154:157], v[170:173], v[124:127]
	v_mfma_f32_16x16x32_bf16 v[120:123], v[162:165], v[170:173], v[120:123]
	v_mfma_f32_16x16x32_bf16 v[116:119], v[154:157], v[178:181], v[116:119]
	v_mfma_f32_16x16x32_bf16 v[112:115], v[162:165], v[178:181], v[112:115]
	v_mfma_f32_16x16x32_bf16 v[104:107], v[154:157], v[186:189], v[104:107]
	v_mfma_f32_16x16x32_bf16 v[96:99], v[162:165], v[186:189], v[96:99]
	v_mfma_f32_16x16x32_bf16 v[88:91], v[154:157], v[194:197], v[88:91]
	v_mfma_f32_16x16x32_bf16 v[80:83], v[162:165], v[194:197], v[80:83]
	v_mfma_f32_16x16x32_bf16 v[124:127], v[158:161], v[174:177], v[124:127]
	v_mfma_f32_16x16x32_bf16 v[120:123], v[166:169], v[174:177], v[120:123]
	v_mfma_f32_16x16x32_bf16 v[116:119], v[158:161], v[182:185], v[116:119]
	v_mfma_f32_16x16x32_bf16 v[112:115], v[166:169], v[182:185], v[112:115]
	v_mfma_f32_16x16x32_bf16 v[104:107], v[158:161], v[190:193], v[104:107]
	v_mfma_f32_16x16x32_bf16 v[96:99], v[166:169], v[190:193], v[96:99]
	v_mfma_f32_16x16x32_bf16 v[88:91], v[158:161], v[198:201], v[88:91]
	v_mfma_f32_16x16x32_bf16 v[80:83], v[166:169], v[198:201], v[80:83]
	s_setprio 0
	s_barrier
	s_add_i32 s30, 0, 0x14000
	v_add_u32_e32 v210, s30, v138
	s_add_i32 s2, s2, s20
	ds_read_b128 v[202:205], v210
	ds_read_b128 v[206:209], v210 offset:1024
	ds_read_b128 v[228:231], v210 offset:2048
	ds_read_b128 v[232:235], v210 offset:3072
	s_mov_b32 m0, s2
	s_nop 0
	global_load_lds_dwordx4 v140, s[0:1]
	s_add_i32 m0, s2, 0x2000
	s_nop 0
	global_load_lds_dwordx4 v132, s[0:1]
	s_barrier
	s_waitcnt lgkmcnt(0)
	s_setprio 1
	v_mfma_f32_16x16x32_bf16 v[108:111], v[202:205], v[170:173], v[108:111]
	v_mfma_f32_16x16x32_bf16 v[100:103], v[228:231], v[170:173], v[100:103]
	v_mfma_f32_16x16x32_bf16 v[92:95], v[202:205], v[178:181], v[92:95]
	v_mfma_f32_16x16x32_bf16 v[84:87], v[228:231], v[178:181], v[84:87]
	v_mfma_f32_16x16x32_bf16 v[76:79], v[202:205], v[186:189], v[76:79]
	v_mfma_f32_16x16x32_bf16 v[72:75], v[228:231], v[186:189], v[72:75]
	v_mfma_f32_16x16x32_bf16 v[68:71], v[202:205], v[194:197], v[68:71]
	v_mfma_f32_16x16x32_bf16 v[64:67], v[228:231], v[194:197], v[64:67]
	v_mfma_f32_16x16x32_bf16 v[108:111], v[206:209], v[174:177], v[108:111]
	v_mfma_f32_16x16x32_bf16 v[100:103], v[232:235], v[174:177], v[100:103]
	v_mfma_f32_16x16x32_bf16 v[92:95], v[206:209], v[182:185], v[92:95]
	v_mfma_f32_16x16x32_bf16 v[84:87], v[232:235], v[182:185], v[84:87]
	v_mfma_f32_16x16x32_bf16 v[76:79], v[206:209], v[190:193], v[76:79]
	v_mfma_f32_16x16x32_bf16 v[72:75], v[232:235], v[190:193], v[72:75]
	v_mfma_f32_16x16x32_bf16 v[68:71], v[206:209], v[198:201], v[68:71]
	v_mfma_f32_16x16x32_bf16 v[64:67], v[232:235], v[198:201], v[64:67]
	s_setprio 0
	s_mov_b32 m0, s11
	s_barrier
	ds_read_b128 v[170:173], v139 offset:16384
	ds_read_b128 v[174:177], v139 offset:17408
	ds_read_b128 v[178:181], v139 offset:18432
	ds_read_b128 v[182:185], v139 offset:19456
	ds_read_b128 v[186:189], v139 offset:20480
	ds_read_b128 v[190:193], v139 offset:21504
	ds_read_b128 v[194:197], v139 offset:22528
	ds_read_b128 v[198:201], v139 offset:23552
	global_load_lds_dwordx4 v128, s[68:69]
	s_mov_b32 m0, s13
	s_nop 0
	global_load_lds_dwordx4 v130, s[68:69]
	s_barrier
	s_waitcnt lgkmcnt(0)
	s_setprio 1
	v_mfma_f32_16x16x32_bf16 v[60:63], v[154:157], v[170:173], v[60:63]
	v_mfma_f32_16x16x32_bf16 v[56:59], v[162:165], v[170:173], v[56:59]
	v_mfma_f32_16x16x32_bf16 v[52:55], v[154:157], v[178:181], v[52:55]
	v_mfma_f32_16x16x32_bf16 v[48:51], v[162:165], v[178:181], v[48:51]
	v_mfma_f32_16x16x32_bf16 v[36:39], v[154:157], v[186:189], v[36:39]
	v_mfma_f32_16x16x32_bf16 v[32:35], v[162:165], v[186:189], v[32:35]
	v_mfma_f32_16x16x32_bf16 v[20:23], v[154:157], v[194:197], v[20:23]
	v_mfma_f32_16x16x32_bf16 v[16:19], v[162:165], v[194:197], v[16:19]
	v_mfma_f32_16x16x32_bf16 v[60:63], v[158:161], v[174:177], v[60:63]
	v_mfma_f32_16x16x32_bf16 v[56:59], v[166:169], v[174:177], v[56:59]
	v_mfma_f32_16x16x32_bf16 v[52:55], v[158:161], v[182:185], v[52:55]
	v_mfma_f32_16x16x32_bf16 v[48:51], v[166:169], v[182:185], v[48:51]
	v_mfma_f32_16x16x32_bf16 v[36:39], v[158:161], v[190:193], v[36:39]
	v_mfma_f32_16x16x32_bf16 v[32:35], v[166:169], v[190:193], v[32:35]
	v_mfma_f32_16x16x32_bf16 v[20:23], v[158:161], v[198:201], v[20:23]
	v_mfma_f32_16x16x32_bf16 v[16:19], v[166:169], v[198:201], v[16:19]
	s_setprio 0
	s_barrier
	s_add_u32 s18, s0, 0x100000
	s_addc_u32 s19, s1, 0
	s_add_i32 s2, s30, s20
	s_mov_b32 m0, s2
	s_nop 0
	global_load_lds_dwordx4 v140, s[18:19]
	s_add_i32 m0, s2, 0x2000
	s_nop 0
	global_load_lds_dwordx4 v132, s[18:19]
	s_waitcnt vmcnt(6)
	s_barrier
	s_setprio 1
	v_mfma_f32_16x16x32_bf16 v[44:47], v[202:205], v[170:173], v[44:47]
	v_mfma_f32_16x16x32_bf16 v[40:43], v[228:231], v[170:173], v[40:43]
	v_mfma_f32_16x16x32_bf16 v[28:31], v[202:205], v[178:181], v[28:31]
	v_mfma_f32_16x16x32_bf16 v[24:27], v[228:231], v[178:181], v[24:27]
	v_mfma_f32_16x16x32_bf16 v[12:15], v[202:205], v[186:189], v[12:15]
	v_mfma_f32_16x16x32_bf16 v[8:11], v[228:231], v[186:189], v[8:11]
	v_mfma_f32_16x16x32_bf16 v[4:7], v[202:205], v[194:197], v[4:7]
	v_mfma_f32_16x16x32_bf16 v[0:3], v[228:231], v[194:197], v[0:3]
	v_mfma_f32_16x16x32_bf16 v[44:47], v[206:209], v[174:177], v[44:47]
	v_mfma_f32_16x16x32_bf16 v[40:43], v[232:235], v[174:177], v[40:43]
	v_mfma_f32_16x16x32_bf16 v[28:31], v[206:209], v[182:185], v[28:31]
	v_mfma_f32_16x16x32_bf16 v[24:27], v[232:235], v[182:185], v[24:27]
	v_mfma_f32_16x16x32_bf16 v[12:15], v[206:209], v[190:193], v[12:15]
	v_mfma_f32_16x16x32_bf16 v[8:11], v[232:235], v[190:193], v[8:11]
	v_mfma_f32_16x16x32_bf16 v[4:7], v[206:209], v[198:201], v[4:7]
	v_mfma_f32_16x16x32_bf16 v[0:3], v[232:235], v[198:201], v[0:3]
	s_setprio 0
	s_add_i32 s2, 0, 0x18000
	v_add_u32_e32 v166, s2, v138
	s_barrier
	ds_read_b128 v[154:157], v166
	ds_read_b128 v[158:161], v166 offset:1024
	ds_read_b128 v[162:165], v166 offset:2048
	ds_read_b128 v[166:169], v166 offset:3072
	s_add_u32 s18, s68, 0x80000
	s_addc_u32 s19, s69, 0
	s_mov_b32 m0, s15
	ds_read_b128 v[170:173], v139 offset:32768
	ds_read_b128 v[174:177], v139 offset:33792
	ds_read_b128 v[178:181], v139 offset:34816
	ds_read_b128 v[182:185], v139 offset:35840
	ds_read_b128 v[186:189], v139 offset:36864
	ds_read_b128 v[190:193], v139 offset:37888
	ds_read_b128 v[194:197], v139 offset:38912
	ds_read_b128 v[198:201], v139 offset:39936
	global_load_lds_dwordx4 v128, s[18:19]
	s_mov_b32 m0, s21
	s_nop 0
	global_load_lds_dwordx4 v130, s[18:19]
	s_waitcnt lgkmcnt(8)
	s_barrier
	s_waitcnt lgkmcnt(0)
	s_setprio 1
	v_mfma_f32_16x16x32_bf16 v[124:127], v[154:157], v[170:173], v[124:127]
	v_mfma_f32_16x16x32_bf16 v[120:123], v[162:165], v[170:173], v[120:123]
	v_mfma_f32_16x16x32_bf16 v[116:119], v[154:157], v[178:181], v[116:119]
	v_mfma_f32_16x16x32_bf16 v[112:115], v[162:165], v[178:181], v[112:115]
	v_mfma_f32_16x16x32_bf16 v[104:107], v[154:157], v[186:189], v[104:107]
	v_mfma_f32_16x16x32_bf16 v[96:99], v[162:165], v[186:189], v[96:99]
	v_mfma_f32_16x16x32_bf16 v[88:91], v[154:157], v[194:197], v[88:91]
	v_mfma_f32_16x16x32_bf16 v[80:83], v[162:165], v[194:197], v[80:83]
	v_mfma_f32_16x16x32_bf16 v[124:127], v[158:161], v[174:177], v[124:127]
	v_mfma_f32_16x16x32_bf16 v[120:123], v[166:169], v[174:177], v[120:123]
	v_mfma_f32_16x16x32_bf16 v[116:119], v[158:161], v[182:185], v[116:119]
	v_mfma_f32_16x16x32_bf16 v[112:115], v[166:169], v[182:185], v[112:115]
	v_mfma_f32_16x16x32_bf16 v[104:107], v[158:161], v[190:193], v[104:107]
	v_mfma_f32_16x16x32_bf16 v[96:99], v[166:169], v[190:193], v[96:99]
	v_mfma_f32_16x16x32_bf16 v[88:91], v[158:161], v[198:201], v[88:91]
	v_mfma_f32_16x16x32_bf16 v[80:83], v[166:169], v[198:201], v[80:83]
	s_setprio 0
	s_barrier
	s_add_i32 s18, 0, 0x1c000
	s_add_i32 s2, s2, s20
	v_add_u32_e32 v232, s18, v138
	s_mov_b32 m0, s2
	ds_read_b128 v[202:205], v232
	ds_read_b128 v[206:209], v232 offset:1024
	ds_read_b128 v[228:231], v232 offset:2048
	ds_read_b128 v[232:235], v232 offset:3072
	s_add_u32 s100, s0, 0x80
	s_addc_u32 s101, s1, 0
	global_load_lds_dwordx4 v140, s[100:101]
	s_add_i32 m0, s2, 0x2000
	s_nop 0
	global_load_lds_dwordx4 v132, s[100:101]
	s_barrier
	s_waitcnt lgkmcnt(0)
	s_setprio 1
	v_mfma_f32_16x16x32_bf16 v[108:111], v[202:205], v[170:173], v[108:111]
	v_mfma_f32_16x16x32_bf16 v[100:103], v[228:231], v[170:173], v[100:103]
	v_mfma_f32_16x16x32_bf16 v[92:95], v[202:205], v[178:181], v[92:95]
	v_mfma_f32_16x16x32_bf16 v[84:87], v[228:231], v[178:181], v[84:87]
	v_mfma_f32_16x16x32_bf16 v[76:79], v[202:205], v[186:189], v[76:79]
	v_mfma_f32_16x16x32_bf16 v[72:75], v[228:231], v[186:189], v[72:75]
	v_mfma_f32_16x16x32_bf16 v[68:71], v[202:205], v[194:197], v[68:71]
	v_mfma_f32_16x16x32_bf16 v[64:67], v[228:231], v[194:197], v[64:67]
	v_mfma_f32_16x16x32_bf16 v[108:111], v[206:209], v[174:177], v[108:111]
	v_mfma_f32_16x16x32_bf16 v[100:103], v[232:235], v[174:177], v[100:103]
	v_mfma_f32_16x16x32_bf16 v[92:95], v[206:209], v[182:185], v[92:95]
	v_mfma_f32_16x16x32_bf16 v[84:87], v[232:235], v[182:185], v[84:87]
	v_mfma_f32_16x16x32_bf16 v[76:79], v[206:209], v[190:193], v[76:79]
	v_mfma_f32_16x16x32_bf16 v[72:75], v[232:235], v[190:193], v[72:75]
	v_mfma_f32_16x16x32_bf16 v[68:71], v[206:209], v[198:201], v[68:71]
	v_mfma_f32_16x16x32_bf16 v[64:67], v[232:235], v[198:201], v[64:67]
	s_setprio 0
	s_mov_b32 m0, s59
	s_barrier
	ds_read_b128 v[170:173], v139 offset:49152
	ds_read_b128 v[174:177], v139 offset:50176
	ds_read_b128 v[178:181], v139 offset:51200
	ds_read_b128 v[182:185], v139 offset:52224
	ds_read_b128 v[186:189], v139 offset:53248
	ds_read_b128 v[190:193], v139 offset:54272
	ds_read_b128 v[194:197], v139 offset:55296
	ds_read_b128 v[198:201], v139 offset:56320
	s_add_u32 s100, s68, 0x80
	s_addc_u32 s101, s69, 0
	global_load_lds_dwordx4 v128, s[100:101]
	s_mov_b32 m0, s71
	s_nop 0
	global_load_lds_dwordx4 v130, s[100:101]
	s_barrier
	s_waitcnt lgkmcnt(0)
	s_setprio 1
	v_mfma_f32_16x16x32_bf16 v[60:63], v[154:157], v[170:173], v[60:63]
	v_mfma_f32_16x16x32_bf16 v[56:59], v[162:165], v[170:173], v[56:59]
	v_mfma_f32_16x16x32_bf16 v[52:55], v[154:157], v[178:181], v[52:55]
	v_mfma_f32_16x16x32_bf16 v[48:51], v[162:165], v[178:181], v[48:51]
	v_mfma_f32_16x16x32_bf16 v[36:39], v[154:157], v[186:189], v[36:39]
	v_mfma_f32_16x16x32_bf16 v[32:35], v[162:165], v[186:189], v[32:35]
	v_mfma_f32_16x16x32_bf16 v[20:23], v[154:157], v[194:197], v[20:23]
	v_mfma_f32_16x16x32_bf16 v[16:19], v[162:165], v[194:197], v[16:19]
	v_mfma_f32_16x16x32_bf16 v[60:63], v[158:161], v[174:177], v[60:63]
	v_mfma_f32_16x16x32_bf16 v[56:59], v[166:169], v[174:177], v[56:59]
	v_mfma_f32_16x16x32_bf16 v[52:55], v[158:161], v[182:185], v[52:55]
	v_mfma_f32_16x16x32_bf16 v[48:51], v[166:169], v[182:185], v[48:51]
	v_mfma_f32_16x16x32_bf16 v[36:39], v[158:161], v[190:193], v[36:39]
	v_mfma_f32_16x16x32_bf16 v[32:35], v[166:169], v[190:193], v[32:35]
	v_mfma_f32_16x16x32_bf16 v[20:23], v[158:161], v[198:201], v[20:23]
	v_mfma_f32_16x16x32_bf16 v[16:19], v[166:169], v[198:201], v[16:19]
	s_setprio 0
	s_barrier
	s_add_u32 s0, s0, 0x100080
	s_addc_u32 s1, s1, 0
	s_add_i32 s2, s18, s20
	s_mov_b32 m0, s2
	s_nop 0
	global_load_lds_dwordx4 v140, s[0:1]
	s_add_i32 m0, s2, 0x2000
	s_nop 0
	global_load_lds_dwordx4 v132, s[0:1]
	s_waitcnt vmcnt(6)
	s_barrier
	s_setprio 1
	v_mfma_f32_16x16x32_bf16 v[44:47], v[202:205], v[170:173], v[44:47]
	v_mfma_f32_16x16x32_bf16 v[40:43], v[228:231], v[170:173], v[40:43]
	v_mfma_f32_16x16x32_bf16 v[28:31], v[202:205], v[178:181], v[28:31]
	v_mfma_f32_16x16x32_bf16 v[24:27], v[228:231], v[178:181], v[24:27]
	v_mfma_f32_16x16x32_bf16 v[12:15], v[202:205], v[186:189], v[12:15]
	v_mfma_f32_16x16x32_bf16 v[8:11], v[228:231], v[186:189], v[8:11]
	v_mfma_f32_16x16x32_bf16 v[4:7], v[202:205], v[194:197], v[4:7]
	v_mfma_f32_16x16x32_bf16 v[0:3], v[228:231], v[194:197], v[0:3]
	v_mfma_f32_16x16x32_bf16 v[44:47], v[206:209], v[174:177], v[44:47]
	v_mfma_f32_16x16x32_bf16 v[40:43], v[232:235], v[174:177], v[40:43]
	v_mfma_f32_16x16x32_bf16 v[28:31], v[206:209], v[182:185], v[28:31]
	v_mfma_f32_16x16x32_bf16 v[24:27], v[232:235], v[182:185], v[24:27]
	v_mfma_f32_16x16x32_bf16 v[12:15], v[206:209], v[190:193], v[12:15]
	v_mfma_f32_16x16x32_bf16 v[8:11], v[232:235], v[190:193], v[8:11]
	v_mfma_f32_16x16x32_bf16 v[4:7], v[206:209], v[198:201], v[4:7]
	v_mfma_f32_16x16x32_bf16 v[0:3], v[232:235], v[198:201], v[0:3]
	s_setprio 0
	s_add_i32 s45, s45, 2
	s_add_u32 s17, s17, 0x100
	s_addc_u32 s41, s41, 0
	s_add_u32 s66, s66, 0x100
	s_addc_u32 s67, s67, 0
	s_cmp_gt_u32 s45, 29
	s_barrier
	s_cbranch_scc0 .LBB0_169
	s_lshl_b32 s0, s10, 11
	s_lshl_b32 s1, s14, 8
	s_add_i32 s0, s0, s57
	v_mbcnt_lo_u32_b32 v155, -1, 0
	v_mbcnt_hi_u32_b32 v155, -1, v155
	s_lshl_b32 s2, s12, 8
	v_ashrrev_i32_e32 v154, 2, v155
	s_add_i32 s0, s0, s1
	v_and_b32_e32 v154, -4, v154
	s_or_b32 s2, s2, s58
	v_and_or_b32 v156, v155, 15, s0
	v_add_u32_e32 v154, s2, v154
	v_ashrrev_i32_e32 v157, 31, v156
	v_ashrrev_i32_e32 v155, 31, v154
	v_lshlrev_b64 v[158:159], 12, v[156:157]
	v_lshl_add_u64 v[158:159], s[26:27], 0, v[158:159]
	v_lshlrev_b64 v[154:155], 2, v[154:155]
	v_lshl_add_u64 v[158:159], v[158:159], 0, v[154:155]
	flat_store_dwordx4 v[158:159], v[124:127]
	flat_store_dwordx4 v[158:159], v[120:123] offset:64
	flat_store_dwordx4 v[158:159], v[108:111] offset:512
	flat_store_dwordx4 v[158:159], v[100:103] offset:576
	s_mov_b64 s[0:1], 0x80000
	s_mov_b32 s10, s16
	v_or_b32_e32 v100, 16, v156
	v_ashrrev_i32_e32 v101, 31, v100
	v_lshlrev_b64 v[100:101], 12, v[100:101]
	v_lshl_add_u64 v[100:101], s[26:27], 0, v[100:101]
	v_lshl_add_u64 v[100:101], v[100:101], 0, v[154:155]
	flat_store_dwordx4 v[100:101], v[116:119]
	flat_store_dwordx4 v[100:101], v[112:115] offset:64
	flat_store_dwordx4 v[100:101], v[92:95] offset:512
	flat_store_dwordx4 v[100:101], v[84:87] offset:576
	s_mov_b32 s12, s40
	s_mov_b32 s14, s44
	v_or_b32_e32 v84, 32, v156
	v_ashrrev_i32_e32 v85, 31, v84
	v_lshlrev_b64 v[84:85], 12, v[84:85]
	v_lshl_add_u64 v[84:85], s[26:27], 0, v[84:85]
	v_lshl_add_u64 v[84:85], v[84:85], 0, v[154:155]
	flat_store_dwordx4 v[84:85], v[104:107]
	flat_store_dwordx4 v[84:85], v[96:99] offset:64
	flat_store_dwordx4 v[84:85], v[76:79] offset:512
	flat_store_dwordx4 v[84:85], v[72:75] offset:576
	s_mov_b64 s[66:67], s[64:65]
	s_nop 0
	v_or_b32_e32 v72, 48, v156
	v_ashrrev_i32_e32 v73, 31, v72
	v_lshlrev_b64 v[72:73], 12, v[72:73]
	v_lshl_add_u64 v[72:73], s[26:27], 0, v[72:73]
	v_lshl_add_u64 v[72:73], v[72:73], 0, v[154:155]
	flat_store_dwordx4 v[72:73], v[88:91]
	flat_store_dwordx4 v[72:73], v[80:83] offset:64
	flat_store_dwordx4 v[72:73], v[68:71] offset:512
	flat_store_dwordx4 v[72:73], v[64:67] offset:576
	s_nop 1
	v_lshl_add_u64 v[64:65], v[158:159], 0, s[0:1]
	s_mov_b32 s0, 0x80000
	v_add_co_u32_e32 v66, vcc, s0, v158
	s_mov_b64 s[0:1], 0x90000
	s_nop 0
	v_addc_co_u32_e32 v67, vcc, 0, v159, vcc
	flat_store_dwordx4 v[66:67], v[60:63]
	flat_store_dwordx4 v[64:65], v[56:59] offset:64
	flat_store_dwordx4 v[64:65], v[44:47] offset:512
	flat_store_dwordx4 v[64:65], v[40:43] offset:576
	s_nop 1
	v_lshl_add_u64 v[40:41], v[158:159], 0, s[0:1]
	s_mov_b32 s0, 0x90000
	v_add_co_u32_e32 v42, vcc, s0, v158
	s_mov_b64 s[0:1], 0xa0000
	s_nop 0
	v_addc_co_u32_e32 v43, vcc, 0, v159, vcc
	flat_store_dwordx4 v[42:43], v[52:55]
	flat_store_dwordx4 v[40:41], v[48:51] offset:64
	flat_store_dwordx4 v[40:41], v[28:31] offset:512
	flat_store_dwordx4 v[40:41], v[24:27] offset:576
	s_nop 1
	v_lshl_add_u64 v[24:25], v[158:159], 0, s[0:1]
	s_mov_b32 s0, 0xa0000
	v_add_co_u32_e32 v26, vcc, s0, v158
	s_mov_b64 s[0:1], 0xb0000
	s_nop 0
	v_addc_co_u32_e32 v27, vcc, 0, v159, vcc
	flat_store_dwordx4 v[26:27], v[36:39]
	flat_store_dwordx4 v[24:25], v[32:35] offset:64
	flat_store_dwordx4 v[24:25], v[12:15] offset:512
	flat_store_dwordx4 v[24:25], v[8:11] offset:576
	s_nop 1
	v_add_co_u32_e32 v10, vcc, 0xb0000, v158
	v_lshl_add_u64 v[8:9], v[158:159], 0, s[0:1]
	s_nop 0
	v_addc_co_u32_e32 v11, vcc, 0, v159, vcc
	s_and_b64 vcc, exec, s[6:7]
	s_mov_b64 s[0:1], s[8:9]
	flat_store_dwordx4 v[10:11], v[20:23]
	flat_store_dwordx4 v[8:9], v[16:19] offset:64
	flat_store_dwordx4 v[8:9], v[4:7] offset:512
	flat_store_dwordx4 v[8:9], v[0:3] offset:576
	s_cbranch_vccz .LBB0_160
	s_waitcnt vmcnt(0)
	s_cmpk_gt_u32 s51, 0xff
	s_cbranch_scc1 .LBB0_173
	s_barrier

.LBB0_203:
	s_add_u32 s2, s44, s13
	s_addc_u32 s15, s45, 0
	s_add_u32 s17, s2, 0x100
	s_addc_u32 s21, s15, 0
	s_and_b64 s[18:19], s[0:1], exec
	s_cselect_b32 s81, s9, s21
	s_cselect_b32 s80, s8, s17
	s_add_u32 s13, s64, s13
	s_addc_u32 s17, s65, 0
	s_add_u32 s13, s13, 0x100
	s_addc_u32 s17, s17, 0
	s_add_i32 s21, 0, 0x10000
	s_and_b64 s[0:1], s[0:1], exec
	s_cselect_b32 s89, s11, s17
	s_cselect_b32 s88, s10, s13
	s_add_u32 s96, s2, 0x10080
	s_addc_u32 s97, s15, 0
	s_add_i32 s43, s21, s52
	s_add_i32 m0, s41, 0xc000
	s_add_i32 s47, s41, 0xe000
	s_add_i32 s42, 0, 0x14000
	s_add_i32 s31, s43, 0x2000
	s_add_u32 s76, s88, 0x40000
	v_add_u32_e32 v138, s21, v136
	s_addc_u32 s77, s89, 0
	s_add_i32 s19, s42, s52
	ds_read_b128 v[154:157], v138
	ds_read_b128 v[158:161], v138 offset:1024
	ds_read_b128 v[162:165], v138 offset:2048
	ds_read_b128 v[166:169], v138 offset:3072
	s_add_i32 s18, s19, 0x2000
	s_add_i32 s17, 0, 0x18000
	s_add_u32 s68, s80, 0x10000
	s_addc_u32 s69, s81, 0
	s_add_i32 s15, s17, s52
	s_add_i32 s13, 0, 0x1c000
	s_add_i32 s2, s15, 0x2000
	s_add_u32 s0, s88, 0x40080
	s_addc_u32 s1, s89, 0
	s_add_i32 s30, s13, s52
	s_add_i32 s21, s30, 0x2000
	ds_read_b128 v[170:173], v137
	ds_read_b128 v[174:177], v137 offset:1024
	ds_read_b128 v[178:181], v137 offset:2048
	ds_read_b128 v[182:185], v137 offset:3072
	ds_read_b128 v[186:189], v137 offset:4096
	ds_read_b128 v[190:193], v137 offset:5120
	ds_read_b128 v[194:197], v137 offset:6144
	ds_read_b128 v[198:201], v137 offset:7168
	global_load_lds_dwordx4 v128, s[96:97]
	s_mov_b32 m0, s47
	s_nop 0
	global_load_lds_dwordx4 v132, s[96:97]
	s_waitcnt lgkmcnt(8)
	s_barrier
	s_waitcnt lgkmcnt(0)
	s_setprio 1
	v_mfma_f32_16x16x32_bf16 v[124:127], v[154:157], v[170:173], v[124:127]
	v_mfma_f32_16x16x32_bf16 v[120:123], v[162:165], v[170:173], v[120:123]
	v_mfma_f32_16x16x32_bf16 v[112:115], v[154:157], v[178:181], v[112:115]
	v_mfma_f32_16x16x32_bf16 v[104:107], v[162:165], v[178:181], v[104:107]
	v_mfma_f32_16x16x32_bf16 v[96:99], v[154:157], v[186:189], v[96:99]
	v_mfma_f32_16x16x32_bf16 v[88:91], v[162:165], v[186:189], v[88:91]
	v_mfma_f32_16x16x32_bf16 v[80:83], v[154:157], v[194:197], v[80:83]
	v_mfma_f32_16x16x32_bf16 v[72:75], v[162:165], v[194:197], v[72:75]
	v_mfma_f32_16x16x32_bf16 v[124:127], v[158:161], v[174:177], v[124:127]
	v_mfma_f32_16x16x32_bf16 v[120:123], v[166:169], v[174:177], v[120:123]
	v_mfma_f32_16x16x32_bf16 v[112:115], v[158:161], v[182:185], v[112:115]
	v_mfma_f32_16x16x32_bf16 v[104:107], v[166:169], v[182:185], v[104:107]
	v_mfma_f32_16x16x32_bf16 v[96:99], v[158:161], v[190:193], v[96:99]
	v_mfma_f32_16x16x32_bf16 v[88:91], v[166:169], v[190:193], v[88:91]
	v_mfma_f32_16x16x32_bf16 v[80:83], v[158:161], v[198:201], v[80:83]
	v_mfma_f32_16x16x32_bf16 v[72:75], v[166:169], v[198:201], v[72:75]
	s_setprio 0
	s_barrier
	v_add_u32_e32 v138, s42, v136
	s_mov_b32 m0, s43
	ds_read_b128 v[202:205], v138
	ds_read_b128 v[206:209], v138 offset:1024
	ds_read_b128 v[228:231], v138 offset:2048
	ds_read_b128 v[232:235], v138 offset:3072
	global_load_lds_dwordx4 v130, s[88:89]
	s_mov_b32 m0, s31
	s_nop 0
	global_load_lds_dwordx4 v134, s[88:89]
	s_barrier
	s_waitcnt lgkmcnt(0)
	s_setprio 1
	v_mfma_f32_16x16x32_bf16 v[116:119], v[202:205], v[170:173], v[116:119]
	v_mfma_f32_16x16x32_bf16 v[108:111], v[228:231], v[170:173], v[108:111]
	v_mfma_f32_16x16x32_bf16 v[100:103], v[202:205], v[178:181], v[100:103]
	v_mfma_f32_16x16x32_bf16 v[92:95], v[228:231], v[178:181], v[92:95]
	v_mfma_f32_16x16x32_bf16 v[84:87], v[202:205], v[186:189], v[84:87]
	v_mfma_f32_16x16x32_bf16 v[76:79], v[228:231], v[186:189], v[76:79]
	v_mfma_f32_16x16x32_bf16 v[68:71], v[202:205], v[194:197], v[68:71]
	v_mfma_f32_16x16x32_bf16 v[64:67], v[228:231], v[194:197], v[64:67]
	v_mfma_f32_16x16x32_bf16 v[116:119], v[206:209], v[174:177], v[116:119]
	v_mfma_f32_16x16x32_bf16 v[108:111], v[232:235], v[174:177], v[108:111]
	v_mfma_f32_16x16x32_bf16 v[100:103], v[206:209], v[182:185], v[100:103]
	v_mfma_f32_16x16x32_bf16 v[92:95], v[232:235], v[182:185], v[92:95]
	v_mfma_f32_16x16x32_bf16 v[84:87], v[206:209], v[190:193], v[84:87]
	v_mfma_f32_16x16x32_bf16 v[76:79], v[232:235], v[190:193], v[76:79]
	v_mfma_f32_16x16x32_bf16 v[68:71], v[206:209], v[198:201], v[68:71]
	v_mfma_f32_16x16x32_bf16 v[64:67], v[232:235], v[198:201], v[64:67]
	s_setprio 0
	s_mov_b32 m0, s41
	s_barrier
	ds_read_b128 v[170:173], v137 offset:16384
	ds_read_b128 v[174:177], v137 offset:17408
	ds_read_b128 v[178:181], v137 offset:18432
	ds_read_b128 v[182:185], v137 offset:19456
	ds_read_b128 v[186:189], v137 offset:20480
	ds_read_b128 v[190:193], v137 offset:21504
	ds_read_b128 v[194:197], v137 offset:22528
	ds_read_b128 v[198:201], v137 offset:23552
	global_load_lds_dwordx4 v128, s[80:81]
	s_mov_b32 m0, s57
	s_nop 0
	global_load_lds_dwordx4 v132, s[80:81]
	s_barrier
	s_waitcnt lgkmcnt(0)
	s_setprio 1
	v_mfma_f32_16x16x32_bf16 v[60:63], v[154:157], v[170:173], v[60:63]
	v_mfma_f32_16x16x32_bf16 v[56:59], v[162:165], v[170:173], v[56:59]
	v_mfma_f32_16x16x32_bf16 v[48:51], v[154:157], v[178:181], v[48:51]
	v_mfma_f32_16x16x32_bf16 v[40:43], v[162:165], v[178:181], v[40:43]
	v_mfma_f32_16x16x32_bf16 v[32:35], v[154:157], v[186:189], v[32:35]
	v_mfma_f32_16x16x32_bf16 v[24:27], v[162:165], v[186:189], v[24:27]
	v_mfma_f32_16x16x32_bf16 v[16:19], v[154:157], v[194:197], v[16:19]
	v_mfma_f32_16x16x32_bf16 v[8:11], v[162:165], v[194:197], v[8:11]
	v_mfma_f32_16x16x32_bf16 v[60:63], v[158:161], v[174:177], v[60:63]
	v_mfma_f32_16x16x32_bf16 v[56:59], v[166:169], v[174:177], v[56:59]
	v_mfma_f32_16x16x32_bf16 v[48:51], v[158:161], v[182:185], v[48:51]
	v_mfma_f32_16x16x32_bf16 v[40:43], v[166:169], v[182:185], v[40:43]
	v_mfma_f32_16x16x32_bf16 v[32:35], v[158:161], v[190:193], v[32:35]
	v_mfma_f32_16x16x32_bf16 v[24:27], v[166:169], v[190:193], v[24:27]
	v_mfma_f32_16x16x32_bf16 v[16:19], v[158:161], v[198:201], v[16:19]
	v_mfma_f32_16x16x32_bf16 v[8:11], v[166:169], v[198:201], v[8:11]
	s_setprio 0
	s_barrier
	s_mov_b32 m0, s19
	s_nop 0
	global_load_lds_dwordx4 v130, s[76:77]
	s_mov_b32 m0, s18
	s_nop 0
	global_load_lds_dwordx4 v134, s[76:77]
	s_waitcnt vmcnt(6)
	s_barrier
	s_setprio 1
	v_mfma_f32_16x16x32_bf16 v[52:55], v[202:205], v[170:173], v[52:55]
	v_mfma_f32_16x16x32_bf16 v[44:47], v[228:231], v[170:173], v[44:47]
	v_mfma_f32_16x16x32_bf16 v[36:39], v[202:205], v[178:181], v[36:39]
	v_mfma_f32_16x16x32_bf16 v[28:31], v[228:231], v[178:181], v[28:31]
	v_mfma_f32_16x16x32_bf16 v[20:23], v[202:205], v[186:189], v[20:23]
	v_mfma_f32_16x16x32_bf16 v[12:15], v[228:231], v[186:189], v[12:15]
	v_mfma_f32_16x16x32_bf16 v[4:7], v[202:205], v[194:197], v[4:7]
	v_mfma_f32_16x16x32_bf16 v[0:3], v[228:231], v[194:197], v[0:3]
	v_mfma_f32_16x16x32_bf16 v[52:55], v[206:209], v[174:177], v[52:55]
	v_mfma_f32_16x16x32_bf16 v[44:47], v[232:235], v[174:177], v[44:47]
	v_mfma_f32_16x16x32_bf16 v[36:39], v[206:209], v[182:185], v[36:39]
	v_mfma_f32_16x16x32_bf16 v[28:31], v[232:235], v[182:185], v[28:31]
	v_mfma_f32_16x16x32_bf16 v[20:23], v[206:209], v[190:193], v[20:23]
	v_mfma_f32_16x16x32_bf16 v[12:15], v[232:235], v[190:193], v[12:15]
	v_mfma_f32_16x16x32_bf16 v[4:7], v[206:209], v[198:201], v[4:7]
	v_mfma_f32_16x16x32_bf16 v[0:3], v[232:235], v[198:201], v[0:3]
	s_setprio 0
	v_add_u32_e32 v140, s17, v136
	s_barrier
	ds_read_b128 v[154:157], v140
	ds_read_b128 v[158:161], v140 offset:1024
	ds_read_b128 v[162:165], v140 offset:2048
	ds_read_b128 v[166:169], v140 offset:3072
	s_mov_b32 m0, s58
	ds_read_b128 v[170:173], v137 offset:32768
	ds_read_b128 v[174:177], v137 offset:33792
	ds_read_b128 v[178:181], v137 offset:34816
	ds_read_b128 v[182:185], v137 offset:35840
	ds_read_b128 v[186:189], v137 offset:36864
	ds_read_b128 v[190:193], v137 offset:37888
	ds_read_b128 v[194:197], v137 offset:38912
	ds_read_b128 v[198:201], v137 offset:39936
	global_load_lds_dwordx4 v128, s[68:69]
	s_mov_b32 m0, s59
	s_nop 0
	global_load_lds_dwordx4 v132, s[68:69]
	s_waitcnt lgkmcnt(8)
	s_barrier
	s_waitcnt lgkmcnt(0)
	s_setprio 1
	v_mfma_f32_16x16x32_bf16 v[124:127], v[154:157], v[170:173], v[124:127]
	v_mfma_f32_16x16x32_bf16 v[120:123], v[162:165], v[170:173], v[120:123]
	v_mfma_f32_16x16x32_bf16 v[112:115], v[154:157], v[178:181], v[112:115]
	v_mfma_f32_16x16x32_bf16 v[104:107], v[162:165], v[178:181], v[104:107]
	v_mfma_f32_16x16x32_bf16 v[96:99], v[154:157], v[186:189], v[96:99]
	v_mfma_f32_16x16x32_bf16 v[88:91], v[162:165], v[186:189], v[88:91]
	v_mfma_f32_16x16x32_bf16 v[80:83], v[154:157], v[194:197], v[80:83]
	v_mfma_f32_16x16x32_bf16 v[72:75], v[162:165], v[194:197], v[72:75]
	v_mfma_f32_16x16x32_bf16 v[124:127], v[158:161], v[174:177], v[124:127]
	v_mfma_f32_16x16x32_bf16 v[120:123], v[166:169], v[174:177], v[120:123]
	v_mfma_f32_16x16x32_bf16 v[112:115], v[158:161], v[182:185], v[112:115]
	v_mfma_f32_16x16x32_bf16 v[104:107], v[166:169], v[182:185], v[104:107]
	v_mfma_f32_16x16x32_bf16 v[96:99], v[158:161], v[190:193], v[96:99]
	v_mfma_f32_16x16x32_bf16 v[88:91], v[166:169], v[190:193], v[88:91]
	v_mfma_f32_16x16x32_bf16 v[80:83], v[158:161], v[198:201], v[80:83]
	v_mfma_f32_16x16x32_bf16 v[72:75], v[166:169], v[198:201], v[72:75]
	s_setprio 0
	s_barrier
	s_mov_b32 m0, s15
	v_add_u32_e32 v140, s13, v136
	ds_read_b128 v[202:205], v140
	ds_read_b128 v[206:209], v140 offset:1024
	ds_read_b128 v[228:231], v140 offset:2048
	ds_read_b128 v[232:235], v140 offset:3072
	s_add_u32 s100, s88, 0x80
	s_addc_u32 s101, s89, 0
	global_load_lds_dwordx4 v130, s[100:101]
	s_mov_b32 m0, s2
	s_nop 0
	global_load_lds_dwordx4 v134, s[100:101]
	s_barrier
	s_waitcnt lgkmcnt(0)
	s_setprio 1
	v_mfma_f32_16x16x32_bf16 v[116:119], v[202:205], v[170:173], v[116:119]
	v_mfma_f32_16x16x32_bf16 v[108:111], v[228:231], v[170:173], v[108:111]
	v_mfma_f32_16x16x32_bf16 v[100:103], v[202:205], v[178:181], v[100:103]
	v_mfma_f32_16x16x32_bf16 v[92:95], v[228:231], v[178:181], v[92:95]
	v_mfma_f32_16x16x32_bf16 v[84:87], v[202:205], v[186:189], v[84:87]
	v_mfma_f32_16x16x32_bf16 v[76:79], v[228:231], v[186:189], v[76:79]
	v_mfma_f32_16x16x32_bf16 v[68:71], v[202:205], v[194:197], v[68:71]
	v_mfma_f32_16x16x32_bf16 v[64:67], v[228:231], v[194:197], v[64:67]
	v_mfma_f32_16x16x32_bf16 v[116:119], v[206:209], v[174:177], v[116:119]
	v_mfma_f32_16x16x32_bf16 v[108:111], v[232:235], v[174:177], v[108:111]
	v_mfma_f32_16x16x32_bf16 v[100:103], v[206:209], v[182:185], v[100:103]
	v_mfma_f32_16x16x32_bf16 v[92:95], v[232:235], v[182:185], v[92:95]
	v_mfma_f32_16x16x32_bf16 v[84:87], v[206:209], v[190:193], v[84:87]
	v_mfma_f32_16x16x32_bf16 v[76:79], v[232:235], v[190:193], v[76:79]
	v_mfma_f32_16x16x32_bf16 v[68:71], v[206:209], v[198:201], v[68:71]
	v_mfma_f32_16x16x32_bf16 v[64:67], v[232:235], v[198:201], v[64:67]
	s_setprio 0
	s_mov_b32 m0, s73
	s_barrier
	ds_read_b128 v[170:173], v137 offset:49152
	ds_read_b128 v[174:177], v137 offset:50176
	ds_read_b128 v[178:181], v137 offset:51200
	ds_read_b128 v[182:185], v137 offset:52224
	ds_read_b128 v[186:189], v137 offset:53248
	ds_read_b128 v[190:193], v137 offset:54272
	ds_read_b128 v[194:197], v137 offset:55296
	ds_read_b128 v[198:201], v137 offset:56320
	s_add_u32 s100, s80, 0x80
	s_addc_u32 s101, s81, 0
	global_load_lds_dwordx4 v128, s[100:101]
	s_mov_b32 m0, s74
	s_nop 0
	global_load_lds_dwordx4 v132, s[100:101]
	s_barrier
	s_waitcnt lgkmcnt(0)
	s_setprio 1
	v_mfma_f32_16x16x32_bf16 v[60:63], v[154:157], v[170:173], v[60:63]
	v_mfma_f32_16x16x32_bf16 v[56:59], v[162:165], v[170:173], v[56:59]
	v_mfma_f32_16x16x32_bf16 v[48:51], v[154:157], v[178:181], v[48:51]
	v_mfma_f32_16x16x32_bf16 v[40:43], v[162:165], v[178:181], v[40:43]
	v_mfma_f32_16x16x32_bf16 v[32:35], v[154:157], v[186:189], v[32:35]
	v_mfma_f32_16x16x32_bf16 v[24:27], v[162:165], v[186:189], v[24:27]
	v_mfma_f32_16x16x32_bf16 v[16:19], v[154:157], v[194:197], v[16:19]
	v_mfma_f32_16x16x32_bf16 v[8:11], v[162:165], v[194:197], v[8:11]
	v_mfma_f32_16x16x32_bf16 v[60:63], v[158:161], v[174:177], v[60:63]
	v_mfma_f32_16x16x32_bf16 v[56:59], v[166:169], v[174:177], v[56:59]
	v_mfma_f32_16x16x32_bf16 v[48:51], v[158:161], v[182:185], v[48:51]
	v_mfma_f32_16x16x32_bf16 v[40:43], v[166:169], v[182:185], v[40:43]
	v_mfma_f32_16x16x32_bf16 v[32:35], v[158:161], v[190:193], v[32:35]
	v_mfma_f32_16x16x32_bf16 v[24:27], v[166:169], v[190:193], v[24:27]
	v_mfma_f32_16x16x32_bf16 v[16:19], v[158:161], v[198:201], v[16:19]
	v_mfma_f32_16x16x32_bf16 v[8:11], v[166:169], v[198:201], v[8:11]
	s_setprio 0
	s_barrier
	s_mov_b32 m0, s30
	s_nop 0
	global_load_lds_dwordx4 v130, s[0:1]
	s_mov_b32 m0, s21
	s_nop 0
	global_load_lds_dwordx4 v134, s[0:1]
	s_waitcnt vmcnt(6)
	s_barrier
	s_setprio 1
	v_mfma_f32_16x16x32_bf16 v[52:55], v[202:205], v[170:173], v[52:55]
	v_mfma_f32_16x16x32_bf16 v[44:47], v[228:231], v[170:173], v[44:47]
	v_mfma_f32_16x16x32_bf16 v[36:39], v[202:205], v[178:181], v[36:39]
	v_mfma_f32_16x16x32_bf16 v[28:31], v[228:231], v[178:181], v[28:31]
	v_mfma_f32_16x16x32_bf16 v[20:23], v[202:205], v[186:189], v[20:23]
	v_mfma_f32_16x16x32_bf16 v[12:15], v[228:231], v[186:189], v[12:15]
	v_mfma_f32_16x16x32_bf16 v[4:7], v[202:205], v[194:197], v[4:7]
	v_mfma_f32_16x16x32_bf16 v[0:3], v[228:231], v[194:197], v[0:3]
	v_mfma_f32_16x16x32_bf16 v[52:55], v[206:209], v[174:177], v[52:55]
	v_mfma_f32_16x16x32_bf16 v[44:47], v[232:235], v[174:177], v[44:47]
	v_mfma_f32_16x16x32_bf16 v[36:39], v[206:209], v[182:185], v[36:39]
	v_mfma_f32_16x16x32_bf16 v[28:31], v[232:235], v[182:185], v[28:31]
	v_mfma_f32_16x16x32_bf16 v[20:23], v[206:209], v[190:193], v[20:23]
	v_mfma_f32_16x16x32_bf16 v[12:15], v[232:235], v[190:193], v[12:15]
	v_mfma_f32_16x16x32_bf16 v[4:7], v[206:209], v[198:201], v[4:7]
	v_mfma_f32_16x16x32_bf16 v[0:3], v[232:235], v[198:201], v[0:3]
	s_setprio 0
	s_movk_i32 s13, 0x100
	s_andn2_b64 vcc, exec, s[66:67]
	s_mov_b64 s[0:1], -1
	s_mov_b64 s[66:67], 0
	s_barrier
	s_cbranch_vccz .LBB0_203
	v_mbcnt_lo_u32_b32 v138, -1, 0
	v_mbcnt_hi_u32_b32 v138, -1, v138
	s_lshl_b32 s0, s40, 8
	v_ashrrev_i32_e32 v139, 1, v138
	s_or_b32 s0, s0, s72
	v_and_b32_e32 v139, -8, v139
	v_add_u32_e32 v139, s0, v139
	s_lshl_b32 s1, s20, 8
	v_and_or_b32 v138, v138, 15, s71
	s_and_b32 s1, s1, 0x300
	v_cvt_pk_bf16_f32 v124, v124, v125
	v_cvt_pk_bf16_f32 v125, v126, v127
	v_cvt_pk_bf16_f32 v126, v120, v121
	v_ashrrev_i32_e32 v120, 1, v139
	v_add_u32_e32 v138, s1, v138
	v_cvt_pk_bf16_f32 v127, v122, v123
	v_and_b32_e32 v122, 0xfffffc00, v120
	v_add_u32_e32 v120, v122, v138
	s_ashr_i32 s0, s20, 2
	v_ashrrev_i32_e32 v121, 31, v120
	s_ashr_i32 s1, s0, 31
	v_lshlrev_b64 v[120:121], 13, v[120:121]
	s_lshl_b64 s[0:1], s[0:1], 12
	v_and_b32_e32 v140, 0x7f8, v139
	v_lshl_add_u64 v[120:121], s[38:39], 0, v[120:121]
	v_lshl_add_u64 v[120:121], v[120:121], 0, s[0:1]
	v_lshlrev_b32_e32 v140, 1, v140
	v_lshl_add_u64 v[120:121], v[120:121], 0, v[140:141]
	flat_store_dwordx4 v[120:121], v[124:127]
	v_add_u32_e32 v120, 0x80, v139
	v_cvt_pk_bf16_f32 v116, v116, v117
	v_cvt_pk_bf16_f32 v117, v118, v119
	v_cvt_pk_bf16_f32 v118, v108, v109
	v_ashrrev_i32_e32 v108, 1, v120
	v_and_b32_e32 v121, 0x7f8, v120
	v_and_b32_e32 v120, 0xfffffc00, v108
	v_add_u32_e32 v108, v120, v138
	v_ashrrev_i32_e32 v109, 31, v108
	v_lshlrev_b64 v[108:109], 13, v[108:109]
	v_lshl_add_u64 v[108:109], s[38:39], 0, v[108:109]
	v_cvt_pk_bf16_f32 v119, v110, v111
	v_lshl_add_u64 v[110:111], v[108:109], 0, s[0:1]
	v_lshlrev_b32_e32 v108, 1, v121
	v_mov_b32_e32 v109, v141
	v_lshl_add_u64 v[110:111], v[110:111], 0, v[108:109]
	flat_store_dwordx4 v[110:111], v[116:119]
	v_cvt_pk_bf16_f32 v110, v112, v113
	v_cvt_pk_bf16_f32 v112, v104, v105
	v_cvt_pk_bf16_f32 v100, v100, v101
	v_cvt_pk_bf16_f32 v101, v102, v103
	v_cvt_pk_bf16_f32 v102, v92, v93
	s_nop 1
	v_or_b32_e32 v116, 16, v138
	v_add_u32_e32 v104, v122, v116
	v_add_u32_e32 v92, v120, v116
	v_ashrrev_i32_e32 v105, 31, v104
	v_ashrrev_i32_e32 v93, 31, v92
	v_lshlrev_b64 v[104:105], 13, v[104:105]
	v_lshlrev_b64 v[92:93], 13, v[92:93]
	v_lshl_add_u64 v[104:105], s[38:39], 0, v[104:105]
	v_lshl_add_u64 v[92:93], s[38:39], 0, v[92:93]
	v_lshl_add_u64 v[104:105], v[104:105], 0, s[0:1]
	v_lshl_add_u64 v[92:93], v[92:93], 0, s[0:1]
	v_lshl_add_u64 v[104:105], v[104:105], 0, v[140:141]
	v_lshl_add_u64 v[92:93], v[92:93], 0, v[108:109]
	v_cvt_pk_bf16_f32 v111, v114, v115
	v_cvt_pk_bf16_f32 v113, v106, v107
	flat_store_dwordx4 v[104:105], v[110:113]
	v_cvt_pk_bf16_f32 v103, v94, v95
	flat_store_dwordx4 v[92:93], v[100:103]
	v_cvt_pk_bf16_f32 v94, v88, v89
	v_cvt_pk_bf16_f32 v84, v84, v85
	v_cvt_pk_bf16_f32 v85, v86, v87
	v_cvt_pk_bf16_f32 v86, v76, v77
	v_cvt_pk_bf16_f32 v92, v96, v97
	s_nop 1
	v_or_b32_e32 v100, 32, v138
	v_add_u32_e32 v88, v122, v100
	v_add_u32_e32 v76, v120, v100
	v_ashrrev_i32_e32 v89, 31, v88
	v_ashrrev_i32_e32 v77, 31, v76
	v_lshlrev_b64 v[88:89], 13, v[88:89]
	v_lshlrev_b64 v[76:77], 13, v[76:77]
	v_lshl_add_u64 v[88:89], s[38:39], 0, v[88:89]
	v_lshl_add_u64 v[76:77], s[38:39], 0, v[76:77]
	v_lshl_add_u64 v[88:89], v[88:89], 0, s[0:1]
	v_lshl_add_u64 v[76:77], v[76:77], 0, s[0:1]
	v_lshl_add_u64 v[88:89], v[88:89], 0, v[140:141]
	v_lshl_add_u64 v[76:77], v[76:77], 0, v[108:109]
	v_cvt_pk_bf16_f32 v93, v98, v99
	v_cvt_pk_bf16_f32 v95, v90, v91
	flat_store_dwordx4 v[88:89], v[92:95]
	v_cvt_pk_bf16_f32 v87, v78, v79
	flat_store_dwordx4 v[76:77], v[84:87]
	v_cvt_pk_bf16_f32 v78, v72, v73
	v_cvt_pk_bf16_f32 v68, v68, v69
	v_cvt_pk_bf16_f32 v69, v70, v71
	v_cvt_pk_bf16_f32 v70, v64, v65
	v_cvt_pk_bf16_f32 v76, v80, v81
	s_nop 1
	v_or_b32_e32 v84, 48, v138
	v_add_u32_e32 v72, v122, v84
	v_add_u32_e32 v64, v120, v84
	v_ashrrev_i32_e32 v73, 31, v72
	v_ashrrev_i32_e32 v65, 31, v64
	v_lshlrev_b64 v[72:73], 13, v[72:73]
	v_lshlrev_b64 v[64:65], 13, v[64:65]
	v_lshl_add_u64 v[72:73], s[38:39], 0, v[72:73]
	v_lshl_add_u64 v[64:65], s[38:39], 0, v[64:65]
	v_lshl_add_u64 v[72:73], v[72:73], 0, s[0:1]
	v_lshl_add_u64 v[64:65], v[64:65], 0, s[0:1]
	v_lshl_add_u64 v[72:73], v[72:73], 0, v[140:141]
	v_lshl_add_u64 v[64:65], v[64:65], 0, v[108:109]
	v_cvt_pk_bf16_f32 v77, v82, v83
	v_cvt_pk_bf16_f32 v79, v74, v75
	flat_store_dwordx4 v[72:73], v[76:79]
	v_cvt_pk_bf16_f32 v71, v66, v67
	flat_store_dwordx4 v[64:65], v[68:71]
	v_add_u32_e32 v64, 0x80, v138
	v_cvt_pk_bf16_f32 v60, v60, v61
	v_cvt_pk_bf16_f32 v61, v62, v63
	v_cvt_pk_bf16_f32 v62, v56, v57
	v_add_u32_e32 v56, v122, v64
	v_cvt_pk_bf16_f32 v52, v52, v53
	v_cvt_pk_bf16_f32 v53, v54, v55
	v_cvt_pk_bf16_f32 v54, v44, v45
	v_add_u32_e32 v44, v120, v64
	v_ashrrev_i32_e32 v57, 31, v56
	v_ashrrev_i32_e32 v45, 31, v44
	v_lshlrev_b64 v[56:57], 13, v[56:57]
	v_lshlrev_b64 v[44:45], 13, v[44:45]
	v_lshl_add_u64 v[56:57], s[38:39], 0, v[56:57]
	v_lshl_add_u64 v[44:45], s[38:39], 0, v[44:45]
	v_lshl_add_u64 v[56:57], v[56:57], 0, s[0:1]
	v_lshl_add_u64 v[44:45], v[44:45], 0, s[0:1]
	v_lshl_add_u64 v[56:57], v[56:57], 0, v[140:141]
	v_lshl_add_u64 v[44:45], v[44:45], 0, v[108:109]
	v_cvt_pk_bf16_f32 v63, v58, v59
	flat_store_dwordx4 v[56:57], v[60:63]
	v_cvt_pk_bf16_f32 v55, v46, v47
	flat_store_dwordx4 v[44:45], v[52:55]
	v_cvt_pk_bf16_f32 v46, v40, v41
	v_cvt_pk_bf16_f32 v36, v36, v37
	v_cvt_pk_bf16_f32 v37, v38, v39
	v_cvt_pk_bf16_f32 v38, v28, v29
	v_cvt_pk_bf16_f32 v44, v48, v49
	s_nop 1
	v_add_u32_e32 v52, 0x90, v138
	v_add_u32_e32 v40, v122, v52
	v_add_u32_e32 v28, v120, v52
	v_ashrrev_i32_e32 v41, 31, v40
	v_ashrrev_i32_e32 v29, 31, v28
	v_lshlrev_b64 v[40:41], 13, v[40:41]
	v_lshlrev_b64 v[28:29], 13, v[28:29]
	v_lshl_add_u64 v[40:41], s[38:39], 0, v[40:41]
	v_lshl_add_u64 v[28:29], s[38:39], 0, v[28:29]
	v_lshl_add_u64 v[40:41], v[40:41], 0, s[0:1]
	v_lshl_add_u64 v[28:29], v[28:29], 0, s[0:1]
	v_lshl_add_u64 v[40:41], v[40:41], 0, v[140:141]
	v_lshl_add_u64 v[28:29], v[28:29], 0, v[108:109]
	v_cvt_pk_bf16_f32 v45, v50, v51
	v_cvt_pk_bf16_f32 v47, v42, v43
	flat_store_dwordx4 v[40:41], v[44:47]
	v_cvt_pk_bf16_f32 v39, v30, v31
	flat_store_dwordx4 v[28:29], v[36:39]
	v_cvt_pk_bf16_f32 v30, v24, v25
	v_cvt_pk_bf16_f32 v20, v20, v21
	v_cvt_pk_bf16_f32 v21, v22, v23
	v_cvt_pk_bf16_f32 v22, v12, v13
	v_cvt_pk_bf16_f32 v28, v32, v33
	s_nop 1
	v_add_u32_e32 v36, 0xa0, v138
	v_add_u32_e32 v24, v122, v36
	v_add_u32_e32 v12, v120, v36
	v_ashrrev_i32_e32 v25, 31, v24
	v_ashrrev_i32_e32 v13, 31, v12
	v_lshlrev_b64 v[24:25], 13, v[24:25]
	v_lshlrev_b64 v[12:13], 13, v[12:13]
	v_lshl_add_u64 v[24:25], s[38:39], 0, v[24:25]
	v_lshl_add_u64 v[12:13], s[38:39], 0, v[12:13]
	v_lshl_add_u64 v[24:25], v[24:25], 0, s[0:1]
	v_lshl_add_u64 v[12:13], v[12:13], 0, s[0:1]
	v_lshl_add_u64 v[24:25], v[24:25], 0, v[140:141]
	v_lshl_add_u64 v[12:13], v[12:13], 0, v[108:109]
	v_cvt_pk_bf16_f32 v29, v34, v35
	v_cvt_pk_bf16_f32 v31, v26, v27
	flat_store_dwordx4 v[24:25], v[28:31]
	v_cvt_pk_bf16_f32 v23, v14, v15
	flat_store_dwordx4 v[12:13], v[20:23]
	v_cvt_pk_bf16_f32 v14, v8, v9
	v_cvt_pk_bf16_f32 v4, v4, v5
	v_cvt_pk_bf16_f32 v5, v6, v7
	v_cvt_pk_bf16_f32 v6, v0, v1
	s_and_b64 vcc, exec, s[6:7]
	s_nop 0
	v_add_u32_e32 v20, 0xb0, v138
	v_add_u32_e32 v8, v122, v20
	v_add_u32_e32 v0, v120, v20
	v_ashrrev_i32_e32 v9, 31, v8
	v_ashrrev_i32_e32 v1, 31, v0
	v_lshlrev_b64 v[8:9], 13, v[8:9]
	v_lshlrev_b64 v[0:1], 13, v[0:1]
	v_lshl_add_u64 v[8:9], s[38:39], 0, v[8:9]
	v_lshl_add_u64 v[0:1], s[38:39], 0, v[0:1]
	v_lshl_add_u64 v[8:9], v[8:9], 0, s[0:1]
	v_lshl_add_u64 v[0:1], v[0:1], 0, s[0:1]
	v_lshl_add_u64 v[8:9], v[8:9], 0, v[140:141]
	v_lshl_add_u64 v[0:1], v[0:1], 0, v[108:109]
	s_mov_b32 s20, s12
	s_mov_b32 s40, s14
	s_mov_b64 s[64:65], s[10:11]
	s_mov_b64 s[44:45], s[8:9]
	v_readlane_b32 s89, v252, 11
	s_mov_b32 s81, 0x10000
	s_mov_b32 s88, 0x8000
	v_readlane_b32 s77, v252, 31
	v_cvt_pk_bf16_f32 v12, v16, v17
	v_cvt_pk_bf16_f32 v13, v18, v19
	v_cvt_pk_bf16_f32 v15, v10, v11
	flat_store_dwordx4 v[8:9], v[12:15]
	v_cvt_pk_bf16_f32 v7, v2, v3
	flat_store_dwordx4 v[0:1], v[4:7]
	s_cbranch_vccz .LBB0_192
	s_waitcnt vmcnt(0)
	s_cmpk_gt_u32 s49, 0xff
	s_cbranch_scc1 .LBB0_207
	s_barrier

.LBB0_275:
	s_add_u32 s0, s12, 0x100
	s_addc_u32 s1, s13, 0
	s_add_i32 s2, 0, 0x10000
	v_add_u32_e32 v138, s2, v154
	ds_read_b128 v[156:159], v138
	ds_read_b128 v[160:163], v138 offset:1024
	ds_read_b128 v[164:167], v138 offset:2048
	ds_read_b128 v[168:171], v138 offset:3072
	s_cmp_eq_u32 s65, 40
	s_cselect_b32 s15, s5, s1
	s_cselect_b32 s14, s4, s0
	s_cselect_b32 s11, s9, s64
	s_cselect_b32 s10, s8, s59
	s_add_i32 m0, s40, 0xc000
	ds_read_b128 v[172:175], v155
	ds_read_b128 v[176:179], v155 offset:1024
	ds_read_b128 v[180:183], v155 offset:2048
	ds_read_b128 v[184:187], v155 offset:3072
	ds_read_b128 v[188:191], v155 offset:4096
	ds_read_b128 v[192:195], v155 offset:5120
	ds_read_b128 v[196:199], v155 offset:6144
	ds_read_b128 v[200:203], v155 offset:7168
	global_load_lds_dwordx4 v136, s[12:13]
	s_add_i32 m0, s40, 0xe000
	s_nop 0
	global_load_lds_dwordx4 v134, s[12:13]
	s_waitcnt lgkmcnt(8)
	s_barrier
	s_waitcnt lgkmcnt(0)
	s_setprio 1
	v_mfma_f32_16x16x32_bf16 v[124:127], v[156:159], v[172:175], v[124:127]
	v_mfma_f32_16x16x32_bf16 v[120:123], v[164:167], v[172:175], v[120:123]
	v_mfma_f32_16x16x32_bf16 v[116:119], v[156:159], v[180:183], v[116:119]
	v_mfma_f32_16x16x32_bf16 v[108:111], v[164:167], v[180:183], v[108:111]
	v_mfma_f32_16x16x32_bf16 v[100:103], v[156:159], v[188:191], v[100:103]
	v_mfma_f32_16x16x32_bf16 v[92:95], v[164:167], v[188:191], v[92:95]
	v_mfma_f32_16x16x32_bf16 v[84:87], v[156:159], v[196:199], v[84:87]
	v_mfma_f32_16x16x32_bf16 v[76:79], v[164:167], v[196:199], v[76:79]
	v_mfma_f32_16x16x32_bf16 v[124:127], v[160:163], v[176:179], v[124:127]
	v_mfma_f32_16x16x32_bf16 v[120:123], v[168:171], v[176:179], v[120:123]
	v_mfma_f32_16x16x32_bf16 v[116:119], v[160:163], v[184:187], v[116:119]
	v_mfma_f32_16x16x32_bf16 v[108:111], v[168:171], v[184:187], v[108:111]
	v_mfma_f32_16x16x32_bf16 v[100:103], v[160:163], v[192:195], v[100:103]
	v_mfma_f32_16x16x32_bf16 v[92:95], v[168:171], v[192:195], v[92:95]
	v_mfma_f32_16x16x32_bf16 v[84:87], v[160:163], v[200:203], v[84:87]
	v_mfma_f32_16x16x32_bf16 v[76:79], v[168:171], v[200:203], v[76:79]
	s_setprio 0
	s_barrier
	s_add_i32 s18, 0, 0x14000
	v_add_u32_e32 v138, s18, v154
	s_add_i32 s2, s2, s39
	ds_read_b128 v[204:207], v138
	ds_read_b128 v[208:211], v138 offset:1024
	ds_read_b128 v[228:231], v138 offset:2048
	ds_read_b128 v[232:235], v138 offset:3072
	s_mov_b32 m0, s2
	s_nop 0
	global_load_lds_dwordx4 v140, s[10:11]
	s_add_i32 m0, s2, 0x2000
	s_nop 0
	global_load_lds_dwordx4 v132, s[10:11]
	s_barrier
	s_waitcnt lgkmcnt(0)
	s_setprio 1
	v_mfma_f32_16x16x32_bf16 v[112:115], v[204:207], v[172:175], v[112:115]
	v_mfma_f32_16x16x32_bf16 v[104:107], v[228:231], v[172:175], v[104:107]
	v_mfma_f32_16x16x32_bf16 v[96:99], v[204:207], v[180:183], v[96:99]
	v_mfma_f32_16x16x32_bf16 v[88:91], v[228:231], v[180:183], v[88:91]
	v_mfma_f32_16x16x32_bf16 v[80:83], v[204:207], v[188:191], v[80:83]
	v_mfma_f32_16x16x32_bf16 v[72:75], v[228:231], v[188:191], v[72:75]
	v_mfma_f32_16x16x32_bf16 v[68:71], v[204:207], v[196:199], v[68:71]
	v_mfma_f32_16x16x32_bf16 v[64:67], v[228:231], v[196:199], v[64:67]
	v_mfma_f32_16x16x32_bf16 v[112:115], v[208:211], v[176:179], v[112:115]
	v_mfma_f32_16x16x32_bf16 v[104:107], v[232:235], v[176:179], v[104:107]
	v_mfma_f32_16x16x32_bf16 v[96:99], v[208:211], v[184:187], v[96:99]
	v_mfma_f32_16x16x32_bf16 v[88:91], v[232:235], v[184:187], v[88:91]
	v_mfma_f32_16x16x32_bf16 v[80:83], v[208:211], v[192:195], v[80:83]
	v_mfma_f32_16x16x32_bf16 v[72:75], v[232:235], v[192:195], v[72:75]
	v_mfma_f32_16x16x32_bf16 v[68:71], v[208:211], v[200:203], v[68:71]
	v_mfma_f32_16x16x32_bf16 v[64:67], v[232:235], v[200:203], v[64:67]
	s_setprio 0
	s_mov_b32 m0, s40
	s_barrier
	ds_read_b128 v[172:175], v155 offset:16384
	ds_read_b128 v[176:179], v155 offset:17408
	ds_read_b128 v[180:183], v155 offset:18432
	ds_read_b128 v[184:187], v155 offset:19456
	ds_read_b128 v[188:191], v155 offset:20480
	ds_read_b128 v[192:195], v155 offset:21504
	ds_read_b128 v[196:199], v155 offset:22528
	ds_read_b128 v[200:203], v155 offset:23552
	global_load_lds_dwordx4 v128, s[14:15]
	s_mov_b32 m0, s41
	s_nop 0
	global_load_lds_dwordx4 v130, s[14:15]
	s_barrier
	s_waitcnt lgkmcnt(0)
	s_setprio 1
	v_mfma_f32_16x16x32_bf16 v[60:63], v[156:159], v[172:175], v[60:63]
	v_mfma_f32_16x16x32_bf16 v[56:59], v[164:167], v[172:175], v[56:59]
	v_mfma_f32_16x16x32_bf16 v[52:55], v[156:159], v[180:183], v[52:55]
	v_mfma_f32_16x16x32_bf16 v[44:47], v[164:167], v[180:183], v[44:47]
	v_mfma_f32_16x16x32_bf16 v[36:39], v[156:159], v[188:191], v[36:39]
	v_mfma_f32_16x16x32_bf16 v[28:31], v[164:167], v[188:191], v[28:31]
	v_mfma_f32_16x16x32_bf16 v[20:23], v[156:159], v[196:199], v[20:23]
	v_mfma_f32_16x16x32_bf16 v[12:15], v[164:167], v[196:199], v[12:15]
	v_mfma_f32_16x16x32_bf16 v[60:63], v[160:163], v[176:179], v[60:63]
	v_mfma_f32_16x16x32_bf16 v[56:59], v[168:171], v[176:179], v[56:59]
	v_mfma_f32_16x16x32_bf16 v[52:55], v[160:163], v[184:187], v[52:55]
	v_mfma_f32_16x16x32_bf16 v[44:47], v[168:171], v[184:187], v[44:47]
	v_mfma_f32_16x16x32_bf16 v[36:39], v[160:163], v[192:195], v[36:39]
	v_mfma_f32_16x16x32_bf16 v[28:31], v[168:171], v[192:195], v[28:31]
	v_mfma_f32_16x16x32_bf16 v[20:23], v[160:163], v[200:203], v[20:23]
	v_mfma_f32_16x16x32_bf16 v[12:15], v[168:171], v[200:203], v[12:15]
	s_setprio 0
	s_barrier
	s_add_u32 s12, s10, 0xb0000
	s_addc_u32 s13, s11, 0
	s_add_i32 s2, s18, s39
	s_mov_b32 m0, s2
	s_nop 0
	global_load_lds_dwordx4 v140, s[12:13]
	s_add_i32 m0, s2, 0x2000
	s_nop 0
	global_load_lds_dwordx4 v132, s[12:13]
	s_waitcnt vmcnt(6)
	s_barrier
	s_setprio 1
	v_mfma_f32_16x16x32_bf16 v[48:51], v[204:207], v[172:175], v[48:51]
	v_mfma_f32_16x16x32_bf16 v[40:43], v[228:231], v[172:175], v[40:43]
	v_mfma_f32_16x16x32_bf16 v[32:35], v[204:207], v[180:183], v[32:35]
	v_mfma_f32_16x16x32_bf16 v[24:27], v[228:231], v[180:183], v[24:27]
	v_mfma_f32_16x16x32_bf16 v[16:19], v[204:207], v[188:191], v[16:19]
	v_mfma_f32_16x16x32_bf16 v[8:11], v[228:231], v[188:191], v[8:11]
	v_mfma_f32_16x16x32_bf16 v[4:7], v[204:207], v[196:199], v[4:7]
	v_mfma_f32_16x16x32_bf16 v[0:3], v[228:231], v[196:199], v[0:3]
	v_mfma_f32_16x16x32_bf16 v[48:51], v[208:211], v[176:179], v[48:51]
	v_mfma_f32_16x16x32_bf16 v[40:43], v[232:235], v[176:179], v[40:43]
	v_mfma_f32_16x16x32_bf16 v[32:35], v[208:211], v[184:187], v[32:35]
	v_mfma_f32_16x16x32_bf16 v[24:27], v[232:235], v[184:187], v[24:27]
	v_mfma_f32_16x16x32_bf16 v[16:19], v[208:211], v[192:195], v[16:19]
	v_mfma_f32_16x16x32_bf16 v[8:11], v[232:235], v[192:195], v[8:11]
	v_mfma_f32_16x16x32_bf16 v[4:7], v[208:211], v[200:203], v[4:7]
	v_mfma_f32_16x16x32_bf16 v[0:3], v[232:235], v[200:203], v[0:3]
	s_setprio 0
	s_add_i32 s2, 0, 0x18000
	v_add_u32_e32 v168, s2, v154
	s_barrier
	ds_read_b128 v[156:159], v168
	ds_read_b128 v[160:163], v168 offset:1024
	ds_read_b128 v[164:167], v168 offset:2048
	ds_read_b128 v[168:171], v168 offset:3072
	s_add_u32 s12, s14, 0xb0000
	s_addc_u32 s13, s15, 0
	s_mov_b32 m0, s44
	ds_read_b128 v[172:175], v155 offset:32768
	ds_read_b128 v[176:179], v155 offset:33792
	ds_read_b128 v[180:183], v155 offset:34816
	ds_read_b128 v[184:187], v155 offset:35840
	ds_read_b128 v[188:191], v155 offset:36864
	ds_read_b128 v[192:195], v155 offset:37888
	ds_read_b128 v[196:199], v155 offset:38912
	ds_read_b128 v[200:203], v155 offset:39936
	global_load_lds_dwordx4 v128, s[12:13]
	s_mov_b32 m0, s45
	s_nop 0
	global_load_lds_dwordx4 v130, s[12:13]
	s_waitcnt lgkmcnt(8)
	s_barrier
	s_waitcnt lgkmcnt(0)
	s_setprio 1
	v_mfma_f32_16x16x32_bf16 v[124:127], v[156:159], v[172:175], v[124:127]
	v_mfma_f32_16x16x32_bf16 v[120:123], v[164:167], v[172:175], v[120:123]
	v_mfma_f32_16x16x32_bf16 v[116:119], v[156:159], v[180:183], v[116:119]
	v_mfma_f32_16x16x32_bf16 v[108:111], v[164:167], v[180:183], v[108:111]
	v_mfma_f32_16x16x32_bf16 v[100:103], v[156:159], v[188:191], v[100:103]
	v_mfma_f32_16x16x32_bf16 v[92:95], v[164:167], v[188:191], v[92:95]
	v_mfma_f32_16x16x32_bf16 v[84:87], v[156:159], v[196:199], v[84:87]
	v_mfma_f32_16x16x32_bf16 v[76:79], v[164:167], v[196:199], v[76:79]
	v_mfma_f32_16x16x32_bf16 v[124:127], v[160:163], v[176:179], v[124:127]
	v_mfma_f32_16x16x32_bf16 v[120:123], v[168:171], v[176:179], v[120:123]
	v_mfma_f32_16x16x32_bf16 v[116:119], v[160:163], v[184:187], v[116:119]
	v_mfma_f32_16x16x32_bf16 v[108:111], v[168:171], v[184:187], v[108:111]
	v_mfma_f32_16x16x32_bf16 v[100:103], v[160:163], v[192:195], v[100:103]
	v_mfma_f32_16x16x32_bf16 v[92:95], v[168:171], v[192:195], v[92:95]
	v_mfma_f32_16x16x32_bf16 v[84:87], v[160:163], v[200:203], v[84:87]
	v_mfma_f32_16x16x32_bf16 v[76:79], v[168:171], v[200:203], v[76:79]
	s_setprio 0
	s_barrier
	s_add_i32 s12, 0, 0x1c000
	s_add_i32 s2, s2, s39
	v_add_u32_e32 v232, s12, v154
	s_mov_b32 m0, s2
	ds_read_b128 v[204:207], v232
	ds_read_b128 v[208:211], v232 offset:1024
	ds_read_b128 v[228:231], v232 offset:2048
	ds_read_b128 v[232:235], v232 offset:3072
	s_add_u32 s100, s10, 0x80
	s_addc_u32 s101, s11, 0
	global_load_lds_dwordx4 v140, s[100:101]
	s_add_i32 m0, s2, 0x2000
	s_nop 0
	global_load_lds_dwordx4 v132, s[100:101]
	s_barrier
	s_waitcnt lgkmcnt(0)
	s_setprio 1
	v_mfma_f32_16x16x32_bf16 v[112:115], v[204:207], v[172:175], v[112:115]
	v_mfma_f32_16x16x32_bf16 v[104:107], v[228:231], v[172:175], v[104:107]
	v_mfma_f32_16x16x32_bf16 v[96:99], v[204:207], v[180:183], v[96:99]
	v_mfma_f32_16x16x32_bf16 v[88:91], v[228:231], v[180:183], v[88:91]
	v_mfma_f32_16x16x32_bf16 v[80:83], v[204:207], v[188:191], v[80:83]
	v_mfma_f32_16x16x32_bf16 v[72:75], v[228:231], v[188:191], v[72:75]
	v_mfma_f32_16x16x32_bf16 v[68:71], v[204:207], v[196:199], v[68:71]
	v_mfma_f32_16x16x32_bf16 v[64:67], v[228:231], v[196:199], v[64:67]
	v_mfma_f32_16x16x32_bf16 v[112:115], v[208:211], v[176:179], v[112:115]
	v_mfma_f32_16x16x32_bf16 v[104:107], v[232:235], v[176:179], v[104:107]
	v_mfma_f32_16x16x32_bf16 v[96:99], v[208:211], v[184:187], v[96:99]
	v_mfma_f32_16x16x32_bf16 v[88:91], v[232:235], v[184:187], v[88:91]
	v_mfma_f32_16x16x32_bf16 v[80:83], v[208:211], v[192:195], v[80:83]
	v_mfma_f32_16x16x32_bf16 v[72:75], v[232:235], v[192:195], v[72:75]
	v_mfma_f32_16x16x32_bf16 v[68:71], v[208:211], v[200:203], v[68:71]
	v_mfma_f32_16x16x32_bf16 v[64:67], v[232:235], v[200:203], v[64:67]
	s_setprio 0
	s_mov_b32 m0, s49
	s_barrier
	ds_read_b128 v[172:175], v155 offset:49152
	ds_read_b128 v[176:179], v155 offset:50176
	ds_read_b128 v[180:183], v155 offset:51200
	ds_read_b128 v[184:187], v155 offset:52224
	ds_read_b128 v[188:191], v155 offset:53248
	ds_read_b128 v[192:195], v155 offset:54272
	ds_read_b128 v[196:199], v155 offset:55296
	ds_read_b128 v[200:203], v155 offset:56320
	s_add_u32 s100, s14, 0x80
	s_addc_u32 s101, s15, 0
	global_load_lds_dwordx4 v128, s[100:101]
	s_mov_b32 m0, s20
	s_nop 0
	global_load_lds_dwordx4 v130, s[100:101]
	s_barrier
	s_waitcnt lgkmcnt(0)
	s_setprio 1
	v_mfma_f32_16x16x32_bf16 v[60:63], v[156:159], v[172:175], v[60:63]
	v_mfma_f32_16x16x32_bf16 v[56:59], v[164:167], v[172:175], v[56:59]
	v_mfma_f32_16x16x32_bf16 v[52:55], v[156:159], v[180:183], v[52:55]
	v_mfma_f32_16x16x32_bf16 v[44:47], v[164:167], v[180:183], v[44:47]
	v_mfma_f32_16x16x32_bf16 v[36:39], v[156:159], v[188:191], v[36:39]
	v_mfma_f32_16x16x32_bf16 v[28:31], v[164:167], v[188:191], v[28:31]
	v_mfma_f32_16x16x32_bf16 v[20:23], v[156:159], v[196:199], v[20:23]
	v_mfma_f32_16x16x32_bf16 v[12:15], v[164:167], v[196:199], v[12:15]
	v_mfma_f32_16x16x32_bf16 v[60:63], v[160:163], v[176:179], v[60:63]
	v_mfma_f32_16x16x32_bf16 v[56:59], v[168:171], v[176:179], v[56:59]
	v_mfma_f32_16x16x32_bf16 v[52:55], v[160:163], v[184:187], v[52:55]
	v_mfma_f32_16x16x32_bf16 v[44:47], v[168:171], v[184:187], v[44:47]
	v_mfma_f32_16x16x32_bf16 v[36:39], v[160:163], v[192:195], v[36:39]
	v_mfma_f32_16x16x32_bf16 v[28:31], v[168:171], v[192:195], v[28:31]
	v_mfma_f32_16x16x32_bf16 v[20:23], v[160:163], v[200:203], v[20:23]
	v_mfma_f32_16x16x32_bf16 v[12:15], v[168:171], v[200:203], v[12:15]
	s_setprio 0
	s_barrier
	s_add_u32 s10, s10, 0xb0080
	s_addc_u32 s11, s11, 0
	s_add_i32 s2, s12, s39
	s_mov_b32 m0, s2
	s_nop 0
	global_load_lds_dwordx4 v140, s[10:11]
	s_add_i32 m0, s2, 0x2000
	s_nop 0
	global_load_lds_dwordx4 v132, s[10:11]
	s_waitcnt vmcnt(6)
	s_barrier
	s_setprio 1
	v_mfma_f32_16x16x32_bf16 v[48:51], v[204:207], v[172:175], v[48:51]
	v_mfma_f32_16x16x32_bf16 v[40:43], v[228:231], v[172:175], v[40:43]
	v_mfma_f32_16x16x32_bf16 v[32:35], v[204:207], v[180:183], v[32:35]
	v_mfma_f32_16x16x32_bf16 v[24:27], v[228:231], v[180:183], v[24:27]
	v_mfma_f32_16x16x32_bf16 v[16:19], v[204:207], v[188:191], v[16:19]
	v_mfma_f32_16x16x32_bf16 v[8:11], v[228:231], v[188:191], v[8:11]
	v_mfma_f32_16x16x32_bf16 v[4:7], v[204:207], v[196:199], v[4:7]
	v_mfma_f32_16x16x32_bf16 v[0:3], v[228:231], v[196:199], v[0:3]
	v_mfma_f32_16x16x32_bf16 v[48:51], v[208:211], v[176:179], v[48:51]
	v_mfma_f32_16x16x32_bf16 v[40:43], v[232:235], v[176:179], v[40:43]
	v_mfma_f32_16x16x32_bf16 v[32:35], v[208:211], v[184:187], v[32:35]
	v_mfma_f32_16x16x32_bf16 v[24:27], v[232:235], v[184:187], v[24:27]
	v_mfma_f32_16x16x32_bf16 v[16:19], v[208:211], v[192:195], v[16:19]
	v_mfma_f32_16x16x32_bf16 v[8:11], v[232:235], v[192:195], v[8:11]
	v_mfma_f32_16x16x32_bf16 v[4:7], v[208:211], v[200:203], v[4:7]
	v_mfma_f32_16x16x32_bf16 v[0:3], v[232:235], v[200:203], v[0:3]
	s_setprio 0
	s_add_i32 s65, s65, 2
	s_add_u32 s59, s59, 0x100
	s_addc_u32 s64, s64, 0
	s_cmp_gt_u32 s65, 41
	s_mov_b64 s[12:13], s[0:1]
	s_barrier
	s_cbranch_scc0 .LBB0_275
	s_lshl_b32 s0, s57, 8
	v_mbcnt_lo_u32_b32 v139, -1, 0
	v_mbcnt_hi_u32_b32 v139, -1, v139
	s_lshl_b32 s1, s58, 8
	v_ashrrev_i32_e32 v138, 1, v139
	s_add_i32 s0, s0, s46
	v_and_b32_e32 v138, -8, v138
	s_or_b32 s1, s1, s48
	v_and_or_b32 v156, v139, 15, s0
	v_add_u32_e32 v138, s1, v138
	v_ashrrev_i32_e32 v157, 31, v156
	v_ashrrev_i32_e32 v139, 31, v138
	v_lshlrev_b64 v[158:159], 11, v[156:157]
	v_lshl_add_u64 v[158:159], s[24:25], 0, v[158:159]
	v_lshlrev_b64 v[160:161], 1, v[138:139]
	v_lshl_add_u64 v[138:139], v[158:159], 0, v[160:161]
	v_cvt_pk_bf16_f32 v60, v60, v61
	v_cvt_pk_bf16_f32 v61, v62, v63
	v_cvt_pk_bf16_f32 v62, v56, v57
	v_add_co_u32_e32 v56, vcc, s19, v138
	v_cvt_pk_bf16_f32 v112, v112, v113
	v_cvt_pk_bf16_f32 v113, v114, v115
	v_cvt_pk_bf16_f32 v114, v104, v105
	v_or_b32_e32 v104, 16, v156
	s_nop 0
	v_addc_co_u32_e32 v57, vcc, 0, v139, vcc
	v_cvt_pk_bf16_f32 v48, v48, v49
	v_cvt_pk_bf16_f32 v49, v50, v51
	v_cvt_pk_bf16_f32 v51, v42, v43
	v_cvt_pk_bf16_f32 v42, v44, v45
	v_add_co_u32_e32 v44, vcc, s30, v138
	v_ashrrev_i32_e32 v105, 31, v104
	v_cvt_pk_bf16_f32 v96, v96, v97
	v_cvt_pk_bf16_f32 v97, v98, v99
	v_cvt_pk_bf16_f32 v98, v88, v89
	v_or_b32_e32 v88, 32, v156
	v_addc_co_u32_e32 v45, vcc, 0, v139, vcc
	v_lshlrev_b64 v[104:105], 11, v[104:105]
	v_ashrrev_i32_e32 v89, 31, v88
	v_cvt_pk_bf16_f32 v80, v80, v81
	v_cvt_pk_bf16_f32 v81, v82, v83
	v_cvt_pk_bf16_f32 v82, v72, v73
	v_or_b32_e32 v72, 48, v156
	s_mov_b64 s[0:1], 0x40000
	v_cvt_pk_bf16_f32 v32, v32, v33
	v_cvt_pk_bf16_f32 v33, v34, v35
	v_cvt_pk_bf16_f32 v35, v26, v27
	v_cvt_pk_bf16_f32 v26, v28, v29
	v_add_co_u32_e32 v28, vcc, s31, v138
	v_lshl_add_u64 v[104:105], s[24:25], 0, v[104:105]
	v_lshlrev_b64 v[88:89], 11, v[88:89]
	v_ashrrev_i32_e32 v73, 31, v72
	v_cvt_pk_bf16_f32 v68, v68, v69
	v_cvt_pk_bf16_f32 v69, v70, v71
	v_cvt_pk_bf16_f32 v70, v64, v65
	v_lshl_add_u64 v[64:65], v[138:139], 0, s[0:1]
	s_mov_b64 s[0:1], 0x48000
	v_addc_co_u32_e32 v29, vcc, 0, v139, vcc
	v_cvt_pk_bf16_f32 v115, v106, v107
	flat_store_dwordx4 v[138:139], v[112:115] offset:256
	v_lshl_add_u64 v[88:89], s[24:25], 0, v[88:89]
	v_lshlrev_b64 v[72:73], 11, v[72:73]
	v_lshl_add_u64 v[112:113], v[104:105], 0, v[160:161]
	v_cvt_pk_bf16_f32 v50, v40, v41
	flat_store_dwordx4 v[64:65], v[48:51] offset:256
	v_cvt_pk_bf16_f32 v16, v16, v17
	v_cvt_pk_bf16_f32 v17, v18, v19
	v_cvt_pk_bf16_f32 v19, v10, v11
	v_cvt_pk_bf16_f32 v10, v12, v13
	v_add_co_u32_e32 v12, vcc, s42, v138
	s_nop 0
	v_lshl_add_u64 v[48:49], v[138:139], 0, s[0:1]
	s_mov_b64 s[0:1], 0x50000
	v_cvt_pk_bf16_f32 v99, v90, v91
	flat_store_dwordx4 v[112:113], v[96:99] offset:256
	v_lshl_add_u64 v[72:73], s[24:25], 0, v[72:73]
	v_cvt_pk_bf16_f32 v34, v24, v25
	flat_store_dwordx4 v[48:49], v[32:35] offset:256
	v_lshl_add_u64 v[96:97], v[88:89], 0, v[160:161]
	v_addc_co_u32_e32 v13, vcc, 0, v139, vcc
	v_lshl_add_u64 v[32:33], v[138:139], 0, s[0:1]
	s_mov_b64 s[0:1], 0x58000
	v_cvt_pk_bf16_f32 v83, v74, v75
	flat_store_dwordx4 v[96:97], v[80:83] offset:256
	v_cvt_pk_bf16_f32 v18, v8, v9
	flat_store_dwordx4 v[32:33], v[16:19] offset:256
	s_and_b64 vcc, exec, s[6:7]
	v_lshl_add_u64 v[80:81], v[72:73], 0, v[160:161]
	v_lshl_add_u64 v[16:17], v[138:139], 0, s[0:1]
	s_mov_b32 s58, s52
	s_mov_b32 s57, s51
	s_mov_b64 s[0:1], s[8:9]
	s_mov_b64 s[12:13], s[4:5]
	v_cvt_pk_bf16_f32 v124, v124, v125
	v_cvt_pk_bf16_f32 v125, v126, v127
	v_cvt_pk_bf16_f32 v126, v120, v121
	v_cvt_pk_bf16_f32 v127, v122, v123
	flat_store_dwordx4 v[138:139], v[124:127]
	v_cvt_pk_bf16_f32 v104, v116, v117
	v_cvt_pk_bf16_f32 v105, v118, v119
	v_cvt_pk_bf16_f32 v106, v108, v109
	v_cvt_pk_bf16_f32 v107, v110, v111
	flat_store_dwordx4 v[112:113], v[104:107]
	v_cvt_pk_bf16_f32 v88, v100, v101
	v_cvt_pk_bf16_f32 v89, v102, v103
	v_cvt_pk_bf16_f32 v90, v92, v93
	v_cvt_pk_bf16_f32 v91, v94, v95
	flat_store_dwordx4 v[96:97], v[88:91]
	v_cvt_pk_bf16_f32 v72, v84, v85
	v_cvt_pk_bf16_f32 v73, v86, v87
	v_cvt_pk_bf16_f32 v74, v76, v77
	v_cvt_pk_bf16_f32 v75, v78, v79
	flat_store_dwordx4 v[80:81], v[72:75]
	v_cvt_pk_bf16_f32 v71, v66, v67
	flat_store_dwordx4 v[80:81], v[68:71] offset:256
	v_cvt_pk_bf16_f32 v63, v58, v59
	flat_store_dwordx4 v[56:57], v[60:63]
	v_cvt_pk_bf16_f32 v40, v52, v53
	v_cvt_pk_bf16_f32 v41, v54, v55
	v_cvt_pk_bf16_f32 v43, v46, v47
	flat_store_dwordx4 v[44:45], v[40:43]
	v_cvt_pk_bf16_f32 v24, v36, v37
	v_cvt_pk_bf16_f32 v25, v38, v39
	v_cvt_pk_bf16_f32 v27, v30, v31
	flat_store_dwordx4 v[28:29], v[24:27]
	v_cvt_pk_bf16_f32 v8, v20, v21
	v_cvt_pk_bf16_f32 v9, v22, v23
	v_cvt_pk_bf16_f32 v11, v14, v15
	flat_store_dwordx4 v[12:13], v[8:11]
	v_cvt_pk_bf16_f32 v4, v4, v5
	v_cvt_pk_bf16_f32 v5, v6, v7
	v_cvt_pk_bf16_f32 v6, v0, v1
	v_cvt_pk_bf16_f32 v7, v2, v3
	flat_store_dwordx4 v[16:17], v[4:7] offset:256
	s_cbranch_vccz .LBB0_264
	s_waitcnt vmcnt(0)
	s_cmpk_gt_u32 s17, 0xff
	s_cbranch_scc1 .LBB0_279
	s_barrier

.LBB0_289:
	s_add_u32 s0, s16, 0xfffc0080
	s_addc_u32 s1, s17, -1
	s_add_i32 s2, 0, 0x10000
	v_add_u32_e32 v138, s2, v154
	ds_read_b128 v[156:159], v138
	ds_read_b128 v[160:163], v138 offset:1024
	ds_read_b128 v[164:167], v138 offset:2048
	ds_read_b128 v[168:171], v138 offset:3072
	s_cmp_eq_u32 s21, 12
	s_cselect_b32 s37, s11, s1
	s_cselect_b32 s36, s10, s0
	s_cselect_b32 s1, s13, s9
	s_cselect_b32 s0, s12, s5
	s_add_i32 m0, s15, 0xc000
	ds_read_b128 v[172:175], v155
	ds_read_b128 v[176:179], v155 offset:1024
	ds_read_b128 v[180:183], v155 offset:2048
	ds_read_b128 v[184:187], v155 offset:3072
	ds_read_b128 v[188:191], v155 offset:4096
	ds_read_b128 v[192:195], v155 offset:5120
	ds_read_b128 v[196:199], v155 offset:6144
	ds_read_b128 v[200:203], v155 offset:7168
	global_load_lds_dwordx4 v136, s[16:17]
	s_add_i32 m0, s15, 0xe000
	s_nop 0
	global_load_lds_dwordx4 v134, s[16:17]
	s_waitcnt lgkmcnt(8)
	s_barrier
	s_waitcnt lgkmcnt(0)
	s_setprio 1
	v_mfma_f32_16x16x32_bf16 v[124:127], v[156:159], v[172:175], v[124:127]
	v_mfma_f32_16x16x32_bf16 v[120:123], v[164:167], v[172:175], v[120:123]
	v_mfma_f32_16x16x32_bf16 v[108:111], v[156:159], v[180:183], v[108:111]
	v_mfma_f32_16x16x32_bf16 v[104:107], v[164:167], v[180:183], v[104:107]
	v_mfma_f32_16x16x32_bf16 v[92:95], v[156:159], v[188:191], v[92:95]
	v_mfma_f32_16x16x32_bf16 v[88:91], v[164:167], v[188:191], v[88:91]
	v_mfma_f32_16x16x32_bf16 v[76:79], v[156:159], v[196:199], v[76:79]
	v_mfma_f32_16x16x32_bf16 v[72:75], v[164:167], v[196:199], v[72:75]
	v_mfma_f32_16x16x32_bf16 v[124:127], v[160:163], v[176:179], v[124:127]
	v_mfma_f32_16x16x32_bf16 v[120:123], v[168:171], v[176:179], v[120:123]
	v_mfma_f32_16x16x32_bf16 v[108:111], v[160:163], v[184:187], v[108:111]
	v_mfma_f32_16x16x32_bf16 v[104:107], v[168:171], v[184:187], v[104:107]
	v_mfma_f32_16x16x32_bf16 v[92:95], v[160:163], v[192:195], v[92:95]
	v_mfma_f32_16x16x32_bf16 v[88:91], v[168:171], v[192:195], v[88:91]
	v_mfma_f32_16x16x32_bf16 v[76:79], v[160:163], v[200:203], v[76:79]
	v_mfma_f32_16x16x32_bf16 v[72:75], v[168:171], v[200:203], v[72:75]
	s_setprio 0
	s_barrier
	s_add_i32 s30, 0, 0x14000
	v_add_u32_e32 v138, s30, v154
	s_add_i32 s2, s2, s44
	ds_read_b128 v[204:207], v138
	ds_read_b128 v[208:211], v138 offset:1024
	ds_read_b128 v[228:231], v138 offset:2048
	ds_read_b128 v[232:235], v138 offset:3072
	s_mov_b32 m0, s2
	s_nop 0
	global_load_lds_dwordx4 v140, s[0:1]
	s_add_i32 m0, s2, 0x2000
	s_nop 0
	global_load_lds_dwordx4 v128, s[0:1]
	s_barrier
	s_waitcnt lgkmcnt(0)
	s_setprio 1
	v_mfma_f32_16x16x32_bf16 v[116:119], v[204:207], v[172:175], v[116:119]
	v_mfma_f32_16x16x32_bf16 v[112:115], v[228:231], v[172:175], v[112:115]
	v_mfma_f32_16x16x32_bf16 v[100:103], v[204:207], v[180:183], v[100:103]
	v_mfma_f32_16x16x32_bf16 v[96:99], v[228:231], v[180:183], v[96:99]
	v_mfma_f32_16x16x32_bf16 v[84:87], v[204:207], v[188:191], v[84:87]
	v_mfma_f32_16x16x32_bf16 v[80:83], v[228:231], v[188:191], v[80:83]
	v_mfma_f32_16x16x32_bf16 v[68:71], v[204:207], v[196:199], v[68:71]
	v_mfma_f32_16x16x32_bf16 v[64:67], v[228:231], v[196:199], v[64:67]
	v_mfma_f32_16x16x32_bf16 v[116:119], v[208:211], v[176:179], v[116:119]
	v_mfma_f32_16x16x32_bf16 v[112:115], v[232:235], v[176:179], v[112:115]
	v_mfma_f32_16x16x32_bf16 v[100:103], v[208:211], v[184:187], v[100:103]
	v_mfma_f32_16x16x32_bf16 v[96:99], v[232:235], v[184:187], v[96:99]
	v_mfma_f32_16x16x32_bf16 v[84:87], v[208:211], v[192:195], v[84:87]
	v_mfma_f32_16x16x32_bf16 v[80:83], v[232:235], v[192:195], v[80:83]
	v_mfma_f32_16x16x32_bf16 v[68:71], v[208:211], v[200:203], v[68:71]
	v_mfma_f32_16x16x32_bf16 v[64:67], v[232:235], v[200:203], v[64:67]
	s_setprio 0
	s_mov_b32 m0, s15
	s_barrier
	ds_read_b128 v[172:175], v155 offset:16384
	ds_read_b128 v[176:179], v155 offset:17408
	ds_read_b128 v[180:183], v155 offset:18432
	ds_read_b128 v[184:187], v155 offset:19456
	ds_read_b128 v[188:191], v155 offset:20480
	ds_read_b128 v[192:195], v155 offset:21504
	ds_read_b128 v[196:199], v155 offset:22528
	ds_read_b128 v[200:203], v155 offset:23552
	global_load_lds_dwordx4 v132, s[36:37]
	s_mov_b32 m0, s45
	s_nop 0
	global_load_lds_dwordx4 v130, s[36:37]
	s_barrier
	s_waitcnt lgkmcnt(0)
	s_setprio 1
	v_mfma_f32_16x16x32_bf16 v[60:63], v[156:159], v[172:175], v[60:63]
	v_mfma_f32_16x16x32_bf16 v[56:59], v[164:167], v[172:175], v[56:59]
	v_mfma_f32_16x16x32_bf16 v[44:47], v[156:159], v[180:183], v[44:47]
	v_mfma_f32_16x16x32_bf16 v[40:43], v[164:167], v[180:183], v[40:43]
	v_mfma_f32_16x16x32_bf16 v[28:31], v[156:159], v[188:191], v[28:31]
	v_mfma_f32_16x16x32_bf16 v[24:27], v[164:167], v[188:191], v[24:27]
	v_mfma_f32_16x16x32_bf16 v[12:15], v[156:159], v[196:199], v[12:15]
	v_mfma_f32_16x16x32_bf16 v[8:11], v[164:167], v[196:199], v[8:11]
	v_mfma_f32_16x16x32_bf16 v[60:63], v[160:163], v[176:179], v[60:63]
	v_mfma_f32_16x16x32_bf16 v[56:59], v[168:171], v[176:179], v[56:59]
	v_mfma_f32_16x16x32_bf16 v[44:47], v[160:163], v[184:187], v[44:47]
	v_mfma_f32_16x16x32_bf16 v[40:43], v[168:171], v[184:187], v[40:43]
	v_mfma_f32_16x16x32_bf16 v[28:31], v[160:163], v[192:195], v[28:31]
	v_mfma_f32_16x16x32_bf16 v[24:27], v[168:171], v[192:195], v[24:27]
	v_mfma_f32_16x16x32_bf16 v[12:15], v[160:163], v[200:203], v[12:15]
	v_mfma_f32_16x16x32_bf16 v[8:11], v[168:171], v[200:203], v[8:11]
	s_setprio 0
	s_barrier
	s_add_u32 s18, s0, 0x40000
	s_addc_u32 s19, s1, 0
	s_add_i32 s2, s30, s44
	s_mov_b32 m0, s2
	s_nop 0
	global_load_lds_dwordx4 v140, s[18:19]
	s_add_i32 m0, s2, 0x2000
	s_nop 0
	global_load_lds_dwordx4 v128, s[18:19]
	s_waitcnt vmcnt(6)
	s_barrier
	s_setprio 1
	v_mfma_f32_16x16x32_bf16 v[52:55], v[204:207], v[172:175], v[52:55]
	v_mfma_f32_16x16x32_bf16 v[48:51], v[228:231], v[172:175], v[48:51]
	v_mfma_f32_16x16x32_bf16 v[36:39], v[204:207], v[180:183], v[36:39]
	v_mfma_f32_16x16x32_bf16 v[32:35], v[228:231], v[180:183], v[32:35]
	v_mfma_f32_16x16x32_bf16 v[20:23], v[204:207], v[188:191], v[20:23]
	v_mfma_f32_16x16x32_bf16 v[16:19], v[228:231], v[188:191], v[16:19]
	v_mfma_f32_16x16x32_bf16 v[4:7], v[204:207], v[196:199], v[4:7]
	v_mfma_f32_16x16x32_bf16 v[0:3], v[228:231], v[196:199], v[0:3]
	v_mfma_f32_16x16x32_bf16 v[52:55], v[208:211], v[176:179], v[52:55]
	v_mfma_f32_16x16x32_bf16 v[48:51], v[232:235], v[176:179], v[48:51]
	v_mfma_f32_16x16x32_bf16 v[36:39], v[208:211], v[184:187], v[36:39]
	v_mfma_f32_16x16x32_bf16 v[32:35], v[232:235], v[184:187], v[32:35]
	v_mfma_f32_16x16x32_bf16 v[20:23], v[208:211], v[192:195], v[20:23]
	v_mfma_f32_16x16x32_bf16 v[16:19], v[232:235], v[192:195], v[16:19]
	v_mfma_f32_16x16x32_bf16 v[4:7], v[208:211], v[200:203], v[4:7]
	v_mfma_f32_16x16x32_bf16 v[0:3], v[232:235], v[200:203], v[0:3]
	s_setprio 0
	s_add_i32 s2, 0, 0x18000
	v_add_u32_e32 v168, s2, v154
	s_barrier
	ds_read_b128 v[156:159], v168
	ds_read_b128 v[160:163], v168 offset:1024
	ds_read_b128 v[164:167], v168 offset:2048
	ds_read_b128 v[168:171], v168 offset:3072
	s_add_u32 s18, s36, 0x40000
	s_addc_u32 s19, s37, 0
	s_mov_b32 m0, s46
	ds_read_b128 v[172:175], v155 offset:32768
	ds_read_b128 v[176:179], v155 offset:33792
	ds_read_b128 v[180:183], v155 offset:34816
	ds_read_b128 v[184:187], v155 offset:35840
	ds_read_b128 v[188:191], v155 offset:36864
	ds_read_b128 v[192:195], v155 offset:37888
	ds_read_b128 v[196:199], v155 offset:38912
	ds_read_b128 v[200:203], v155 offset:39936
	global_load_lds_dwordx4 v132, s[18:19]
	s_mov_b32 m0, s48
	s_nop 0
	global_load_lds_dwordx4 v130, s[18:19]
	s_waitcnt lgkmcnt(8)
	s_barrier
	s_waitcnt lgkmcnt(0)
	s_setprio 1
	v_mfma_f32_16x16x32_bf16 v[124:127], v[156:159], v[172:175], v[124:127]
	v_mfma_f32_16x16x32_bf16 v[120:123], v[164:167], v[172:175], v[120:123]
	v_mfma_f32_16x16x32_bf16 v[108:111], v[156:159], v[180:183], v[108:111]
	v_mfma_f32_16x16x32_bf16 v[104:107], v[164:167], v[180:183], v[104:107]
	v_mfma_f32_16x16x32_bf16 v[92:95], v[156:159], v[188:191], v[92:95]
	v_mfma_f32_16x16x32_bf16 v[88:91], v[164:167], v[188:191], v[88:91]
	v_mfma_f32_16x16x32_bf16 v[76:79], v[156:159], v[196:199], v[76:79]
	v_mfma_f32_16x16x32_bf16 v[72:75], v[164:167], v[196:199], v[72:75]
	v_mfma_f32_16x16x32_bf16 v[124:127], v[160:163], v[176:179], v[124:127]
	v_mfma_f32_16x16x32_bf16 v[120:123], v[168:171], v[176:179], v[120:123]
	v_mfma_f32_16x16x32_bf16 v[108:111], v[160:163], v[184:187], v[108:111]
	v_mfma_f32_16x16x32_bf16 v[104:107], v[168:171], v[184:187], v[104:107]
	v_mfma_f32_16x16x32_bf16 v[92:95], v[160:163], v[192:195], v[92:95]
	v_mfma_f32_16x16x32_bf16 v[88:91], v[168:171], v[192:195], v[88:91]
	v_mfma_f32_16x16x32_bf16 v[76:79], v[160:163], v[200:203], v[76:79]
	v_mfma_f32_16x16x32_bf16 v[72:75], v[168:171], v[200:203], v[72:75]
	s_setprio 0
	s_barrier
	s_add_i32 s18, 0, 0x1c000
	s_add_i32 s2, s2, s44
	v_add_u32_e32 v232, s18, v154
	s_mov_b32 m0, s2
	ds_read_b128 v[204:207], v232
	ds_read_b128 v[208:211], v232 offset:1024
	ds_read_b128 v[228:231], v232 offset:2048
	ds_read_b128 v[232:235], v232 offset:3072
	s_add_u32 s100, s0, 0x80
	s_addc_u32 s101, s1, 0
	global_load_lds_dwordx4 v140, s[100:101]
	s_add_i32 m0, s2, 0x2000
	s_nop 0
	global_load_lds_dwordx4 v128, s[100:101]
	s_barrier
	s_waitcnt lgkmcnt(0)
	s_setprio 1
	v_mfma_f32_16x16x32_bf16 v[116:119], v[204:207], v[172:175], v[116:119]
	v_mfma_f32_16x16x32_bf16 v[112:115], v[228:231], v[172:175], v[112:115]
	v_mfma_f32_16x16x32_bf16 v[100:103], v[204:207], v[180:183], v[100:103]
	v_mfma_f32_16x16x32_bf16 v[96:99], v[228:231], v[180:183], v[96:99]
	v_mfma_f32_16x16x32_bf16 v[84:87], v[204:207], v[188:191], v[84:87]
	v_mfma_f32_16x16x32_bf16 v[80:83], v[228:231], v[188:191], v[80:83]
	v_mfma_f32_16x16x32_bf16 v[68:71], v[204:207], v[196:199], v[68:71]
	v_mfma_f32_16x16x32_bf16 v[64:67], v[228:231], v[196:199], v[64:67]
	v_mfma_f32_16x16x32_bf16 v[116:119], v[208:211], v[176:179], v[116:119]
	v_mfma_f32_16x16x32_bf16 v[112:115], v[232:235], v[176:179], v[112:115]
	v_mfma_f32_16x16x32_bf16 v[100:103], v[208:211], v[184:187], v[100:103]
	v_mfma_f32_16x16x32_bf16 v[96:99], v[232:235], v[184:187], v[96:99]
	v_mfma_f32_16x16x32_bf16 v[84:87], v[208:211], v[192:195], v[84:87]
	v_mfma_f32_16x16x32_bf16 v[80:83], v[232:235], v[192:195], v[80:83]
	v_mfma_f32_16x16x32_bf16 v[68:71], v[208:211], v[200:203], v[68:71]
	v_mfma_f32_16x16x32_bf16 v[64:67], v[232:235], v[200:203], v[64:67]
	s_setprio 0
	s_mov_b32 m0, s57
	s_barrier
	ds_read_b128 v[172:175], v155 offset:49152
	ds_read_b128 v[176:179], v155 offset:50176
	ds_read_b128 v[180:183], v155 offset:51200
	ds_read_b128 v[184:187], v155 offset:52224
	ds_read_b128 v[188:191], v155 offset:53248
	ds_read_b128 v[192:195], v155 offset:54272
	ds_read_b128 v[196:199], v155 offset:55296
	ds_read_b128 v[200:203], v155 offset:56320
	s_add_u32 s100, s36, 0x80
	s_addc_u32 s101, s37, 0
	global_load_lds_dwordx4 v132, s[100:101]
	s_mov_b32 m0, s58
	s_nop 0
	global_load_lds_dwordx4 v130, s[100:101]
	s_barrier
	s_waitcnt lgkmcnt(0)
	s_setprio 1
	v_mfma_f32_16x16x32_bf16 v[60:63], v[156:159], v[172:175], v[60:63]
	v_mfma_f32_16x16x32_bf16 v[56:59], v[164:167], v[172:175], v[56:59]
	v_mfma_f32_16x16x32_bf16 v[44:47], v[156:159], v[180:183], v[44:47]
	v_mfma_f32_16x16x32_bf16 v[40:43], v[164:167], v[180:183], v[40:43]
	v_mfma_f32_16x16x32_bf16 v[28:31], v[156:159], v[188:191], v[28:31]
	v_mfma_f32_16x16x32_bf16 v[24:27], v[164:167], v[188:191], v[24:27]
	v_mfma_f32_16x16x32_bf16 v[12:15], v[156:159], v[196:199], v[12:15]
	v_mfma_f32_16x16x32_bf16 v[8:11], v[164:167], v[196:199], v[8:11]
	v_mfma_f32_16x16x32_bf16 v[60:63], v[160:163], v[176:179], v[60:63]
	v_mfma_f32_16x16x32_bf16 v[56:59], v[168:171], v[176:179], v[56:59]
	v_mfma_f32_16x16x32_bf16 v[44:47], v[160:163], v[184:187], v[44:47]
	v_mfma_f32_16x16x32_bf16 v[40:43], v[168:171], v[184:187], v[40:43]
	v_mfma_f32_16x16x32_bf16 v[28:31], v[160:163], v[192:195], v[28:31]
	v_mfma_f32_16x16x32_bf16 v[24:27], v[168:171], v[192:195], v[24:27]
	v_mfma_f32_16x16x32_bf16 v[12:15], v[160:163], v[200:203], v[12:15]
	v_mfma_f32_16x16x32_bf16 v[8:11], v[168:171], v[200:203], v[8:11]
	s_setprio 0
	s_barrier
	s_add_u32 s0, s0, 0x40080
	s_addc_u32 s1, s1, 0
	s_add_i32 s2, s18, s44
	s_mov_b32 m0, s2
	s_nop 0
	global_load_lds_dwordx4 v140, s[0:1]
	s_add_i32 m0, s2, 0x2000
	s_nop 0
	global_load_lds_dwordx4 v128, s[0:1]
	s_waitcnt vmcnt(6)
	s_barrier
	s_setprio 1
	v_mfma_f32_16x16x32_bf16 v[52:55], v[204:207], v[172:175], v[52:55]
	v_mfma_f32_16x16x32_bf16 v[48:51], v[228:231], v[172:175], v[48:51]
	v_mfma_f32_16x16x32_bf16 v[36:39], v[204:207], v[180:183], v[36:39]
	v_mfma_f32_16x16x32_bf16 v[32:35], v[228:231], v[180:183], v[32:35]
	v_mfma_f32_16x16x32_bf16 v[20:23], v[204:207], v[188:191], v[20:23]
	v_mfma_f32_16x16x32_bf16 v[16:19], v[228:231], v[188:191], v[16:19]
	v_mfma_f32_16x16x32_bf16 v[4:7], v[204:207], v[196:199], v[4:7]
	v_mfma_f32_16x16x32_bf16 v[0:3], v[228:231], v[196:199], v[0:3]
	v_mfma_f32_16x16x32_bf16 v[52:55], v[208:211], v[176:179], v[52:55]
	v_mfma_f32_16x16x32_bf16 v[48:51], v[232:235], v[176:179], v[48:51]
	v_mfma_f32_16x16x32_bf16 v[36:39], v[208:211], v[184:187], v[36:39]
	v_mfma_f32_16x16x32_bf16 v[32:35], v[232:235], v[184:187], v[32:35]
	v_mfma_f32_16x16x32_bf16 v[20:23], v[208:211], v[192:195], v[20:23]
	v_mfma_f32_16x16x32_bf16 v[16:19], v[232:235], v[192:195], v[16:19]
	v_mfma_f32_16x16x32_bf16 v[4:7], v[208:211], v[200:203], v[4:7]
	v_mfma_f32_16x16x32_bf16 v[0:3], v[232:235], v[200:203], v[0:3]
	s_setprio 0
	s_add_i32 s21, s21, 2
	s_add_u32 s5, s5, 0x100
	s_addc_u32 s9, s9, 0
	s_add_u32 s16, s16, 0x100
	s_addc_u32 s17, s17, 0
	s_cmp_gt_u32 s21, 13
	s_barrier
	s_cbranch_scc0 .LBB0_289
	v_mul_f32_e32 v161, 0xbfb8aa3b, v124
	v_exp_f32_e32 v161, v161
	v_mul_f32_e32 v162, 0xbfb8aa3b, v125
	v_exp_f32_e32 v162, v162
	v_mul_f32_e32 v163, 0xbfb8aa3b, v126
	v_exp_f32_e32 v163, v163
	v_mul_f32_e32 v164, 0xbfb8aa3b, v127
	v_exp_f32_e32 v164, v164
	v_mul_f32_e32 v165, 0xbfb8aa3b, v120
	v_exp_f32_e32 v165, v165
	v_mul_f32_e32 v166, 0xbfb8aa3b, v121
	v_add_f32_e32 v161, 1.0, v161
	v_exp_f32_e32 v166, v166
	v_mul_f32_e32 v167, 0xbfb8aa3b, v122
	v_rcp_f32_e32 v161, v161
	v_add_f32_e32 v162, 1.0, v162
	v_exp_f32_e32 v167, v167
	v_mul_f32_e32 v168, 0xbfb8aa3b, v123
	v_rcp_f32_e32 v162, v162
	v_add_f32_e32 v163, 1.0, v163
	v_exp_f32_e32 v168, v168
	v_rcp_f32_e32 v163, v163
	v_add_f32_e32 v164, 1.0, v164
	v_rcp_f32_e32 v164, v164
	v_add_f32_e32 v165, 1.0, v165
	v_rcp_f32_e32 v165, v165
	v_add_f32_e32 v166, 1.0, v166
	v_mul_f32_e32 v124, v124, v161
	v_rcp_f32_e32 v166, v166
	v_add_f32_e32 v167, 1.0, v167
	v_mul_f32_e32 v116, v124, v116
	v_mul_f32_e32 v124, v125, v162
	s_lshl_b32 s0, s14, 8
	v_rcp_f32_e32 v167, v167
	v_add_f32_e32 v168, 1.0, v168
	v_mul_f32_e32 v117, v124, v117
	v_mul_f32_e32 v124, v126, v163
	v_mbcnt_lo_u32_b32 v138, -1, 0
	v_mbcnt_hi_u32_b32 v138, -1, v138
	s_add_i32 s0, s0, s51
	v_rcp_f32_e32 v168, v168
	v_mul_f32_e32 v124, v124, v118
	v_mul_f32_e32 v118, v127, v164
	v_and_or_b32 v160, v138, 15, s0
	s_lshl_b32 s0, s20, 7
	v_ashrrev_i32_e32 v138, 1, v138
	v_mul_f32_e32 v125, v118, v119
	v_mul_f32_e32 v118, v120, v165
	s_or_b32 s0, s0, s52
	v_and_b32_e32 v138, -8, v138
	v_mul_f32_e32 v120, v118, v112
	v_mul_f32_e32 v112, v121, v166
	v_add_u32_e32 v156, s0, v138
	v_mul_f32_e32 v121, v112, v113
	v_mul_f32_e32 v112, v122, v167
	v_ashrrev_i32_e32 v157, 31, v156
	v_mov_b64_e32 v[138:139], s[34:35]
	v_mul_f32_e32 v122, v112, v114
	v_mul_f32_e32 v112, v123, v168
	v_mad_i64_i32 v[158:159], s[0:1], v160, s33, v[138:139]
	v_mul_f32_e32 v123, v112, v115
	v_lshlrev_b64 v[112:113], 1, v[156:157]
	v_lshl_add_u64 v[118:119], v[158:159], 0, v[112:113]
	v_cvt_pk_bf16_f32 v114, v116, v117
	v_cvt_pk_bf16_f32 v116, v120, v121
	v_cvt_pk_bf16_f32 v115, v124, v125
	v_cvt_pk_bf16_f32 v117, v122, v123
	flat_store_dwordx4 v[118:119], v[114:117]
	v_mul_f32_e32 v118, 0xbfb8aa3b, v110
	v_exp_f32_e32 v118, v118
	v_mul_f32_e32 v116, 0xbfb8aa3b, v108
	v_exp_f32_e32 v116, v116
	v_mul_f32_e32 v117, 0xbfb8aa3b, v109
	v_exp_f32_e32 v117, v117
	v_mul_f32_e32 v119, 0xbfb8aa3b, v111
	v_exp_f32_e32 v119, v119
	v_mul_f32_e32 v120, 0xbfb8aa3b, v104
	v_exp_f32_e32 v120, v120
	v_mul_f32_e32 v121, 0xbfb8aa3b, v105
	v_add_f32_e32 v116, 1.0, v116
	v_exp_f32_e32 v121, v121
	v_mul_f32_e32 v122, 0xbfb8aa3b, v106
	v_rcp_f32_e32 v116, v116
	v_add_f32_e32 v117, 1.0, v117
	v_exp_f32_e32 v122, v122
	v_mul_f32_e32 v123, 0xbfb8aa3b, v107
	v_rcp_f32_e32 v117, v117
	v_add_f32_e32 v118, 1.0, v118
	v_exp_f32_e32 v123, v123
	v_rcp_f32_e32 v118, v118
	v_add_f32_e32 v119, 1.0, v119
	v_rcp_f32_e32 v119, v119
	v_add_f32_e32 v120, 1.0, v120
	v_rcp_f32_e32 v120, v120
	v_add_f32_e32 v121, 1.0, v121
	v_mul_f32_e32 v108, v108, v116
	v_rcp_f32_e32 v121, v121
	v_add_f32_e32 v122, 1.0, v122
	v_mul_f32_e32 v108, v108, v100
	v_mul_f32_e32 v100, v109, v117
	v_rcp_f32_e32 v122, v122
	v_add_f32_e32 v123, 1.0, v123
	v_mul_f32_e32 v109, v100, v101
	v_mul_f32_e32 v100, v110, v118
	v_rcp_f32_e32 v123, v123
	v_mul_f32_e32 v102, v100, v102
	v_mul_f32_e32 v100, v111, v119
	v_mul_f32_e32 v103, v100, v103
	v_mul_f32_e32 v100, v104, v120
	v_mul_f32_e32 v104, v100, v96
	v_mul_f32_e32 v96, v105, v121
	v_or_b32_e32 v114, 16, v160
	v_mul_f32_e32 v105, v96, v97
	v_mul_f32_e32 v96, v106, v122
	v_mad_i64_i32 v[114:115], s[0:1], v114, s33, v[138:139]
	v_mul_f32_e32 v106, v96, v98
	v_mul_f32_e32 v96, v107, v123
	v_mul_f32_e32 v99, v96, v99
	v_lshl_add_u64 v[100:101], v[114:115], 0, v[112:113]
	v_cvt_pk_bf16_f32 v98, v104, v105
	v_cvt_pk_bf16_f32 v96, v108, v109
	v_cvt_pk_bf16_f32 v97, v102, v103
	v_cvt_pk_bf16_f32 v99, v106, v99
	flat_store_dwordx4 v[100:101], v[96:99]
	v_mul_f32_e32 v100, 0xbfb8aa3b, v94
	v_exp_f32_e32 v100, v100
	v_mul_f32_e32 v98, 0xbfb8aa3b, v92
	v_exp_f32_e32 v98, v98
	v_mul_f32_e32 v99, 0xbfb8aa3b, v93
	v_exp_f32_e32 v99, v99
	v_mul_f32_e32 v101, 0xbfb8aa3b, v95
	v_exp_f32_e32 v101, v101
	v_mul_f32_e32 v102, 0xbfb8aa3b, v88
	v_exp_f32_e32 v102, v102
	v_mul_f32_e32 v103, 0xbfb8aa3b, v89
	v_add_f32_e32 v98, 1.0, v98
	v_exp_f32_e32 v103, v103
	v_mul_f32_e32 v104, 0xbfb8aa3b, v90
	v_rcp_f32_e32 v98, v98
	v_add_f32_e32 v99, 1.0, v99
	v_exp_f32_e32 v104, v104
	v_mul_f32_e32 v105, 0xbfb8aa3b, v91
	v_rcp_f32_e32 v99, v99
	v_add_f32_e32 v100, 1.0, v100
	v_exp_f32_e32 v105, v105
	v_rcp_f32_e32 v100, v100
	v_add_f32_e32 v101, 1.0, v101
	v_rcp_f32_e32 v101, v101
	v_add_f32_e32 v102, 1.0, v102
	v_rcp_f32_e32 v102, v102
	v_add_f32_e32 v103, 1.0, v103
	v_mul_f32_e32 v92, v92, v98
	v_rcp_f32_e32 v103, v103
	v_add_f32_e32 v104, 1.0, v104
	v_mul_f32_e32 v92, v92, v84
	v_mul_f32_e32 v84, v93, v99
	v_rcp_f32_e32 v104, v104
	v_add_f32_e32 v105, 1.0, v105
	v_mul_f32_e32 v93, v84, v85
	v_mul_f32_e32 v84, v94, v100
	v_rcp_f32_e32 v105, v105
	v_mul_f32_e32 v86, v84, v86
	v_mul_f32_e32 v84, v95, v101
	v_mul_f32_e32 v87, v84, v87
	v_mul_f32_e32 v84, v88, v102
	v_mul_f32_e32 v88, v84, v80
	v_mul_f32_e32 v80, v89, v103
	v_or_b32_e32 v96, 32, v160
	v_mul_f32_e32 v89, v80, v81
	v_mul_f32_e32 v80, v90, v104
	v_mad_i64_i32 v[96:97], s[0:1], v96, s33, v[138:139]
	v_mul_f32_e32 v90, v80, v82
	v_mul_f32_e32 v80, v91, v105
	v_mul_f32_e32 v83, v80, v83
	v_lshl_add_u64 v[84:85], v[96:97], 0, v[112:113]
	v_cvt_pk_bf16_f32 v82, v88, v89
	v_cvt_pk_bf16_f32 v80, v92, v93
	v_cvt_pk_bf16_f32 v81, v86, v87
	v_cvt_pk_bf16_f32 v83, v90, v83
	flat_store_dwordx4 v[84:85], v[80:83]
	v_mul_f32_e32 v84, 0xbfb8aa3b, v78
	v_exp_f32_e32 v84, v84
	v_mul_f32_e32 v82, 0xbfb8aa3b, v76
	v_exp_f32_e32 v82, v82
	v_mul_f32_e32 v83, 0xbfb8aa3b, v77
	v_exp_f32_e32 v83, v83
	v_mul_f32_e32 v85, 0xbfb8aa3b, v79
	v_exp_f32_e32 v85, v85
	v_mul_f32_e32 v86, 0xbfb8aa3b, v72
	v_exp_f32_e32 v86, v86
	v_mul_f32_e32 v87, 0xbfb8aa3b, v73
	v_add_f32_e32 v82, 1.0, v82
	v_exp_f32_e32 v87, v87
	v_mul_f32_e32 v88, 0xbfb8aa3b, v74
	v_rcp_f32_e32 v82, v82
	v_add_f32_e32 v83, 1.0, v83
	v_exp_f32_e32 v88, v88
	v_mul_f32_e32 v89, 0xbfb8aa3b, v75
	v_rcp_f32_e32 v83, v83
	v_add_f32_e32 v84, 1.0, v84
	v_exp_f32_e32 v89, v89
	v_rcp_f32_e32 v84, v84
	v_add_f32_e32 v85, 1.0, v85
	v_rcp_f32_e32 v85, v85
	v_add_f32_e32 v86, 1.0, v86
	v_rcp_f32_e32 v86, v86
	v_add_f32_e32 v87, 1.0, v87
	v_mul_f32_e32 v76, v76, v82
	v_rcp_f32_e32 v87, v87
	v_add_f32_e32 v88, 1.0, v88
	v_mul_f32_e32 v76, v76, v68
	v_mul_f32_e32 v68, v77, v83
	v_rcp_f32_e32 v88, v88
	v_add_f32_e32 v89, 1.0, v89
	v_mul_f32_e32 v77, v68, v69
	v_mul_f32_e32 v68, v78, v84
	v_rcp_f32_e32 v89, v89
	v_mul_f32_e32 v70, v68, v70
	v_mul_f32_e32 v68, v79, v85
	v_mul_f32_e32 v71, v68, v71
	v_mul_f32_e32 v68, v72, v86
	v_mul_f32_e32 v72, v68, v64
	v_mul_f32_e32 v64, v73, v87
	v_or_b32_e32 v80, 48, v160
	v_mul_f32_e32 v73, v64, v65
	v_mul_f32_e32 v64, v74, v88
	v_mad_i64_i32 v[80:81], s[0:1], v80, s33, v[138:139]
	v_mul_f32_e32 v74, v64, v66
	v_mul_f32_e32 v64, v75, v89
	v_mul_f32_e32 v67, v64, v67
	v_lshl_add_u64 v[68:69], v[80:81], 0, v[112:113]
	v_cvt_pk_bf16_f32 v66, v72, v73
	v_cvt_pk_bf16_f32 v64, v76, v77
	v_cvt_pk_bf16_f32 v65, v70, v71
	v_cvt_pk_bf16_f32 v67, v74, v67
	flat_store_dwordx4 v[68:69], v[64:67]
	v_mul_f32_e32 v68, 0xbfb8aa3b, v62
	v_exp_f32_e32 v68, v68
	v_mul_f32_e32 v66, 0xbfb8aa3b, v60
	v_exp_f32_e32 v66, v66
	v_mul_f32_e32 v67, 0xbfb8aa3b, v61
	v_exp_f32_e32 v67, v67
	v_mul_f32_e32 v69, 0xbfb8aa3b, v63
	v_exp_f32_e32 v69, v69
	v_mul_f32_e32 v70, 0xbfb8aa3b, v56
	v_exp_f32_e32 v70, v70
	v_mul_f32_e32 v71, 0xbfb8aa3b, v57
	v_add_f32_e32 v66, 1.0, v66
	v_exp_f32_e32 v71, v71
	v_mul_f32_e32 v72, 0xbfb8aa3b, v58
	v_rcp_f32_e32 v66, v66
	v_add_f32_e32 v67, 1.0, v67
	v_exp_f32_e32 v72, v72
	v_mul_f32_e32 v73, 0xbfb8aa3b, v59
	v_rcp_f32_e32 v67, v67
	v_add_f32_e32 v68, 1.0, v68
	v_exp_f32_e32 v73, v73
	v_rcp_f32_e32 v68, v68
	v_add_f32_e32 v69, 1.0, v69
	v_rcp_f32_e32 v69, v69
	v_add_f32_e32 v70, 1.0, v70
	v_rcp_f32_e32 v70, v70
	v_add_f32_e32 v71, 1.0, v71
	v_mul_f32_e32 v60, v60, v66
	v_rcp_f32_e32 v71, v71
	v_add_f32_e32 v72, 1.0, v72
	v_mul_f32_e32 v60, v60, v52
	v_mul_f32_e32 v52, v61, v67
	v_rcp_f32_e32 v72, v72
	v_add_f32_e32 v73, 1.0, v73
	v_mul_f32_e32 v61, v52, v53
	v_mul_f32_e32 v52, v62, v68
	v_rcp_f32_e32 v73, v73
	v_mul_f32_e32 v54, v52, v54
	v_mul_f32_e32 v52, v63, v69
	v_mul_f32_e32 v55, v52, v55
	v_mul_f32_e32 v52, v56, v70
	v_mul_f32_e32 v56, v52, v48
	v_mul_f32_e32 v48, v57, v71
	v_add_u32_e32 v64, 0x80, v160
	v_mul_f32_e32 v57, v48, v49
	v_mul_f32_e32 v48, v58, v72
	v_mad_i64_i32 v[64:65], s[0:1], v64, s33, v[138:139]
	v_mul_f32_e32 v58, v48, v50
	v_mul_f32_e32 v48, v59, v73
	v_mul_f32_e32 v51, v48, v51
	v_lshl_add_u64 v[52:53], v[64:65], 0, v[112:113]
	v_cvt_pk_bf16_f32 v50, v56, v57
	v_cvt_pk_bf16_f32 v48, v60, v61
	v_cvt_pk_bf16_f32 v49, v54, v55
	v_cvt_pk_bf16_f32 v51, v58, v51
	flat_store_dwordx4 v[52:53], v[48:51]
	v_mul_f32_e32 v52, 0xbfb8aa3b, v46
	v_exp_f32_e32 v52, v52
	v_mul_f32_e32 v50, 0xbfb8aa3b, v44
	v_exp_f32_e32 v50, v50
	v_mul_f32_e32 v51, 0xbfb8aa3b, v45
	v_exp_f32_e32 v51, v51
	v_mul_f32_e32 v53, 0xbfb8aa3b, v47
	v_exp_f32_e32 v53, v53
	v_mul_f32_e32 v54, 0xbfb8aa3b, v40
	v_exp_f32_e32 v54, v54
	v_mul_f32_e32 v55, 0xbfb8aa3b, v41
	v_add_f32_e32 v50, 1.0, v50
	v_exp_f32_e32 v55, v55
	v_mul_f32_e32 v56, 0xbfb8aa3b, v42
	v_rcp_f32_e32 v50, v50
	v_add_f32_e32 v51, 1.0, v51
	v_exp_f32_e32 v56, v56
	v_mul_f32_e32 v57, 0xbfb8aa3b, v43
	v_rcp_f32_e32 v51, v51
	v_add_f32_e32 v52, 1.0, v52
	v_exp_f32_e32 v57, v57
	v_rcp_f32_e32 v52, v52
	v_add_f32_e32 v53, 1.0, v53
	v_rcp_f32_e32 v53, v53
	v_add_f32_e32 v54, 1.0, v54
	v_rcp_f32_e32 v54, v54
	v_add_f32_e32 v55, 1.0, v55
	v_mul_f32_e32 v44, v44, v50
	v_rcp_f32_e32 v55, v55
	v_add_f32_e32 v56, 1.0, v56
	v_mul_f32_e32 v44, v44, v36
	v_mul_f32_e32 v36, v45, v51
	v_rcp_f32_e32 v56, v56
	v_add_f32_e32 v57, 1.0, v57
	v_mul_f32_e32 v45, v36, v37
	v_mul_f32_e32 v36, v46, v52
	v_rcp_f32_e32 v57, v57
	v_mul_f32_e32 v38, v36, v38
	v_mul_f32_e32 v36, v47, v53
	v_mul_f32_e32 v39, v36, v39
	v_mul_f32_e32 v36, v40, v54
	v_mul_f32_e32 v40, v36, v32
	v_mul_f32_e32 v32, v41, v55
	v_add_u32_e32 v48, 0x90, v160
	v_mul_f32_e32 v41, v32, v33
	v_mul_f32_e32 v32, v42, v56
	v_mad_i64_i32 v[48:49], s[0:1], v48, s33, v[138:139]
	v_mul_f32_e32 v42, v32, v34
	v_mul_f32_e32 v32, v43, v57
	v_mul_f32_e32 v35, v32, v35
	v_lshl_add_u64 v[36:37], v[48:49], 0, v[112:113]
	v_cvt_pk_bf16_f32 v34, v40, v41
	v_cvt_pk_bf16_f32 v32, v44, v45
	v_cvt_pk_bf16_f32 v33, v38, v39
	v_cvt_pk_bf16_f32 v35, v42, v35
	flat_store_dwordx4 v[36:37], v[32:35]
	v_mul_f32_e32 v36, 0xbfb8aa3b, v30
	v_exp_f32_e32 v36, v36
	v_mul_f32_e32 v34, 0xbfb8aa3b, v28
	v_exp_f32_e32 v34, v34
	v_mul_f32_e32 v35, 0xbfb8aa3b, v29
	v_exp_f32_e32 v35, v35
	v_mul_f32_e32 v37, 0xbfb8aa3b, v31
	v_exp_f32_e32 v37, v37
	v_mul_f32_e32 v38, 0xbfb8aa3b, v24
	v_exp_f32_e32 v38, v38
	v_mul_f32_e32 v39, 0xbfb8aa3b, v25
	v_add_f32_e32 v34, 1.0, v34
	v_exp_f32_e32 v39, v39
	v_mul_f32_e32 v40, 0xbfb8aa3b, v26
	v_rcp_f32_e32 v34, v34
	v_add_f32_e32 v35, 1.0, v35
	v_exp_f32_e32 v40, v40
	v_mul_f32_e32 v41, 0xbfb8aa3b, v27
	v_rcp_f32_e32 v35, v35
	v_add_f32_e32 v36, 1.0, v36
	v_exp_f32_e32 v41, v41
	v_rcp_f32_e32 v36, v36
	v_add_f32_e32 v37, 1.0, v37
	v_rcp_f32_e32 v37, v37
	v_add_f32_e32 v38, 1.0, v38
	v_rcp_f32_e32 v38, v38
	v_add_f32_e32 v39, 1.0, v39
	v_mul_f32_e32 v28, v28, v34
	v_rcp_f32_e32 v39, v39
	v_add_f32_e32 v40, 1.0, v40
	v_mul_f32_e32 v28, v28, v20
	v_mul_f32_e32 v20, v29, v35
	v_rcp_f32_e32 v40, v40
	v_add_f32_e32 v41, 1.0, v41
	v_mul_f32_e32 v29, v20, v21
	v_mul_f32_e32 v20, v30, v36
	v_rcp_f32_e32 v41, v41
	v_mul_f32_e32 v22, v20, v22
	v_mul_f32_e32 v20, v31, v37
	v_mul_f32_e32 v23, v20, v23
	v_mul_f32_e32 v20, v24, v38
	v_mul_f32_e32 v24, v20, v16
	v_mul_f32_e32 v16, v25, v39
	v_add_u32_e32 v32, 0xa0, v160
	v_mul_f32_e32 v25, v16, v17
	v_mul_f32_e32 v16, v26, v40
	v_mad_i64_i32 v[32:33], s[0:1], v32, s33, v[138:139]
	v_mul_f32_e32 v26, v16, v18
	v_mul_f32_e32 v16, v27, v41
	v_mul_f32_e32 v19, v16, v19
	v_lshl_add_u64 v[20:21], v[32:33], 0, v[112:113]
	v_cvt_pk_bf16_f32 v18, v24, v25
	v_cvt_pk_bf16_f32 v16, v28, v29
	v_cvt_pk_bf16_f32 v17, v22, v23
	v_cvt_pk_bf16_f32 v19, v26, v19
	flat_store_dwordx4 v[20:21], v[16:19]
	v_mul_f32_e32 v20, 0xbfb8aa3b, v14
	v_exp_f32_e32 v20, v20
	v_mul_f32_e32 v18, 0xbfb8aa3b, v12
	v_exp_f32_e32 v18, v18
	v_mul_f32_e32 v19, 0xbfb8aa3b, v13
	v_exp_f32_e32 v19, v19
	v_mul_f32_e32 v21, 0xbfb8aa3b, v15
	v_exp_f32_e32 v21, v21
	v_mul_f32_e32 v22, 0xbfb8aa3b, v8
	v_exp_f32_e32 v22, v22
	v_mul_f32_e32 v23, 0xbfb8aa3b, v9
	v_add_f32_e32 v18, 1.0, v18
	v_exp_f32_e32 v23, v23
	v_mul_f32_e32 v24, 0xbfb8aa3b, v10
	v_rcp_f32_e32 v18, v18
	v_add_f32_e32 v19, 1.0, v19
	v_exp_f32_e32 v24, v24
	v_mul_f32_e32 v25, 0xbfb8aa3b, v11
	v_rcp_f32_e32 v19, v19
	v_add_f32_e32 v20, 1.0, v20
	v_exp_f32_e32 v25, v25
	v_rcp_f32_e32 v20, v20
	v_add_f32_e32 v21, 1.0, v21
	v_rcp_f32_e32 v21, v21
	v_add_f32_e32 v22, 1.0, v22
	v_rcp_f32_e32 v22, v22
	v_add_f32_e32 v23, 1.0, v23
	v_mul_f32_e32 v12, v12, v18
	v_rcp_f32_e32 v23, v23
	v_add_f32_e32 v24, 1.0, v24
	v_mul_f32_e32 v12, v12, v4
	v_mul_f32_e32 v4, v13, v19
	v_rcp_f32_e32 v24, v24
	v_add_f32_e32 v25, 1.0, v25
	v_mul_f32_e32 v13, v4, v5
	v_mul_f32_e32 v4, v14, v20
	v_rcp_f32_e32 v25, v25
	v_mul_f32_e32 v6, v4, v6
	v_mul_f32_e32 v4, v15, v21
	v_mul_f32_e32 v7, v4, v7
	v_mul_f32_e32 v4, v8, v22
	v_mul_f32_e32 v8, v4, v0
	v_mul_f32_e32 v0, v9, v23
	v_add_u32_e32 v16, 0xb0, v160
	v_mul_f32_e32 v9, v0, v1
	v_mul_f32_e32 v0, v10, v24
	v_mad_i64_i32 v[16:17], s[0:1], v16, s33, v[138:139]
	v_mul_f32_e32 v10, v0, v2
	v_mul_f32_e32 v0, v11, v25
	v_mul_f32_e32 v3, v0, v3
	v_lshl_add_u64 v[4:5], v[16:17], 0, v[112:113]
	s_and_b64 vcc, exec, s[6:7]
	s_mov_b32 s20, s8
	s_mov_b32 s14, s4
	s_mov_b64 s[16:17], s[12:13]
	s_mov_b64 s[0:1], s[10:11]
	v_cvt_pk_bf16_f32 v0, v12, v13
	v_cvt_pk_bf16_f32 v1, v6, v7
	v_cvt_pk_bf16_f32 v2, v8, v9
	v_cvt_pk_bf16_f32 v3, v10, v3
	flat_store_dwordx4 v[4:5], v[0:3]
	s_cbranch_vccz .LBB0_286
	s_waitcnt vmcnt(0)
	s_cmpk_gt_u32 s39, 0xff
	v_readlane_b32 s51, v252, 10
	s_cbranch_scc1 .LBB0_293
	s_barrier

.LBB0_321:
	s_add_u32 s0, s16, 0xfffc0080
	s_addc_u32 s1, s17, -1
	s_add_i32 s2, 0, 0x10000
	v_add_u32_e32 v138, s2, v154
	ds_read_b128 v[156:159], v138
	ds_read_b128 v[160:163], v138 offset:1024
	ds_read_b128 v[164:167], v138 offset:2048
	ds_read_b128 v[168:171], v138 offset:3072
	s_cmp_eq_u32 s59, 12
	s_cselect_b32 s41, s11, s1
	s_cselect_b32 s40, s10, s0
	s_cselect_b32 s1, s13, s9
	s_cselect_b32 s0, s12, s5
	s_add_i32 m0, s15, 0xc000
	ds_read_b128 v[172:175], v155
	ds_read_b128 v[176:179], v155 offset:1024
	ds_read_b128 v[180:183], v155 offset:2048
	ds_read_b128 v[184:187], v155 offset:3072
	ds_read_b128 v[188:191], v155 offset:4096
	ds_read_b128 v[192:195], v155 offset:5120
	ds_read_b128 v[196:199], v155 offset:6144
	ds_read_b128 v[200:203], v155 offset:7168
	global_load_lds_dwordx4 v136, s[16:17]
	s_add_i32 m0, s15, 0xe000
	s_nop 0
	global_load_lds_dwordx4 v134, s[16:17]
	s_waitcnt lgkmcnt(8)
	s_barrier
	s_waitcnt lgkmcnt(0)
	s_setprio 1
	v_mfma_f32_16x16x32_bf16 v[124:127], v[156:159], v[172:175], v[124:127]
	v_mfma_f32_16x16x32_bf16 v[120:123], v[164:167], v[172:175], v[120:123]
	v_mfma_f32_16x16x32_bf16 v[116:119], v[156:159], v[180:183], v[116:119]
	v_mfma_f32_16x16x32_bf16 v[108:111], v[164:167], v[180:183], v[108:111]
	v_mfma_f32_16x16x32_bf16 v[100:103], v[156:159], v[188:191], v[100:103]
	v_mfma_f32_16x16x32_bf16 v[92:95], v[164:167], v[188:191], v[92:95]
	v_mfma_f32_16x16x32_bf16 v[84:87], v[156:159], v[196:199], v[84:87]
	v_mfma_f32_16x16x32_bf16 v[76:79], v[164:167], v[196:199], v[76:79]
	v_mfma_f32_16x16x32_bf16 v[124:127], v[160:163], v[176:179], v[124:127]
	v_mfma_f32_16x16x32_bf16 v[120:123], v[168:171], v[176:179], v[120:123]
	v_mfma_f32_16x16x32_bf16 v[116:119], v[160:163], v[184:187], v[116:119]
	v_mfma_f32_16x16x32_bf16 v[108:111], v[168:171], v[184:187], v[108:111]
	v_mfma_f32_16x16x32_bf16 v[100:103], v[160:163], v[192:195], v[100:103]
	v_mfma_f32_16x16x32_bf16 v[92:95], v[168:171], v[192:195], v[92:95]
	v_mfma_f32_16x16x32_bf16 v[84:87], v[160:163], v[200:203], v[84:87]
	v_mfma_f32_16x16x32_bf16 v[76:79], v[168:171], v[200:203], v[76:79]
	s_setprio 0
	s_barrier
	s_add_i32 s30, 0, 0x14000
	v_add_u32_e32 v138, s30, v154
	s_add_i32 s2, s2, s45
	ds_read_b128 v[204:207], v138
	ds_read_b128 v[208:211], v138 offset:1024
	ds_read_b128 v[228:231], v138 offset:2048
	ds_read_b128 v[232:235], v138 offset:3072
	s_mov_b32 m0, s2
	s_nop 0
	global_load_lds_dwordx4 v140, s[0:1]
	s_add_i32 m0, s2, 0x2000
	s_nop 0
	global_load_lds_dwordx4 v132, s[0:1]
	s_barrier
	s_waitcnt lgkmcnt(0)
	s_setprio 1
	v_mfma_f32_16x16x32_bf16 v[112:115], v[204:207], v[172:175], v[112:115]
	v_mfma_f32_16x16x32_bf16 v[104:107], v[228:231], v[172:175], v[104:107]
	v_mfma_f32_16x16x32_bf16 v[96:99], v[204:207], v[180:183], v[96:99]
	v_mfma_f32_16x16x32_bf16 v[88:91], v[228:231], v[180:183], v[88:91]
	v_mfma_f32_16x16x32_bf16 v[80:83], v[204:207], v[188:191], v[80:83]
	v_mfma_f32_16x16x32_bf16 v[72:75], v[228:231], v[188:191], v[72:75]
	v_mfma_f32_16x16x32_bf16 v[68:71], v[204:207], v[196:199], v[68:71]
	v_mfma_f32_16x16x32_bf16 v[64:67], v[228:231], v[196:199], v[64:67]
	v_mfma_f32_16x16x32_bf16 v[112:115], v[208:211], v[176:179], v[112:115]
	v_mfma_f32_16x16x32_bf16 v[104:107], v[232:235], v[176:179], v[104:107]
	v_mfma_f32_16x16x32_bf16 v[96:99], v[208:211], v[184:187], v[96:99]
	v_mfma_f32_16x16x32_bf16 v[88:91], v[232:235], v[184:187], v[88:91]
	v_mfma_f32_16x16x32_bf16 v[80:83], v[208:211], v[192:195], v[80:83]
	v_mfma_f32_16x16x32_bf16 v[72:75], v[232:235], v[192:195], v[72:75]
	v_mfma_f32_16x16x32_bf16 v[68:71], v[208:211], v[200:203], v[68:71]
	v_mfma_f32_16x16x32_bf16 v[64:67], v[232:235], v[200:203], v[64:67]
	s_setprio 0
	s_mov_b32 m0, s15
	s_barrier
	ds_read_b128 v[172:175], v155 offset:16384
	ds_read_b128 v[176:179], v155 offset:17408
	ds_read_b128 v[180:183], v155 offset:18432
	ds_read_b128 v[184:187], v155 offset:19456
	ds_read_b128 v[188:191], v155 offset:20480
	ds_read_b128 v[192:195], v155 offset:21504
	ds_read_b128 v[196:199], v155 offset:22528
	ds_read_b128 v[200:203], v155 offset:23552
	global_load_lds_dwordx4 v128, s[40:41]
	s_mov_b32 m0, s46
	s_nop 0
	global_load_lds_dwordx4 v130, s[40:41]
	s_barrier
	s_waitcnt lgkmcnt(0)
	s_setprio 1
	v_mfma_f32_16x16x32_bf16 v[60:63], v[156:159], v[172:175], v[60:63]
	v_mfma_f32_16x16x32_bf16 v[56:59], v[164:167], v[172:175], v[56:59]
	v_mfma_f32_16x16x32_bf16 v[52:55], v[156:159], v[180:183], v[52:55]
	v_mfma_f32_16x16x32_bf16 v[44:47], v[164:167], v[180:183], v[44:47]
	v_mfma_f32_16x16x32_bf16 v[36:39], v[156:159], v[188:191], v[36:39]
	v_mfma_f32_16x16x32_bf16 v[28:31], v[164:167], v[188:191], v[28:31]
	v_mfma_f32_16x16x32_bf16 v[20:23], v[156:159], v[196:199], v[20:23]
	v_mfma_f32_16x16x32_bf16 v[12:15], v[164:167], v[196:199], v[12:15]
	v_mfma_f32_16x16x32_bf16 v[60:63], v[160:163], v[176:179], v[60:63]
	v_mfma_f32_16x16x32_bf16 v[56:59], v[168:171], v[176:179], v[56:59]
	v_mfma_f32_16x16x32_bf16 v[52:55], v[160:163], v[184:187], v[52:55]
	v_mfma_f32_16x16x32_bf16 v[44:47], v[168:171], v[184:187], v[44:47]
	v_mfma_f32_16x16x32_bf16 v[36:39], v[160:163], v[192:195], v[36:39]
	v_mfma_f32_16x16x32_bf16 v[28:31], v[168:171], v[192:195], v[28:31]
	v_mfma_f32_16x16x32_bf16 v[20:23], v[160:163], v[200:203], v[20:23]
	v_mfma_f32_16x16x32_bf16 v[12:15], v[168:171], v[200:203], v[12:15]
	s_setprio 0
	s_barrier
	s_add_u32 s18, s0, 0x40000
	s_addc_u32 s19, s1, 0
	s_add_i32 s2, s30, s45
	s_mov_b32 m0, s2
	s_nop 0
	global_load_lds_dwordx4 v140, s[18:19]
	s_add_i32 m0, s2, 0x2000
	s_nop 0
	global_load_lds_dwordx4 v132, s[18:19]
	s_waitcnt vmcnt(6)
	s_barrier
	s_setprio 1
	v_mfma_f32_16x16x32_bf16 v[48:51], v[204:207], v[172:175], v[48:51]
	v_mfma_f32_16x16x32_bf16 v[40:43], v[228:231], v[172:175], v[40:43]
	v_mfma_f32_16x16x32_bf16 v[32:35], v[204:207], v[180:183], v[32:35]
	v_mfma_f32_16x16x32_bf16 v[24:27], v[228:231], v[180:183], v[24:27]
	v_mfma_f32_16x16x32_bf16 v[16:19], v[204:207], v[188:191], v[16:19]
	v_mfma_f32_16x16x32_bf16 v[8:11], v[228:231], v[188:191], v[8:11]
	v_mfma_f32_16x16x32_bf16 v[4:7], v[204:207], v[196:199], v[4:7]
	v_mfma_f32_16x16x32_bf16 v[0:3], v[228:231], v[196:199], v[0:3]
	v_mfma_f32_16x16x32_bf16 v[48:51], v[208:211], v[176:179], v[48:51]
	v_mfma_f32_16x16x32_bf16 v[40:43], v[232:235], v[176:179], v[40:43]
	v_mfma_f32_16x16x32_bf16 v[32:35], v[208:211], v[184:187], v[32:35]
	v_mfma_f32_16x16x32_bf16 v[24:27], v[232:235], v[184:187], v[24:27]
	v_mfma_f32_16x16x32_bf16 v[16:19], v[208:211], v[192:195], v[16:19]
	v_mfma_f32_16x16x32_bf16 v[8:11], v[232:235], v[192:195], v[8:11]
	v_mfma_f32_16x16x32_bf16 v[4:7], v[208:211], v[200:203], v[4:7]
	v_mfma_f32_16x16x32_bf16 v[0:3], v[232:235], v[200:203], v[0:3]
	s_setprio 0
	s_add_i32 s2, 0, 0x18000
	v_add_u32_e32 v168, s2, v154
	s_barrier
	ds_read_b128 v[156:159], v168
	ds_read_b128 v[160:163], v168 offset:1024
	ds_read_b128 v[164:167], v168 offset:2048
	ds_read_b128 v[168:171], v168 offset:3072
	s_add_u32 s18, s40, 0x40000
	s_addc_u32 s19, s41, 0
	s_mov_b32 m0, s48
	ds_read_b128 v[172:175], v155 offset:32768
	ds_read_b128 v[176:179], v155 offset:33792
	ds_read_b128 v[180:183], v155 offset:34816
	ds_read_b128 v[184:187], v155 offset:35840
	ds_read_b128 v[188:191], v155 offset:36864
	ds_read_b128 v[192:195], v155 offset:37888
	ds_read_b128 v[196:199], v155 offset:38912
	ds_read_b128 v[200:203], v155 offset:39936
	global_load_lds_dwordx4 v128, s[18:19]
	s_mov_b32 m0, s49
	s_nop 0
	global_load_lds_dwordx4 v130, s[18:19]
	s_waitcnt lgkmcnt(8)
	s_barrier
	s_waitcnt lgkmcnt(0)
	s_setprio 1
	v_mfma_f32_16x16x32_bf16 v[124:127], v[156:159], v[172:175], v[124:127]
	v_mfma_f32_16x16x32_bf16 v[120:123], v[164:167], v[172:175], v[120:123]
	v_mfma_f32_16x16x32_bf16 v[116:119], v[156:159], v[180:183], v[116:119]
	v_mfma_f32_16x16x32_bf16 v[108:111], v[164:167], v[180:183], v[108:111]
	v_mfma_f32_16x16x32_bf16 v[100:103], v[156:159], v[188:191], v[100:103]
	v_mfma_f32_16x16x32_bf16 v[92:95], v[164:167], v[188:191], v[92:95]
	v_mfma_f32_16x16x32_bf16 v[84:87], v[156:159], v[196:199], v[84:87]
	v_mfma_f32_16x16x32_bf16 v[76:79], v[164:167], v[196:199], v[76:79]
	v_mfma_f32_16x16x32_bf16 v[124:127], v[160:163], v[176:179], v[124:127]
	v_mfma_f32_16x16x32_bf16 v[120:123], v[168:171], v[176:179], v[120:123]
	v_mfma_f32_16x16x32_bf16 v[116:119], v[160:163], v[184:187], v[116:119]
	v_mfma_f32_16x16x32_bf16 v[108:111], v[168:171], v[184:187], v[108:111]
	v_mfma_f32_16x16x32_bf16 v[100:103], v[160:163], v[192:195], v[100:103]
	v_mfma_f32_16x16x32_bf16 v[92:95], v[168:171], v[192:195], v[92:95]
	v_mfma_f32_16x16x32_bf16 v[84:87], v[160:163], v[200:203], v[84:87]
	v_mfma_f32_16x16x32_bf16 v[76:79], v[168:171], v[200:203], v[76:79]
	s_setprio 0
	s_barrier
	s_add_i32 s18, 0, 0x1c000
	s_add_i32 s2, s2, s45
	v_add_u32_e32 v232, s18, v154
	s_mov_b32 m0, s2
	ds_read_b128 v[204:207], v232
	ds_read_b128 v[208:211], v232 offset:1024
	ds_read_b128 v[228:231], v232 offset:2048
	ds_read_b128 v[232:235], v232 offset:3072
	s_add_u32 s100, s0, 0x80
	s_addc_u32 s101, s1, 0
	global_load_lds_dwordx4 v140, s[100:101]
	s_add_i32 m0, s2, 0x2000
	s_nop 0
	global_load_lds_dwordx4 v132, s[100:101]
	s_barrier
	s_waitcnt lgkmcnt(0)
	s_setprio 1
	v_mfma_f32_16x16x32_bf16 v[112:115], v[204:207], v[172:175], v[112:115]
	v_mfma_f32_16x16x32_bf16 v[104:107], v[228:231], v[172:175], v[104:107]
	v_mfma_f32_16x16x32_bf16 v[96:99], v[204:207], v[180:183], v[96:99]
	v_mfma_f32_16x16x32_bf16 v[88:91], v[228:231], v[180:183], v[88:91]
	v_mfma_f32_16x16x32_bf16 v[80:83], v[204:207], v[188:191], v[80:83]
	v_mfma_f32_16x16x32_bf16 v[72:75], v[228:231], v[188:191], v[72:75]
	v_mfma_f32_16x16x32_bf16 v[68:71], v[204:207], v[196:199], v[68:71]
	v_mfma_f32_16x16x32_bf16 v[64:67], v[228:231], v[196:199], v[64:67]
	v_mfma_f32_16x16x32_bf16 v[112:115], v[208:211], v[176:179], v[112:115]
	v_mfma_f32_16x16x32_bf16 v[104:107], v[232:235], v[176:179], v[104:107]
	v_mfma_f32_16x16x32_bf16 v[96:99], v[208:211], v[184:187], v[96:99]
	v_mfma_f32_16x16x32_bf16 v[88:91], v[232:235], v[184:187], v[88:91]
	v_mfma_f32_16x16x32_bf16 v[80:83], v[208:211], v[192:195], v[80:83]
	v_mfma_f32_16x16x32_bf16 v[72:75], v[232:235], v[192:195], v[72:75]
	v_mfma_f32_16x16x32_bf16 v[68:71], v[208:211], v[200:203], v[68:71]
	v_mfma_f32_16x16x32_bf16 v[64:67], v[232:235], v[200:203], v[64:67]
	s_setprio 0
	s_mov_b32 m0, s57
	s_barrier
	ds_read_b128 v[172:175], v155 offset:49152
	ds_read_b128 v[176:179], v155 offset:50176
	ds_read_b128 v[180:183], v155 offset:51200
	ds_read_b128 v[184:187], v155 offset:52224
	ds_read_b128 v[188:191], v155 offset:53248
	ds_read_b128 v[192:195], v155 offset:54272
	ds_read_b128 v[196:199], v155 offset:55296
	ds_read_b128 v[200:203], v155 offset:56320
	s_add_u32 s100, s40, 0x80
	s_addc_u32 s101, s41, 0
	global_load_lds_dwordx4 v128, s[100:101]
	s_mov_b32 m0, s58
	s_nop 0
	global_load_lds_dwordx4 v130, s[100:101]
	s_barrier
	s_waitcnt lgkmcnt(0)
	s_setprio 1
	v_mfma_f32_16x16x32_bf16 v[60:63], v[156:159], v[172:175], v[60:63]
	v_mfma_f32_16x16x32_bf16 v[56:59], v[164:167], v[172:175], v[56:59]
	v_mfma_f32_16x16x32_bf16 v[52:55], v[156:159], v[180:183], v[52:55]
	v_mfma_f32_16x16x32_bf16 v[44:47], v[164:167], v[180:183], v[44:47]
	v_mfma_f32_16x16x32_bf16 v[36:39], v[156:159], v[188:191], v[36:39]
	v_mfma_f32_16x16x32_bf16 v[28:31], v[164:167], v[188:191], v[28:31]
	v_mfma_f32_16x16x32_bf16 v[20:23], v[156:159], v[196:199], v[20:23]
	v_mfma_f32_16x16x32_bf16 v[12:15], v[164:167], v[196:199], v[12:15]
	v_mfma_f32_16x16x32_bf16 v[60:63], v[160:163], v[176:179], v[60:63]
	v_mfma_f32_16x16x32_bf16 v[56:59], v[168:171], v[176:179], v[56:59]
	v_mfma_f32_16x16x32_bf16 v[52:55], v[160:163], v[184:187], v[52:55]
	v_mfma_f32_16x16x32_bf16 v[44:47], v[168:171], v[184:187], v[44:47]
	v_mfma_f32_16x16x32_bf16 v[36:39], v[160:163], v[192:195], v[36:39]
	v_mfma_f32_16x16x32_bf16 v[28:31], v[168:171], v[192:195], v[28:31]
	v_mfma_f32_16x16x32_bf16 v[20:23], v[160:163], v[200:203], v[20:23]
	v_mfma_f32_16x16x32_bf16 v[12:15], v[168:171], v[200:203], v[12:15]
	s_setprio 0
	s_barrier
	s_add_u32 s0, s0, 0x40080
	s_addc_u32 s1, s1, 0
	s_add_i32 s2, s18, s45
	s_mov_b32 m0, s2
	s_nop 0
	global_load_lds_dwordx4 v140, s[0:1]
	s_add_i32 m0, s2, 0x2000
	s_nop 0
	global_load_lds_dwordx4 v132, s[0:1]
	s_waitcnt vmcnt(6)
	s_barrier
	s_setprio 1
	v_mfma_f32_16x16x32_bf16 v[48:51], v[204:207], v[172:175], v[48:51]
	v_mfma_f32_16x16x32_bf16 v[40:43], v[228:231], v[172:175], v[40:43]
	v_mfma_f32_16x16x32_bf16 v[32:35], v[204:207], v[180:183], v[32:35]
	v_mfma_f32_16x16x32_bf16 v[24:27], v[228:231], v[180:183], v[24:27]
	v_mfma_f32_16x16x32_bf16 v[16:19], v[204:207], v[188:191], v[16:19]
	v_mfma_f32_16x16x32_bf16 v[8:11], v[228:231], v[188:191], v[8:11]
	v_mfma_f32_16x16x32_bf16 v[4:7], v[204:207], v[196:199], v[4:7]
	v_mfma_f32_16x16x32_bf16 v[0:3], v[228:231], v[196:199], v[0:3]
	v_mfma_f32_16x16x32_bf16 v[48:51], v[208:211], v[176:179], v[48:51]
	v_mfma_f32_16x16x32_bf16 v[40:43], v[232:235], v[176:179], v[40:43]
	v_mfma_f32_16x16x32_bf16 v[32:35], v[208:211], v[184:187], v[32:35]
	v_mfma_f32_16x16x32_bf16 v[24:27], v[232:235], v[184:187], v[24:27]
	v_mfma_f32_16x16x32_bf16 v[16:19], v[208:211], v[192:195], v[16:19]
	v_mfma_f32_16x16x32_bf16 v[8:11], v[232:235], v[192:195], v[8:11]
	v_mfma_f32_16x16x32_bf16 v[4:7], v[208:211], v[200:203], v[4:7]
	v_mfma_f32_16x16x32_bf16 v[0:3], v[232:235], v[200:203], v[0:3]
	s_setprio 0
	s_add_i32 s59, s59, 2
	s_add_u32 s5, s5, 0x100
	s_addc_u32 s9, s9, 0
	s_add_u32 s16, s16, 0x100
	s_addc_u32 s17, s17, 0
	s_cmp_gt_u32 s59, 13
	s_barrier
	s_cbranch_scc0 .LBB0_321
	s_lshl_b32 s0, s14, 8
	v_mbcnt_lo_u32_b32 v139, -1, 0
	v_mbcnt_hi_u32_b32 v139, -1, v139
	s_lshl_b32 s1, s21, 8
	v_ashrrev_i32_e32 v138, 1, v139
	s_add_i32 s0, s0, s51
	v_and_b32_e32 v138, -8, v138
	s_or_b32 s1, s1, s52
	v_and_or_b32 v156, v139, 15, s0
	v_add_u32_e32 v138, s1, v138
	v_ashrrev_i32_e32 v157, 31, v156
	v_ashrrev_i32_e32 v139, 31, v138
	v_lshlrev_b64 v[158:159], 11, v[156:157]
	v_lshl_add_u64 v[158:159], s[26:27], 0, v[158:159]
	v_lshlrev_b64 v[160:161], 1, v[138:139]
	v_lshl_add_u64 v[138:139], v[158:159], 0, v[160:161]
	v_cvt_pk_bf16_f32 v60, v60, v61
	v_cvt_pk_bf16_f32 v61, v62, v63
	v_cvt_pk_bf16_f32 v62, v56, v57
	v_add_co_u32_e32 v56, vcc, s31, v138
	v_cvt_pk_bf16_f32 v112, v112, v113
	v_cvt_pk_bf16_f32 v113, v114, v115
	v_cvt_pk_bf16_f32 v114, v104, v105
	v_or_b32_e32 v104, 16, v156
	s_nop 0
	v_addc_co_u32_e32 v57, vcc, 0, v139, vcc
	v_cvt_pk_bf16_f32 v48, v48, v49
	v_cvt_pk_bf16_f32 v49, v50, v51
	v_cvt_pk_bf16_f32 v51, v42, v43
	v_cvt_pk_bf16_f32 v42, v44, v45
	v_add_co_u32_e32 v44, vcc, s42, v138
	v_ashrrev_i32_e32 v105, 31, v104
	v_cvt_pk_bf16_f32 v96, v96, v97
	v_cvt_pk_bf16_f32 v97, v98, v99
	v_cvt_pk_bf16_f32 v98, v88, v89
	v_or_b32_e32 v88, 32, v156
	v_addc_co_u32_e32 v45, vcc, 0, v139, vcc
	v_lshlrev_b64 v[104:105], 11, v[104:105]
	v_ashrrev_i32_e32 v89, 31, v88
	v_cvt_pk_bf16_f32 v80, v80, v81
	v_cvt_pk_bf16_f32 v81, v82, v83
	v_cvt_pk_bf16_f32 v82, v72, v73
	v_or_b32_e32 v72, 48, v156
	s_mov_b64 s[0:1], 0x40000
	v_cvt_pk_bf16_f32 v32, v32, v33
	v_cvt_pk_bf16_f32 v33, v34, v35
	v_cvt_pk_bf16_f32 v35, v26, v27
	v_cvt_pk_bf16_f32 v26, v28, v29
	v_add_co_u32_e32 v28, vcc, s43, v138
	v_lshl_add_u64 v[104:105], s[26:27], 0, v[104:105]
	v_lshlrev_b64 v[88:89], 11, v[88:89]
	v_ashrrev_i32_e32 v73, 31, v72
	v_cvt_pk_bf16_f32 v68, v68, v69
	v_cvt_pk_bf16_f32 v69, v70, v71
	v_cvt_pk_bf16_f32 v70, v64, v65
	v_lshl_add_u64 v[64:65], v[138:139], 0, s[0:1]
	s_mov_b64 s[0:1], 0x48000
	v_addc_co_u32_e32 v29, vcc, 0, v139, vcc
	v_cvt_pk_bf16_f32 v115, v106, v107
	flat_store_dwordx4 v[138:139], v[112:115] offset:256
	v_lshl_add_u64 v[88:89], s[26:27], 0, v[88:89]
	v_lshlrev_b64 v[72:73], 11, v[72:73]
	v_lshl_add_u64 v[112:113], v[104:105], 0, v[160:161]
	v_cvt_pk_bf16_f32 v50, v40, v41
	flat_store_dwordx4 v[64:65], v[48:51] offset:256
	v_cvt_pk_bf16_f32 v16, v16, v17
	v_cvt_pk_bf16_f32 v17, v18, v19
	v_cvt_pk_bf16_f32 v19, v10, v11
	v_cvt_pk_bf16_f32 v10, v12, v13
	v_add_co_u32_e32 v12, vcc, s47, v138
	s_nop 0
	v_lshl_add_u64 v[48:49], v[138:139], 0, s[0:1]
	s_mov_b64 s[0:1], 0x50000
	v_cvt_pk_bf16_f32 v99, v90, v91
	flat_store_dwordx4 v[112:113], v[96:99] offset:256
	v_lshl_add_u64 v[72:73], s[26:27], 0, v[72:73]
	v_cvt_pk_bf16_f32 v34, v24, v25
	flat_store_dwordx4 v[48:49], v[32:35] offset:256
	v_lshl_add_u64 v[96:97], v[88:89], 0, v[160:161]
	v_addc_co_u32_e32 v13, vcc, 0, v139, vcc
	v_lshl_add_u64 v[32:33], v[138:139], 0, s[0:1]
	s_mov_b64 s[0:1], 0x58000
	v_cvt_pk_bf16_f32 v83, v74, v75
	flat_store_dwordx4 v[96:97], v[80:83] offset:256
	v_cvt_pk_bf16_f32 v18, v8, v9
	flat_store_dwordx4 v[32:33], v[16:19] offset:256
	s_and_b64 vcc, exec, s[6:7]
	v_lshl_add_u64 v[80:81], v[72:73], 0, v[160:161]
	v_lshl_add_u64 v[16:17], v[138:139], 0, s[0:1]
	s_mov_b32 s21, s8
	s_mov_b32 s14, s4
	s_mov_b64 s[16:17], s[12:13]
	s_mov_b64 s[0:1], s[10:11]
	v_cvt_pk_bf16_f32 v124, v124, v125
	v_cvt_pk_bf16_f32 v125, v126, v127
	v_cvt_pk_bf16_f32 v126, v120, v121
	v_cvt_pk_bf16_f32 v127, v122, v123
	flat_store_dwordx4 v[138:139], v[124:127]
	v_cvt_pk_bf16_f32 v104, v116, v117
	v_cvt_pk_bf16_f32 v105, v118, v119
	v_cvt_pk_bf16_f32 v106, v108, v109
	v_cvt_pk_bf16_f32 v107, v110, v111
	flat_store_dwordx4 v[112:113], v[104:107]
	v_cvt_pk_bf16_f32 v88, v100, v101
	v_cvt_pk_bf16_f32 v89, v102, v103
	v_cvt_pk_bf16_f32 v90, v92, v93
	v_cvt_pk_bf16_f32 v91, v94, v95
	flat_store_dwordx4 v[96:97], v[88:91]
	v_cvt_pk_bf16_f32 v72, v84, v85
	v_cvt_pk_bf16_f32 v73, v86, v87
	v_cvt_pk_bf16_f32 v74, v76, v77
	v_cvt_pk_bf16_f32 v75, v78, v79
	flat_store_dwordx4 v[80:81], v[72:75]
	v_cvt_pk_bf16_f32 v71, v66, v67
	flat_store_dwordx4 v[80:81], v[68:71] offset:256
	v_cvt_pk_bf16_f32 v63, v58, v59
	flat_store_dwordx4 v[56:57], v[60:63]
	v_cvt_pk_bf16_f32 v40, v52, v53
	v_cvt_pk_bf16_f32 v41, v54, v55
	v_cvt_pk_bf16_f32 v43, v46, v47
	flat_store_dwordx4 v[44:45], v[40:43]
	v_cvt_pk_bf16_f32 v24, v36, v37
	v_cvt_pk_bf16_f32 v25, v38, v39
	v_cvt_pk_bf16_f32 v27, v30, v31
	flat_store_dwordx4 v[28:29], v[24:27]
	v_cvt_pk_bf16_f32 v8, v20, v21
	v_cvt_pk_bf16_f32 v9, v22, v23
	v_cvt_pk_bf16_f32 v11, v14, v15
	flat_store_dwordx4 v[12:13], v[8:11]
	v_cvt_pk_bf16_f32 v4, v4, v5
	v_cvt_pk_bf16_f32 v5, v6, v7
	v_cvt_pk_bf16_f32 v6, v0, v1
	v_cvt_pk_bf16_f32 v7, v2, v3
	flat_store_dwordx4 v[16:17], v[4:7] offset:256
	s_cbranch_vccz .LBB0_314
	s_waitcnt vmcnt(0)
	s_cmpk_gt_u32 s37, 0xff
	s_cbranch_scc1 .LBB0_325
	s_barrier

.LBB0_367:
	s_add_i32 s15, s1, 1
	s_waitcnt vmcnt(0)
	s_barrier
	s_add_i32 s2, s13, 1
	s_cmp_lg_u32 s13, 2
	s_mov_b32 s14, s13
	s_cselect_b32 s13, s2, 0
	s_cmp_ge_i32 s15, s20
	s_cbranch_scc1 .Lattn_skipdma
	s_add_i32 s18, s12, s1
	s_ashr_i32 s19, s18, 31
	s_lshl_b64 s[18:19], s[18:19], s45
	s_add_u32 s18, s39, s18
	s_addc_u32 s19, s21, s19
	s_lshl_b32 s1, s13, 15
	s_add_i32 s1, s44, s1
	s_mov_b32 m0, s1
	s_add_i32 s2, s1, 0x400
	global_load_lds_dwordx4 v106, s[18:19]
	s_mov_b32 m0, s2
	s_add_i32 s2, s1, 0x800
	global_load_lds_dwordx4 v108, s[18:19]
	s_mov_b32 m0, s2
	s_add_i32 s2, s1, 0xc00
	global_load_lds_dwordx4 v110, s[18:19]
	s_mov_b32 m0, s2
	s_and_b64 vcc, exec, s[10:11]
	global_load_lds_dwordx4 v112, s[18:19]
.Lattn_afterdma:
	s_cbranch_vccz .LBB0_373
.LBB0_369:
	s_cmp_gt_i32 s15, s20
	s_cselect_b64 s[0:1], -1, 0
	s_cbranch_scc0 .LBB0_374

.LBB0_371:
	v_add_f32_e32 v117, 0xc2800000, v117
	s_and_b64 vcc, exec, s[0:1]
	s_cbranch_vccnz .LBB0_377
	s_mov_b32 s1, s15
	s_mov_b32 s0, s14
	s_branch .LBB0_367
.Lattn_skipdma:
	s_and_b64 vcc, exec, s[10:11]
	s_branch .Lattn_afterdma
.LBB0_373:
	s_lshl_b32 s0, s0, 15
	s_add_i32 s0, s0, 0
	v_add_u32_e32 v178, s0, v139
	v_add_u32_e32 v210, s0, v154
	ds_read_b128 v[118:121], v178 offset:16384
	ds_read_b128 v[122:125], v178 offset:16896
	ds_read_b128 v[158:161], v178 offset:17408
	ds_read_b128 v[162:165], v178 offset:17920
	ds_read_b128 v[166:169], v178 offset:18432
	ds_read_b128 v[170:173], v178 offset:18944
	ds_read_b128 v[174:177], v178 offset:19456
	ds_read_b128 v[178:181], v178 offset:19968
	ds_read_b128 v[182:185], v210 offset:16384
	ds_read_b128 v[186:189], v210 offset:16896
	ds_read_b128 v[190:193], v210 offset:17408
	ds_read_b128 v[194:197], v210 offset:17920
	ds_read_b128 v[198:201], v210 offset:18432
	ds_read_b128 v[202:205], v210 offset:18944
	ds_read_b128 v[206:209], v210 offset:19456
	ds_read_b128 v[228:231], v210 offset:19968
	s_waitcnt lgkmcnt(0)
	v_mfma_f32_16x16x32_bf16 v[56:59], v[118:121], v[84:87], v[56:59]
	v_mfma_f32_16x16x32_bf16 v[48:51], v[118:121], v[88:91], v[48:51]
	v_mfma_f32_16x16x32_bf16 v[60:63], v[122:125], v[84:87], v[60:63]
	v_mfma_f32_16x16x32_bf16 v[44:47], v[122:125], v[88:91], v[44:47]
	v_mfma_f32_16x16x32_bf16 v[64:67], v[158:161], v[84:87], v[64:67]
	v_mfma_f32_16x16x32_bf16 v[40:43], v[158:161], v[88:91], v[40:43]
	v_mfma_f32_16x16x32_bf16 v[68:71], v[162:165], v[84:87], v[68:71]
	v_mfma_f32_16x16x32_bf16 v[36:39], v[162:165], v[88:91], v[36:39]
	v_mfma_f32_16x16x32_bf16 v[72:75], v[166:169], v[84:87], v[72:75]
	v_mfma_f32_16x16x32_bf16 v[32:35], v[166:169], v[88:91], v[32:35]
	v_mfma_f32_16x16x32_bf16 v[76:79], v[170:173], v[84:87], v[76:79]
	v_mfma_f32_16x16x32_bf16 v[24:27], v[170:173], v[88:91], v[24:27]
	v_mfma_f32_16x16x32_bf16 v[80:83], v[174:177], v[84:87], v[80:83]
	v_mfma_f32_16x16x32_bf16 v[20:23], v[174:177], v[88:91], v[20:23]
	v_mfma_f32_16x16x32_bf16 v[28:31], v[178:181], v[84:87], v[28:31]
	v_mfma_f32_16x16x32_bf16 v[16:19], v[178:181], v[88:91], v[16:19]
	v_mfma_f32_16x16x32_bf16 v[56:59], v[182:185], v[92:95], v[56:59]
	v_mfma_f32_16x16x32_bf16 v[48:51], v[182:185], v[96:99], v[48:51]
	v_mfma_f32_16x16x32_bf16 v[60:63], v[186:189], v[92:95], v[60:63]
	v_mfma_f32_16x16x32_bf16 v[44:47], v[186:189], v[96:99], v[44:47]
	v_mfma_f32_16x16x32_bf16 v[64:67], v[190:193], v[92:95], v[64:67]
	v_mfma_f32_16x16x32_bf16 v[40:43], v[190:193], v[96:99], v[40:43]
	v_mfma_f32_16x16x32_bf16 v[68:71], v[194:197], v[92:95], v[68:71]
	v_mfma_f32_16x16x32_bf16 v[36:39], v[194:197], v[96:99], v[36:39]
	v_mfma_f32_16x16x32_bf16 v[72:75], v[198:201], v[92:95], v[72:75]
	v_mfma_f32_16x16x32_bf16 v[32:35], v[198:201], v[96:99], v[32:35]
	v_mfma_f32_16x16x32_bf16 v[76:79], v[202:205], v[92:95], v[76:79]
	v_mfma_f32_16x16x32_bf16 v[24:27], v[202:205], v[96:99], v[24:27]
	v_mfma_f32_16x16x32_bf16 v[80:83], v[206:209], v[92:95], v[80:83]
	v_mfma_f32_16x16x32_bf16 v[20:23], v[206:209], v[96:99], v[20:23]
	v_mfma_f32_16x16x32_bf16 v[28:31], v[228:231], v[92:95], v[28:31]
	v_mfma_f32_16x16x32_bf16 v[16:19], v[228:231], v[96:99], v[16:19]
	s_cmp_gt_i32 s15, s20
	s_cselect_b64 s[0:1], -1, 0
	s_cbranch_scc1 .LBB0_370
.LBB0_374:
	s_lshl_b32 s2, s14, 15
	s_add_i32 s2, s2, 0
	v_add_u32_e32 v170, s2, v135
	v_add_u32_e32 v178, s2, v136
	v_add_u32_e32 v186, s2, v137
	v_add_u32_e32 v194, s2, v138
	ds_read_b128 v[84:87], v170
	ds_read_b128 v[88:91], v170 offset:1024
	ds_read_b128 v[92:95], v178
	ds_read_b128 v[96:99], v178 offset:1024
	ds_read_b128 v[118:121], v186
	ds_read_b128 v[122:125], v186 offset:1024
	ds_read_b128 v[158:161], v194
	ds_read_b128 v[162:165], v194 offset:1024
	ds_read_b128 v[166:169], v170 offset:2048
	ds_read_b128 v[170:173], v170 offset:3072
	ds_read_b128 v[174:177], v178 offset:2048
	ds_read_b128 v[178:181], v178 offset:3072
	ds_read_b128 v[182:185], v186 offset:2048
	ds_read_b128 v[186:189], v186 offset:3072
	ds_read_b128 v[190:193], v194 offset:2048
	ds_read_b128 v[194:197], v194 offset:3072
	s_waitcnt lgkmcnt(0)
	v_mfma_f32_16x16x32_bf16 v[84:87], v[84:87], v[0:3], v[52:55]
	v_mfma_f32_16x16x32_bf16 v[118:121], v[118:121], v[8:11], v[52:55]
	v_mfma_f32_16x16x32_bf16 v[88:91], v[88:91], v[0:3], v[52:55]
	v_mfma_f32_16x16x32_bf16 v[122:125], v[122:125], v[8:11], v[52:55]
	v_mfma_f32_16x16x32_bf16 v[166:169], v[166:169], v[0:3], v[52:55]
	v_mfma_f32_16x16x32_bf16 v[182:185], v[182:185], v[8:11], v[52:55]
	v_mfma_f32_16x16x32_bf16 v[170:173], v[170:173], v[0:3], v[52:55]
	v_mfma_f32_16x16x32_bf16 v[186:189], v[186:189], v[8:11], v[52:55]
	v_mfma_f32_16x16x32_bf16 v[84:87], v[92:95], v[4:7], v[84:87]
	v_mfma_f32_16x16x32_bf16 v[92:95], v[158:161], v[12:15], v[118:121]
	v_mfma_f32_16x16x32_bf16 v[88:91], v[96:99], v[4:7], v[88:91]
	v_mfma_f32_16x16x32_bf16 v[96:99], v[162:165], v[12:15], v[122:125]
	v_mfma_f32_16x16x32_bf16 v[118:121], v[174:177], v[4:7], v[166:169]
	v_mfma_f32_16x16x32_bf16 v[122:125], v[190:193], v[12:15], v[182:185]
	v_mfma_f32_16x16x32_bf16 v[158:161], v[178:181], v[4:7], v[170:173]
	v_mfma_f32_16x16x32_bf16 v[162:165], v[194:197], v[12:15], v[186:189]
	v_add_f32_e32 v170, 0x42100000, v117
	v_fma_f32 v84, -v157, |v170|, v84
	v_add_f32_e32 v168, -1.0, v170
	v_fma_f32 v92, -v157, |v170|, v92
	v_exp_f32_e32 v166, v84
	v_fma_f32 v84, -v157, |v168|, v85
	v_exp_f32_e32 v167, v92
	v_exp_f32_e32 v92, v84
	v_fma_f32 v84, -v157, |v168|, v93
	v_exp_f32_e32 v93, v84
	v_add_f32_e32 v84, -2.0, v170
	v_fma_f32 v85, -v157, |v84|, v86
	v_fma_f32 v84, -v157, |v84|, v94
	v_exp_f32_e32 v169, v84
	v_add_f32_e32 v84, 0xc0400000, v170
	v_exp_f32_e32 v168, v85
	v_fma_f32 v85, -v157, |v84|, v87
	v_fma_f32 v84, -v157, |v84|, v95
	v_exp_f32_e32 v95, v84
	v_add_f32_e32 v84, 0x42000000, v117
	v_exp_f32_e32 v94, v85
	v_fma_f32 v85, -v157, |v84|, v88
	v_exp_f32_e32 v170, v85
	v_fma_f32 v85, -v157, |v84|, v96
	v_exp_f32_e32 v171, v85
	v_add_f32_e32 v85, -1.0, v84
	v_fma_f32 v86, -v157, |v85|, v89
	v_fma_f32 v85, -v157, |v85|, v97
	v_exp_f32_e32 v97, v85
	v_add_f32_e32 v85, -2.0, v84
	v_exp_f32_e32 v96, v86
	v_fma_f32 v86, -v157, |v85|, v90
	v_fma_f32 v85, -v157, |v85|, v98
	v_add_f32_e32 v84, 0xc0400000, v84
	v_exp_f32_e32 v173, v85
	v_fma_f32 v85, -v157, |v84|, v91
	v_fma_f32 v84, -v157, |v84|, v99
	v_exp_f32_e32 v90, v85
	v_exp_f32_e32 v91, v84
	v_add_f32_e32 v84, v114, v166
	v_add_f32_e32 v85, v115, v167
	v_exp_f32_e32 v172, v86
	v_add_f32_e32 v84, v84, v92
	v_add_f32_e32 v85, v85, v93
	v_add_f32_e32 v84, v84, v168
	v_add_f32_e32 v85, v85, v169
	v_cvt_pk_bf16_f32 v88, v167, v93
	v_cvt_pk_bf16_f32 v86, v170, v96
	v_cvt_pk_bf16_f32 v87, v172, v90
	v_add_f32_e32 v84, v84, v94
	v_add_f32_e32 v85, v85, v95
	v_add_f32_e32 v84, v84, v170
	v_add_f32_e32 v85, v85, v171
	v_add_f32_e32 v84, v84, v96
	v_add_f32_e32 v85, v85, v97
	v_add_f32_e32 v84, v84, v172
	v_add_f32_e32 v85, v85, v173
	v_add_f32_e32 v98, v84, v90
	v_add_f32_e32 v99, v85, v91
	v_cvt_pk_bf16_f32 v84, v166, v92
	v_cvt_pk_bf16_f32 v90, v171, v97
	v_cvt_pk_bf16_f32 v85, v168, v94
	v_cvt_pk_bf16_f32 v89, v169, v95
	v_add_f32_e32 v92, 4.0, v117
	v_fma_f32 v93, -v157, |v92|, v118
	v_exp_f32_e32 v96, v93
	v_fma_f32 v93, -v157, |v92|, v122
	v_exp_f32_e32 v97, v93
	v_add_f32_e32 v93, -1.0, v92
	v_fma_f32 v94, -v157, |v93|, v119
	v_fma_f32 v93, -v157, |v93|, v123
	v_exp_f32_e32 v119, v93
	v_add_f32_e32 v93, -2.0, v92
	v_exp_f32_e32 v118, v94
	v_fma_f32 v94, -v157, |v93|, v120
	v_exp_f32_e32 v122, v94
	v_fma_f32 v93, -v157, |v93|, v124
	v_add_f32_e32 v92, 0xc0400000, v92
	v_exp_f32_e32 v123, v93
	v_fma_f32 v93, -v157, |v92|, v121
	v_fma_f32 v92, -v157, |v92|, v125
	v_exp_f32_e32 v121, v92
	v_fma_f32 v92, -v157, |v117|, v158
	v_exp_f32_e32 v124, v92
	v_fma_f32 v92, -v157, |v117|, v162
	v_exp_f32_e32 v125, v92
	v_add_f32_e32 v92, -1.0, v117
	v_exp_f32_e32 v120, v93
	v_fma_f32 v93, -v157, |v92|, v159
	v_fma_f32 v92, -v157, |v92|, v163
	v_exp_f32_e32 v159, v92
	v_add_f32_e32 v92, -2.0, v117
	v_exp_f32_e32 v158, v93
	v_fma_f32 v93, -v157, |v92|, v160
	v_fma_f32 v92, -v157, |v92|, v164
	v_exp_f32_e32 v162, v93
	v_exp_f32_e32 v163, v92
	v_add_f32_e32 v92, v98, v96
	v_add_f32_e32 v93, v99, v97
	v_add_f32_e32 v94, 0xc0400000, v117
	v_add_f32_e32 v92, v92, v118
	v_add_f32_e32 v93, v93, v119
	v_fma_f32 v95, -v157, |v94|, v161
	v_add_f32_e32 v92, v92, v122
	v_add_f32_e32 v93, v93, v123
	v_fma_f32 v94, -v157, |v94|, v165
	v_add_f32_e32 v92, v92, v120
	v_add_f32_e32 v93, v93, v121
	v_exp_f32_e32 v98, v95
	v_exp_f32_e32 v99, v94
	v_add_f32_e32 v92, v92, v124
	v_add_f32_e32 v93, v93, v125
	v_cvt_pk_bf16_f32 v91, v173, v91
	v_cvt_pk_bf16_f32 v94, v124, v158
	v_cvt_pk_bf16_f32 v95, v162, v98
	v_add_f32_e32 v92, v92, v158
	v_add_f32_e32 v93, v93, v159
	v_add_f32_e32 v92, v92, v162
	v_add_f32_e32 v93, v93, v163
	v_add_f32_e32 v114, v92, v98
	v_add_f32_e32 v115, v93, v99
	v_cvt_pk_bf16_f32 v92, v96, v118
	v_cvt_pk_bf16_f32 v93, v122, v120
	v_cvt_pk_bf16_f32 v96, v97, v119
	v_cvt_pk_bf16_f32 v97, v123, v121
	v_cvt_pk_bf16_f32 v98, v125, v159
	v_cvt_pk_bf16_f32 v99, v163, v99
	s_or_b64 s[18:19], s[54:55], s[0:1]
	s_and_b64 vcc, exec, s[18:19]
	s_cbranch_vccnz .LBB0_371

.LBB0_405:
	s_add_i32 s21, s0, 2
	s_add_u32 s1, vcc_lo, 0xfffe0080
	s_addc_u32 s2, vcc_hi, -1
	s_add_i32 s18, 0, 0x10000
	v_add_u32_e32 v164, s18, v178
	ds_read_b128 v[128:131], v164
	ds_read_b128 v[132:135], v164 offset:1024
	ds_read_b128 v[136:139], v164 offset:2048
	ds_read_b128 v[164:167], v164 offset:3072
	s_cmp_eq_u32 s5, s0
	s_cselect_b32 s0, s10, s17
	s_cselect_b32 s89, s9, s2
	s_cselect_b32 s88, s8, s1
	s_cselect_b32 s1, s11, s20
	v_lshl_add_u64 v[176:177], vcc, 0, v[162:163]
	s_add_i32 m0, s97, 0xc000
	ds_read_b128 v[168:171], v179
	ds_read_b128 v[172:175], v179 offset:1024
	ds_read_b128 v[180:183], v179 offset:2048
	ds_read_b128 v[184:187], v179 offset:3072
	ds_read_b128 v[188:191], v179 offset:4096
	ds_read_b128 v[192:195], v179 offset:5120
	ds_read_b128 v[196:199], v179 offset:6144
	ds_read_b128 v[200:203], v179 offset:7168
	global_load_lds_dwordx4 v[176:177], off
	v_lshl_add_u64 v[176:177], vcc, 0, v[160:161]
	s_add_i32 m0, s97, 0xe000
	s_nop 0
	global_load_lds_dwordx4 v[176:177], off
	s_waitcnt lgkmcnt(8)
	s_barrier
	s_waitcnt lgkmcnt(0)
	s_setprio 1
	v_mfma_f32_16x16x32_bf16 v[120:123], v[128:131], v[168:171], v[120:123]
	v_mfma_f32_16x16x32_bf16 v[68:71], v[136:139], v[168:171], v[68:71]
	v_mfma_f32_16x16x32_bf16 v[116:119], v[128:131], v[180:183], v[116:119]
	v_mfma_f32_16x16x32_bf16 v[60:63], v[136:139], v[180:183], v[60:63]
	v_mfma_f32_16x16x32_bf16 v[108:111], v[128:131], v[188:191], v[108:111]
	v_mfma_f32_16x16x32_bf16 v[44:47], v[136:139], v[188:191], v[44:47]
	v_mfma_f32_16x16x32_bf16 v[100:103], v[128:131], v[196:199], v[100:103]
	v_mfma_f32_16x16x32_bf16 v[36:39], v[136:139], v[196:199], v[36:39]
	v_mfma_f32_16x16x32_bf16 v[120:123], v[132:135], v[172:175], v[120:123]
	v_mfma_f32_16x16x32_bf16 v[68:71], v[164:167], v[172:175], v[68:71]
	v_mfma_f32_16x16x32_bf16 v[116:119], v[132:135], v[184:187], v[116:119]
	v_mfma_f32_16x16x32_bf16 v[60:63], v[164:167], v[184:187], v[60:63]
	v_mfma_f32_16x16x32_bf16 v[108:111], v[132:135], v[192:195], v[108:111]
	v_mfma_f32_16x16x32_bf16 v[44:47], v[164:167], v[192:195], v[44:47]
	v_mfma_f32_16x16x32_bf16 v[100:103], v[132:135], v[200:203], v[100:103]
	v_mfma_f32_16x16x32_bf16 v[36:39], v[164:167], v[200:203], v[36:39]
	s_setprio 0
	s_barrier
	s_add_i32 s2, 0, 0x14000
	v_add_u32_e32 v176, s2, v178
	s_add_i32 s18, s18, s59
	ds_read_b128 v[204:207], v176
	ds_read_b128 v[208:211], v176 offset:1024
	ds_read_b128 v[228:231], v176 offset:2048
	ds_read_b128 v[232:235], v176 offset:3072
	s_mov_b32 m0, s18
	s_nop 0
	global_load_lds_dwordx4 v140, s[0:1]
	s_add_i32 m0, s18, 0x2000
	s_nop 0
	global_load_lds_dwordx4 v158, s[0:1]
	s_barrier
	s_waitcnt lgkmcnt(0)
	s_setprio 1
	v_mfma_f32_16x16x32_bf16 v[124:127], v[204:207], v[168:171], v[124:127]
	v_mfma_f32_16x16x32_bf16 v[64:67], v[228:231], v[168:171], v[64:67]
	v_mfma_f32_16x16x32_bf16 v[112:115], v[204:207], v[180:183], v[112:115]
	v_mfma_f32_16x16x32_bf16 v[56:59], v[228:231], v[180:183], v[56:59]
	v_mfma_f32_16x16x32_bf16 v[104:107], v[204:207], v[188:191], v[104:107]
	v_mfma_f32_16x16x32_bf16 v[40:43], v[228:231], v[188:191], v[40:43]
	v_mfma_f32_16x16x32_bf16 v[96:99], v[204:207], v[196:199], v[96:99]
	v_mfma_f32_16x16x32_bf16 v[32:35], v[228:231], v[196:199], v[32:35]
	v_mfma_f32_16x16x32_bf16 v[124:127], v[208:211], v[172:175], v[124:127]
	v_mfma_f32_16x16x32_bf16 v[64:67], v[232:235], v[172:175], v[64:67]
	v_mfma_f32_16x16x32_bf16 v[112:115], v[208:211], v[184:187], v[112:115]
	v_mfma_f32_16x16x32_bf16 v[56:59], v[232:235], v[184:187], v[56:59]
	v_mfma_f32_16x16x32_bf16 v[104:107], v[208:211], v[192:195], v[104:107]
	v_mfma_f32_16x16x32_bf16 v[40:43], v[232:235], v[192:195], v[40:43]
	v_mfma_f32_16x16x32_bf16 v[96:99], v[208:211], v[200:203], v[96:99]
	v_mfma_f32_16x16x32_bf16 v[32:35], v[232:235], v[200:203], v[32:35]
	s_setprio 0
	s_mov_b32 m0, s97
	s_barrier
	ds_read_b128 v[168:171], v179 offset:16384
	ds_read_b128 v[172:175], v179 offset:17408
	ds_read_b128 v[180:183], v179 offset:18432
	ds_read_b128 v[184:187], v179 offset:19456
	ds_read_b128 v[188:191], v179 offset:20480
	ds_read_b128 v[192:195], v179 offset:21504
	ds_read_b128 v[196:199], v179 offset:22528
	ds_read_b128 v[200:203], v179 offset:23552
	global_load_lds_dwordx4 v154, s[88:89]
	s_mov_b32 m0, s74
	s_nop 0
	global_load_lds_dwordx4 v156, s[88:89]
	s_barrier
	s_waitcnt lgkmcnt(0)
	s_setprio 1
	v_mfma_f32_16x16x32_bf16 v[92:95], v[128:131], v[168:171], v[92:95]
	v_mfma_f32_16x16x32_bf16 v[28:31], v[136:139], v[168:171], v[28:31]
	v_mfma_f32_16x16x32_bf16 v[84:87], v[128:131], v[180:183], v[84:87]
	v_mfma_f32_16x16x32_bf16 v[20:23], v[136:139], v[180:183], v[20:23]
	v_mfma_f32_16x16x32_bf16 v[76:79], v[128:131], v[188:191], v[76:79]
	v_mfma_f32_16x16x32_bf16 v[12:15], v[136:139], v[188:191], v[12:15]
	v_mfma_f32_16x16x32_bf16 v[52:55], v[128:131], v[196:199], v[52:55]
	v_mfma_f32_16x16x32_bf16 v[4:7], v[136:139], v[196:199], v[4:7]
	v_mfma_f32_16x16x32_bf16 v[92:95], v[132:135], v[172:175], v[92:95]
	v_mfma_f32_16x16x32_bf16 v[28:31], v[164:167], v[172:175], v[28:31]
	v_mfma_f32_16x16x32_bf16 v[84:87], v[132:135], v[184:187], v[84:87]
	v_mfma_f32_16x16x32_bf16 v[20:23], v[164:167], v[184:187], v[20:23]
	v_mfma_f32_16x16x32_bf16 v[76:79], v[132:135], v[192:195], v[76:79]
	v_mfma_f32_16x16x32_bf16 v[12:15], v[164:167], v[192:195], v[12:15]
	v_mfma_f32_16x16x32_bf16 v[52:55], v[132:135], v[200:203], v[52:55]
	v_mfma_f32_16x16x32_bf16 v[4:7], v[164:167], v[200:203], v[4:7]
	s_setprio 0
	s_barrier
	s_add_u32 s18, s0, 0x10000
	s_addc_u32 s19, s1, 0
	s_add_i32 s2, s2, s59
	s_mov_b32 m0, s2
	s_nop 0
	global_load_lds_dwordx4 v140, s[18:19]
	s_add_i32 m0, s2, 0x2000
	s_nop 0
	global_load_lds_dwordx4 v158, s[18:19]
	s_waitcnt vmcnt(6)
	s_barrier
	s_setprio 1
	v_mfma_f32_16x16x32_bf16 v[88:91], v[204:207], v[168:171], v[88:91]
	v_mfma_f32_16x16x32_bf16 v[24:27], v[228:231], v[168:171], v[24:27]
	v_mfma_f32_16x16x32_bf16 v[80:83], v[204:207], v[180:183], v[80:83]
	v_mfma_f32_16x16x32_bf16 v[16:19], v[228:231], v[180:183], v[16:19]
	v_mfma_f32_16x16x32_bf16 v[72:75], v[204:207], v[188:191], v[72:75]
	v_mfma_f32_16x16x32_bf16 v[8:11], v[228:231], v[188:191], v[8:11]
	v_mfma_f32_16x16x32_bf16 v[48:51], v[204:207], v[196:199], v[48:51]
	v_mfma_f32_16x16x32_bf16 v[0:3], v[228:231], v[196:199], v[0:3]
	v_mfma_f32_16x16x32_bf16 v[88:91], v[208:211], v[172:175], v[88:91]
	v_mfma_f32_16x16x32_bf16 v[24:27], v[232:235], v[172:175], v[24:27]
	v_mfma_f32_16x16x32_bf16 v[80:83], v[208:211], v[184:187], v[80:83]
	v_mfma_f32_16x16x32_bf16 v[16:19], v[232:235], v[184:187], v[16:19]
	v_mfma_f32_16x16x32_bf16 v[72:75], v[208:211], v[192:195], v[72:75]
	v_mfma_f32_16x16x32_bf16 v[8:11], v[232:235], v[192:195], v[8:11]
	v_mfma_f32_16x16x32_bf16 v[48:51], v[208:211], v[200:203], v[48:51]
	v_mfma_f32_16x16x32_bf16 v[0:3], v[232:235], v[200:203], v[0:3]
	s_setprio 0
	s_add_i32 s2, 0, 0x18000
	v_add_u32_e32 v164, s2, v178
	s_barrier
	ds_read_b128 v[128:131], v164
	ds_read_b128 v[132:135], v164 offset:1024
	ds_read_b128 v[136:139], v164 offset:2048
	ds_read_b128 v[164:167], v164 offset:3072
	s_add_u32 s18, s88, 0x20000
	s_addc_u32 s19, s89, 0
	s_mov_b32 m0, s75
	ds_read_b128 v[168:171], v179 offset:32768
	ds_read_b128 v[172:175], v179 offset:33792
	ds_read_b128 v[180:183], v179 offset:34816
	ds_read_b128 v[184:187], v179 offset:35840
	ds_read_b128 v[188:191], v179 offset:36864
	ds_read_b128 v[192:195], v179 offset:37888
	ds_read_b128 v[196:199], v179 offset:38912
	ds_read_b128 v[200:203], v179 offset:39936
	global_load_lds_dwordx4 v154, s[18:19]
	s_mov_b32 m0, s72
	s_nop 0
	global_load_lds_dwordx4 v156, s[18:19]
	s_waitcnt lgkmcnt(8)
	s_barrier
	s_waitcnt lgkmcnt(0)
	s_setprio 1
	v_mfma_f32_16x16x32_bf16 v[120:123], v[128:131], v[168:171], v[120:123]
	v_mfma_f32_16x16x32_bf16 v[68:71], v[136:139], v[168:171], v[68:71]
	v_mfma_f32_16x16x32_bf16 v[116:119], v[128:131], v[180:183], v[116:119]
	v_mfma_f32_16x16x32_bf16 v[60:63], v[136:139], v[180:183], v[60:63]
	v_mfma_f32_16x16x32_bf16 v[108:111], v[128:131], v[188:191], v[108:111]
	v_mfma_f32_16x16x32_bf16 v[44:47], v[136:139], v[188:191], v[44:47]
	v_mfma_f32_16x16x32_bf16 v[100:103], v[128:131], v[196:199], v[100:103]
	v_mfma_f32_16x16x32_bf16 v[36:39], v[136:139], v[196:199], v[36:39]
	v_mfma_f32_16x16x32_bf16 v[120:123], v[132:135], v[172:175], v[120:123]
	v_mfma_f32_16x16x32_bf16 v[68:71], v[164:167], v[172:175], v[68:71]
	v_mfma_f32_16x16x32_bf16 v[116:119], v[132:135], v[184:187], v[116:119]
	v_mfma_f32_16x16x32_bf16 v[60:63], v[164:167], v[184:187], v[60:63]
	v_mfma_f32_16x16x32_bf16 v[108:111], v[132:135], v[192:195], v[108:111]
	v_mfma_f32_16x16x32_bf16 v[44:47], v[164:167], v[192:195], v[44:47]
	v_mfma_f32_16x16x32_bf16 v[100:103], v[132:135], v[200:203], v[100:103]
	v_mfma_f32_16x16x32_bf16 v[36:39], v[164:167], v[200:203], v[36:39]
	s_setprio 0
	s_barrier
	s_add_i32 s18, 0, 0x1c000
	s_add_i32 s2, s2, s59
	v_add_u32_e32 v232, s18, v178
	s_mov_b32 m0, s2
	ds_read_b128 v[204:207], v232
	ds_read_b128 v[208:211], v232 offset:1024
	ds_read_b128 v[228:231], v232 offset:2048
	ds_read_b128 v[232:235], v232 offset:3072
	s_add_u32 s100, s0, 0x80
	s_addc_u32 s101, s1, 0
	global_load_lds_dwordx4 v140, s[100:101]
	s_add_i32 m0, s2, 0x2000
	s_nop 0
	global_load_lds_dwordx4 v158, s[100:101]
	s_barrier
	s_waitcnt lgkmcnt(0)
	s_setprio 1
	v_mfma_f32_16x16x32_bf16 v[124:127], v[204:207], v[168:171], v[124:127]
	v_mfma_f32_16x16x32_bf16 v[64:67], v[228:231], v[168:171], v[64:67]
	v_mfma_f32_16x16x32_bf16 v[112:115], v[204:207], v[180:183], v[112:115]
	v_mfma_f32_16x16x32_bf16 v[56:59], v[228:231], v[180:183], v[56:59]
	v_mfma_f32_16x16x32_bf16 v[104:107], v[204:207], v[188:191], v[104:107]
	v_mfma_f32_16x16x32_bf16 v[40:43], v[228:231], v[188:191], v[40:43]
	v_mfma_f32_16x16x32_bf16 v[96:99], v[204:207], v[196:199], v[96:99]
	v_mfma_f32_16x16x32_bf16 v[32:35], v[228:231], v[196:199], v[32:35]
	v_mfma_f32_16x16x32_bf16 v[124:127], v[208:211], v[172:175], v[124:127]
	v_mfma_f32_16x16x32_bf16 v[64:67], v[232:235], v[172:175], v[64:67]
	v_mfma_f32_16x16x32_bf16 v[112:115], v[208:211], v[184:187], v[112:115]
	v_mfma_f32_16x16x32_bf16 v[56:59], v[232:235], v[184:187], v[56:59]
	v_mfma_f32_16x16x32_bf16 v[104:107], v[208:211], v[192:195], v[104:107]
	v_mfma_f32_16x16x32_bf16 v[40:43], v[232:235], v[192:195], v[40:43]
	v_mfma_f32_16x16x32_bf16 v[96:99], v[208:211], v[200:203], v[96:99]
	v_mfma_f32_16x16x32_bf16 v[32:35], v[232:235], v[200:203], v[32:35]
	s_setprio 0
	s_mov_b32 m0, s38
	s_barrier
	ds_read_b128 v[168:171], v179 offset:49152
	ds_read_b128 v[172:175], v179 offset:50176
	ds_read_b128 v[180:183], v179 offset:51200
	ds_read_b128 v[184:187], v179 offset:52224
	ds_read_b128 v[188:191], v179 offset:53248
	ds_read_b128 v[192:195], v179 offset:54272
	ds_read_b128 v[196:199], v179 offset:55296
	ds_read_b128 v[200:203], v179 offset:56320
	s_add_u32 s100, s88, 0x80
	s_addc_u32 s101, s89, 0
	global_load_lds_dwordx4 v154, s[100:101]
	s_mov_b32 m0, s39
	s_nop 0
	global_load_lds_dwordx4 v156, s[100:101]
	s_barrier
	s_waitcnt lgkmcnt(0)
	s_setprio 1
	v_mfma_f32_16x16x32_bf16 v[92:95], v[128:131], v[168:171], v[92:95]
	v_mfma_f32_16x16x32_bf16 v[28:31], v[136:139], v[168:171], v[28:31]
	v_mfma_f32_16x16x32_bf16 v[84:87], v[128:131], v[180:183], v[84:87]
	v_mfma_f32_16x16x32_bf16 v[20:23], v[136:139], v[180:183], v[20:23]
	v_mfma_f32_16x16x32_bf16 v[76:79], v[128:131], v[188:191], v[76:79]
	v_mfma_f32_16x16x32_bf16 v[12:15], v[136:139], v[188:191], v[12:15]
	v_mfma_f32_16x16x32_bf16 v[52:55], v[128:131], v[196:199], v[52:55]
	v_mfma_f32_16x16x32_bf16 v[4:7], v[136:139], v[196:199], v[4:7]
	v_mfma_f32_16x16x32_bf16 v[92:95], v[132:135], v[172:175], v[92:95]
	v_mfma_f32_16x16x32_bf16 v[28:31], v[164:167], v[172:175], v[28:31]
	v_mfma_f32_16x16x32_bf16 v[84:87], v[132:135], v[184:187], v[84:87]
	v_mfma_f32_16x16x32_bf16 v[20:23], v[164:167], v[184:187], v[20:23]
	v_mfma_f32_16x16x32_bf16 v[76:79], v[132:135], v[192:195], v[76:79]
	v_mfma_f32_16x16x32_bf16 v[12:15], v[164:167], v[192:195], v[12:15]
	v_mfma_f32_16x16x32_bf16 v[52:55], v[132:135], v[200:203], v[52:55]
	v_mfma_f32_16x16x32_bf16 v[4:7], v[164:167], v[200:203], v[4:7]
	s_setprio 0
	s_barrier
	s_add_u32 s0, s0, 0x10080
	s_addc_u32 s1, s1, 0
	s_add_i32 s2, s18, s59
	s_mov_b32 m0, s2
	s_nop 0
	global_load_lds_dwordx4 v140, s[0:1]
	s_add_i32 m0, s2, 0x2000
	s_nop 0
	global_load_lds_dwordx4 v158, s[0:1]
	s_waitcnt vmcnt(6)
	s_barrier
	s_setprio 1
	v_mfma_f32_16x16x32_bf16 v[88:91], v[204:207], v[168:171], v[88:91]
	v_mfma_f32_16x16x32_bf16 v[24:27], v[228:231], v[168:171], v[24:27]
	v_mfma_f32_16x16x32_bf16 v[80:83], v[204:207], v[180:183], v[80:83]
	v_mfma_f32_16x16x32_bf16 v[16:19], v[228:231], v[180:183], v[16:19]
	v_mfma_f32_16x16x32_bf16 v[72:75], v[204:207], v[188:191], v[72:75]
	v_mfma_f32_16x16x32_bf16 v[8:11], v[228:231], v[188:191], v[8:11]
	v_mfma_f32_16x16x32_bf16 v[48:51], v[204:207], v[196:199], v[48:51]
	v_mfma_f32_16x16x32_bf16 v[0:3], v[228:231], v[196:199], v[0:3]
	v_mfma_f32_16x16x32_bf16 v[88:91], v[208:211], v[172:175], v[88:91]
	v_mfma_f32_16x16x32_bf16 v[24:27], v[232:235], v[172:175], v[24:27]
	v_mfma_f32_16x16x32_bf16 v[80:83], v[208:211], v[184:187], v[80:83]
	v_mfma_f32_16x16x32_bf16 v[16:19], v[232:235], v[184:187], v[16:19]
	v_mfma_f32_16x16x32_bf16 v[72:75], v[208:211], v[192:195], v[72:75]
	v_mfma_f32_16x16x32_bf16 v[8:11], v[232:235], v[192:195], v[8:11]
	v_mfma_f32_16x16x32_bf16 v[48:51], v[208:211], v[200:203], v[48:51]
	v_mfma_f32_16x16x32_bf16 v[0:3], v[232:235], v[200:203], v[0:3]
	s_setprio 0
	s_add_u32 s17, s17, 0x100
	s_addc_u32 s20, s20, 0
	s_add_u32 vcc_lo, vcc_lo, 0x100
	s_addc_u32 vcc_hi, vcc_hi, 0
	s_cmp_ge_i32 s21, s36
	s_mov_b32 s0, s21
	s_barrier
	s_cbranch_scc0 .LBB0_405
	s_branch .LBB0_392

.LBB0_507:
	s_add_u32 s0, s8, 0xfffc0080
	s_addc_u32 s1, s9, -1
	s_add_i32 s2, 0, 0x10000
	v_add_u32_e32 v140, s2, v168
	ds_read_b128 v[154:157], v140
	ds_read_b128 v[158:161], v140 offset:1024
	ds_read_b128 v[162:165], v140 offset:2048
	ds_read_b128 v[170:173], v140 offset:3072
	s_cmp_eq_u32 s21, 12
	s_cselect_b32 s31, s29, s1
	s_cselect_b32 s30, s28, s0
	s_cselect_b32 s1, s11, s19
	s_cselect_b32 s0, s10, s17
	s_add_i32 m0, s36, 0xc000
	ds_read_b128 v[174:177], v169
	ds_read_b128 v[178:181], v169 offset:1024
	ds_read_b128 v[182:185], v169 offset:2048
	ds_read_b128 v[186:189], v169 offset:3072
	ds_read_b128 v[190:193], v169 offset:4096
	ds_read_b128 v[194:197], v169 offset:5120
	ds_read_b128 v[198:201], v169 offset:6144
	ds_read_b128 v[202:205], v169 offset:7168
	global_load_lds_dwordx4 v138, s[8:9]
	s_add_i32 m0, s36, 0xe000
	s_nop 0
	global_load_lds_dwordx4 v136, s[8:9]
	s_waitcnt lgkmcnt(8)
	s_barrier
	s_waitcnt lgkmcnt(0)
	s_setprio 1
	v_mfma_f32_16x16x32_bf16 v[124:127], v[154:157], v[174:177], v[124:127]
	v_mfma_f32_16x16x32_bf16 v[120:123], v[162:165], v[174:177], v[120:123]
	v_mfma_f32_16x16x32_bf16 v[112:115], v[154:157], v[182:185], v[112:115]
	v_mfma_f32_16x16x32_bf16 v[104:107], v[162:165], v[182:185], v[104:107]
	v_mfma_f32_16x16x32_bf16 v[96:99], v[154:157], v[190:193], v[96:99]
	v_mfma_f32_16x16x32_bf16 v[88:91], v[162:165], v[190:193], v[88:91]
	v_mfma_f32_16x16x32_bf16 v[80:83], v[154:157], v[198:201], v[80:83]
	v_mfma_f32_16x16x32_bf16 v[72:75], v[162:165], v[198:201], v[72:75]
	v_mfma_f32_16x16x32_bf16 v[124:127], v[158:161], v[178:181], v[124:127]
	v_mfma_f32_16x16x32_bf16 v[120:123], v[170:173], v[178:181], v[120:123]
	v_mfma_f32_16x16x32_bf16 v[112:115], v[158:161], v[186:189], v[112:115]
	v_mfma_f32_16x16x32_bf16 v[104:107], v[170:173], v[186:189], v[104:107]
	v_mfma_f32_16x16x32_bf16 v[96:99], v[158:161], v[194:197], v[96:99]
	v_mfma_f32_16x16x32_bf16 v[88:91], v[170:173], v[194:197], v[88:91]
	v_mfma_f32_16x16x32_bf16 v[80:83], v[158:161], v[202:205], v[80:83]
	v_mfma_f32_16x16x32_bf16 v[72:75], v[170:173], v[202:205], v[72:75]
	s_setprio 0
	s_barrier
	s_add_i32 s49, 0, 0x14000
	s_add_i32 s2, s2, s35
	v_add_u32_e32 v140, s49, v168
	s_mov_b32 m0, s2
	ds_read_b128 v[206:209], v140
	ds_read_b128 v[228:231], v140 offset:1024
	ds_read_b128 v[232:235], v140 offset:2048
	ds_read_b128 v[236:239], v140 offset:3072
	global_load_lds_dwordx4 v130, s[0:1]
	s_add_i32 m0, s2, 0x2000
	s_nop 0
	global_load_lds_dwordx4 v134, s[0:1]
	s_barrier
	s_waitcnt lgkmcnt(0)
	s_setprio 1
	v_mfma_f32_16x16x32_bf16 v[116:119], v[206:209], v[174:177], v[116:119]
	v_mfma_f32_16x16x32_bf16 v[108:111], v[232:235], v[174:177], v[108:111]
	v_mfma_f32_16x16x32_bf16 v[100:103], v[206:209], v[182:185], v[100:103]
	v_mfma_f32_16x16x32_bf16 v[92:95], v[232:235], v[182:185], v[92:95]
	v_mfma_f32_16x16x32_bf16 v[84:87], v[206:209], v[190:193], v[84:87]
	v_mfma_f32_16x16x32_bf16 v[76:79], v[232:235], v[190:193], v[76:79]
	v_mfma_f32_16x16x32_bf16 v[68:71], v[206:209], v[198:201], v[68:71]
	v_mfma_f32_16x16x32_bf16 v[64:67], v[232:235], v[198:201], v[64:67]
	v_mfma_f32_16x16x32_bf16 v[116:119], v[228:231], v[178:181], v[116:119]
	v_mfma_f32_16x16x32_bf16 v[108:111], v[236:239], v[178:181], v[108:111]
	v_mfma_f32_16x16x32_bf16 v[100:103], v[228:231], v[186:189], v[100:103]
	v_mfma_f32_16x16x32_bf16 v[92:95], v[236:239], v[186:189], v[92:95]
	v_mfma_f32_16x16x32_bf16 v[84:87], v[228:231], v[194:197], v[84:87]
	v_mfma_f32_16x16x32_bf16 v[76:79], v[236:239], v[194:197], v[76:79]
	v_mfma_f32_16x16x32_bf16 v[68:71], v[228:231], v[202:205], v[68:71]
	v_mfma_f32_16x16x32_bf16 v[64:67], v[236:239], v[202:205], v[64:67]
	s_setprio 0
	s_mov_b32 m0, s36
	v_lshl_add_u64 v[240:241], s[30:31], 0, v[128:129]
	s_barrier
	ds_read_b128 v[174:177], v169 offset:16384
	ds_read_b128 v[178:181], v169 offset:17408
	ds_read_b128 v[182:185], v169 offset:18432
	ds_read_b128 v[186:189], v169 offset:19456
	ds_read_b128 v[190:193], v169 offset:20480
	ds_read_b128 v[194:197], v169 offset:21504
	ds_read_b128 v[198:201], v169 offset:22528
	ds_read_b128 v[202:205], v169 offset:23552
	global_load_lds_dwordx4 v128, s[30:31]
	v_lshl_add_u64 v[242:243], s[30:31], 0, v[132:133]
	s_mov_b32 m0, s37
	s_nop 0
	global_load_lds_dwordx4 v132, s[30:31]
	s_barrier
	s_waitcnt lgkmcnt(0)
	s_setprio 1
	v_mfma_f32_16x16x32_bf16 v[60:63], v[154:157], v[174:177], v[60:63]
	v_mfma_f32_16x16x32_bf16 v[56:59], v[162:165], v[174:177], v[56:59]
	v_mfma_f32_16x16x32_bf16 v[48:51], v[154:157], v[182:185], v[48:51]
	v_mfma_f32_16x16x32_bf16 v[40:43], v[162:165], v[182:185], v[40:43]
	v_mfma_f32_16x16x32_bf16 v[32:35], v[154:157], v[190:193], v[32:35]
	v_mfma_f32_16x16x32_bf16 v[24:27], v[162:165], v[190:193], v[24:27]
	v_mfma_f32_16x16x32_bf16 v[16:19], v[154:157], v[198:201], v[16:19]
	v_mfma_f32_16x16x32_bf16 v[8:11], v[162:165], v[198:201], v[8:11]
	v_mfma_f32_16x16x32_bf16 v[60:63], v[158:161], v[178:181], v[60:63]
	v_mfma_f32_16x16x32_bf16 v[56:59], v[170:173], v[178:181], v[56:59]
	v_mfma_f32_16x16x32_bf16 v[48:51], v[158:161], v[186:189], v[48:51]
	v_mfma_f32_16x16x32_bf16 v[40:43], v[170:173], v[186:189], v[40:43]
	v_mfma_f32_16x16x32_bf16 v[32:35], v[158:161], v[194:197], v[32:35]
	v_mfma_f32_16x16x32_bf16 v[24:27], v[170:173], v[194:197], v[24:27]
	v_mfma_f32_16x16x32_bf16 v[16:19], v[158:161], v[202:205], v[16:19]
	v_mfma_f32_16x16x32_bf16 v[8:11], v[170:173], v[202:205], v[8:11]
	s_setprio 0
	s_barrier
	s_add_u32 s42, s0, 0x40000
	s_addc_u32 s43, s1, 0
	s_add_i32 s2, s49, s35
	s_mov_b32 m0, s2
	s_nop 0
	global_load_lds_dwordx4 v130, s[42:43]
	s_add_i32 m0, s2, 0x2000
	s_nop 0
	global_load_lds_dwordx4 v134, s[42:43]
	s_waitcnt vmcnt(6)
	s_barrier
	s_setprio 1
	v_mfma_f32_16x16x32_bf16 v[52:55], v[206:209], v[174:177], v[52:55]
	v_mfma_f32_16x16x32_bf16 v[44:47], v[232:235], v[174:177], v[44:47]
	v_mfma_f32_16x16x32_bf16 v[36:39], v[206:209], v[182:185], v[36:39]
	v_mfma_f32_16x16x32_bf16 v[28:31], v[232:235], v[182:185], v[28:31]
	v_mfma_f32_16x16x32_bf16 v[20:23], v[206:209], v[190:193], v[20:23]
	v_mfma_f32_16x16x32_bf16 v[12:15], v[232:235], v[190:193], v[12:15]
	v_mfma_f32_16x16x32_bf16 v[4:7], v[206:209], v[198:201], v[4:7]
	v_mfma_f32_16x16x32_bf16 v[0:3], v[232:235], v[198:201], v[0:3]
	v_mfma_f32_16x16x32_bf16 v[52:55], v[228:231], v[178:181], v[52:55]
	v_mfma_f32_16x16x32_bf16 v[44:47], v[236:239], v[178:181], v[44:47]
	v_mfma_f32_16x16x32_bf16 v[36:39], v[228:231], v[186:189], v[36:39]
	v_mfma_f32_16x16x32_bf16 v[28:31], v[236:239], v[186:189], v[28:31]
	v_mfma_f32_16x16x32_bf16 v[20:23], v[228:231], v[194:197], v[20:23]
	v_mfma_f32_16x16x32_bf16 v[12:15], v[236:239], v[194:197], v[12:15]
	v_mfma_f32_16x16x32_bf16 v[4:7], v[228:231], v[202:205], v[4:7]
	v_mfma_f32_16x16x32_bf16 v[0:3], v[236:239], v[202:205], v[0:3]
	s_setprio 0
	s_add_i32 s2, 0, 0x18000
	v_add_u32_e32 v140, s2, v168
	s_barrier
	ds_read_b128 v[154:157], v140
	ds_read_b128 v[158:161], v140 offset:1024
	ds_read_b128 v[162:165], v140 offset:2048
	ds_read_b128 v[170:173], v140 offset:3072
	s_add_u32 s30, s30, 0x40000
	s_addc_u32 s31, s31, 0
	s_mov_b32 m0, s38
	ds_read_b128 v[174:177], v169 offset:32768
	ds_read_b128 v[178:181], v169 offset:33792
	ds_read_b128 v[182:185], v169 offset:34816
	ds_read_b128 v[186:189], v169 offset:35840
	ds_read_b128 v[190:193], v169 offset:36864
	ds_read_b128 v[194:197], v169 offset:37888
	ds_read_b128 v[198:201], v169 offset:38912
	ds_read_b128 v[202:205], v169 offset:39936
	global_load_lds_dwordx4 v128, s[30:31]
	s_mov_b32 m0, s39
	s_nop 0
	global_load_lds_dwordx4 v132, s[30:31]
	s_waitcnt lgkmcnt(8)
	s_barrier
	s_waitcnt lgkmcnt(0)
	s_setprio 1
	v_mfma_f32_16x16x32_bf16 v[124:127], v[154:157], v[174:177], v[124:127]
	v_mfma_f32_16x16x32_bf16 v[120:123], v[162:165], v[174:177], v[120:123]
	v_mfma_f32_16x16x32_bf16 v[112:115], v[154:157], v[182:185], v[112:115]
	v_mfma_f32_16x16x32_bf16 v[104:107], v[162:165], v[182:185], v[104:107]
	v_mfma_f32_16x16x32_bf16 v[96:99], v[154:157], v[190:193], v[96:99]
	v_mfma_f32_16x16x32_bf16 v[88:91], v[162:165], v[190:193], v[88:91]
	v_mfma_f32_16x16x32_bf16 v[80:83], v[154:157], v[198:201], v[80:83]
	v_mfma_f32_16x16x32_bf16 v[72:75], v[162:165], v[198:201], v[72:75]
	v_mfma_f32_16x16x32_bf16 v[124:127], v[158:161], v[178:181], v[124:127]
	v_mfma_f32_16x16x32_bf16 v[120:123], v[170:173], v[178:181], v[120:123]
	v_mfma_f32_16x16x32_bf16 v[112:115], v[158:161], v[186:189], v[112:115]
	v_mfma_f32_16x16x32_bf16 v[104:107], v[170:173], v[186:189], v[104:107]
	v_mfma_f32_16x16x32_bf16 v[96:99], v[158:161], v[194:197], v[96:99]
	v_mfma_f32_16x16x32_bf16 v[88:91], v[170:173], v[194:197], v[88:91]
	v_mfma_f32_16x16x32_bf16 v[80:83], v[158:161], v[202:205], v[80:83]
	v_mfma_f32_16x16x32_bf16 v[72:75], v[170:173], v[202:205], v[72:75]
	s_setprio 0
	s_barrier
	s_add_i32 s30, 0, 0x1c000
	s_add_i32 s2, s2, s35
	v_add_u32_e32 v140, s30, v168
	s_mov_b32 m0, s2
	ds_read_b128 v[206:209], v140
	ds_read_b128 v[228:231], v140 offset:1024
	ds_read_b128 v[232:235], v140 offset:2048
	ds_read_b128 v[236:239], v140 offset:3072
	s_add_u32 s100, s0, 0x80
	s_addc_u32 s101, s1, 0
	global_load_lds_dwordx4 v130, s[100:101]
	s_add_i32 m0, s2, 0x2000
	s_nop 0
	global_load_lds_dwordx4 v134, s[100:101]
	s_barrier
	s_waitcnt lgkmcnt(0)
	s_setprio 1
	v_mfma_f32_16x16x32_bf16 v[116:119], v[206:209], v[174:177], v[116:119]
	v_mfma_f32_16x16x32_bf16 v[108:111], v[232:235], v[174:177], v[108:111]
	v_mfma_f32_16x16x32_bf16 v[100:103], v[206:209], v[182:185], v[100:103]
	v_mfma_f32_16x16x32_bf16 v[92:95], v[232:235], v[182:185], v[92:95]
	v_mfma_f32_16x16x32_bf16 v[84:87], v[206:209], v[190:193], v[84:87]
	v_mfma_f32_16x16x32_bf16 v[76:79], v[232:235], v[190:193], v[76:79]
	v_mfma_f32_16x16x32_bf16 v[68:71], v[206:209], v[198:201], v[68:71]
	v_mfma_f32_16x16x32_bf16 v[64:67], v[232:235], v[198:201], v[64:67]
	v_mfma_f32_16x16x32_bf16 v[116:119], v[228:231], v[178:181], v[116:119]
	v_mfma_f32_16x16x32_bf16 v[108:111], v[236:239], v[178:181], v[108:111]
	v_mfma_f32_16x16x32_bf16 v[100:103], v[228:231], v[186:189], v[100:103]
	v_mfma_f32_16x16x32_bf16 v[92:95], v[236:239], v[186:189], v[92:95]
	v_mfma_f32_16x16x32_bf16 v[84:87], v[228:231], v[194:197], v[84:87]
	v_mfma_f32_16x16x32_bf16 v[76:79], v[236:239], v[194:197], v[76:79]
	v_mfma_f32_16x16x32_bf16 v[68:71], v[228:231], v[202:205], v[68:71]
	v_mfma_f32_16x16x32_bf16 v[64:67], v[236:239], v[202:205], v[64:67]
	s_setprio 0
	s_mov_b32 m0, s44
	v_lshl_add_u64 v[166:167], v[240:241], 0, s[82:83]
	s_barrier
	ds_read_b128 v[174:177], v169 offset:49152
	ds_read_b128 v[178:181], v169 offset:50176
	ds_read_b128 v[182:185], v169 offset:51200
	ds_read_b128 v[186:189], v169 offset:52224
	ds_read_b128 v[190:193], v169 offset:53248
	ds_read_b128 v[194:197], v169 offset:54272
	ds_read_b128 v[198:201], v169 offset:55296
	ds_read_b128 v[202:205], v169 offset:56320
	global_load_lds_dwordx4 v[166:167], off
	v_lshl_add_u64 v[166:167], v[242:243], 0, s[82:83]
	s_mov_b32 m0, s45
	s_nop 0
	global_load_lds_dwordx4 v[166:167], off
	s_barrier
	s_waitcnt lgkmcnt(0)
	s_setprio 1
	v_mfma_f32_16x16x32_bf16 v[60:63], v[154:157], v[174:177], v[60:63]
	v_mfma_f32_16x16x32_bf16 v[56:59], v[162:165], v[174:177], v[56:59]
	v_mfma_f32_16x16x32_bf16 v[48:51], v[154:157], v[182:185], v[48:51]
	v_mfma_f32_16x16x32_bf16 v[40:43], v[162:165], v[182:185], v[40:43]
	v_mfma_f32_16x16x32_bf16 v[32:35], v[154:157], v[190:193], v[32:35]
	v_mfma_f32_16x16x32_bf16 v[24:27], v[162:165], v[190:193], v[24:27]
	v_mfma_f32_16x16x32_bf16 v[16:19], v[154:157], v[198:201], v[16:19]
	v_mfma_f32_16x16x32_bf16 v[8:11], v[162:165], v[198:201], v[8:11]
	v_mfma_f32_16x16x32_bf16 v[60:63], v[158:161], v[178:181], v[60:63]
	v_mfma_f32_16x16x32_bf16 v[56:59], v[170:173], v[178:181], v[56:59]
	v_mfma_f32_16x16x32_bf16 v[48:51], v[158:161], v[186:189], v[48:51]
	v_mfma_f32_16x16x32_bf16 v[40:43], v[170:173], v[186:189], v[40:43]
	v_mfma_f32_16x16x32_bf16 v[32:35], v[158:161], v[194:197], v[32:35]
	v_mfma_f32_16x16x32_bf16 v[24:27], v[170:173], v[194:197], v[24:27]
	v_mfma_f32_16x16x32_bf16 v[16:19], v[158:161], v[202:205], v[16:19]
	v_mfma_f32_16x16x32_bf16 v[8:11], v[170:173], v[202:205], v[8:11]
	s_setprio 0
	s_barrier
	s_add_u32 s0, s0, 0x40080
	s_addc_u32 s1, s1, 0
	s_add_i32 s2, s30, s35
	s_mov_b32 m0, s2
	s_nop 0
	global_load_lds_dwordx4 v130, s[0:1]
	s_add_i32 m0, s2, 0x2000
	s_nop 0
	global_load_lds_dwordx4 v134, s[0:1]
	s_waitcnt vmcnt(6)
	s_barrier
	s_setprio 1
	v_mfma_f32_16x16x32_bf16 v[52:55], v[206:209], v[174:177], v[52:55]
	v_mfma_f32_16x16x32_bf16 v[44:47], v[232:235], v[174:177], v[44:47]
	v_mfma_f32_16x16x32_bf16 v[36:39], v[206:209], v[182:185], v[36:39]
	v_mfma_f32_16x16x32_bf16 v[28:31], v[232:235], v[182:185], v[28:31]
	v_mfma_f32_16x16x32_bf16 v[20:23], v[206:209], v[190:193], v[20:23]
	v_mfma_f32_16x16x32_bf16 v[12:15], v[232:235], v[190:193], v[12:15]
	v_mfma_f32_16x16x32_bf16 v[4:7], v[206:209], v[198:201], v[4:7]
	v_mfma_f32_16x16x32_bf16 v[0:3], v[232:235], v[198:201], v[0:3]
	v_mfma_f32_16x16x32_bf16 v[52:55], v[228:231], v[178:181], v[52:55]
	v_mfma_f32_16x16x32_bf16 v[44:47], v[236:239], v[178:181], v[44:47]
	v_mfma_f32_16x16x32_bf16 v[36:39], v[228:231], v[186:189], v[36:39]
	v_mfma_f32_16x16x32_bf16 v[28:31], v[236:239], v[186:189], v[28:31]
	v_mfma_f32_16x16x32_bf16 v[20:23], v[228:231], v[194:197], v[20:23]
	v_mfma_f32_16x16x32_bf16 v[12:15], v[236:239], v[194:197], v[12:15]
	v_mfma_f32_16x16x32_bf16 v[4:7], v[228:231], v[202:205], v[4:7]
	v_mfma_f32_16x16x32_bf16 v[0:3], v[236:239], v[202:205], v[0:3]
	s_setprio 0
	s_add_i32 s21, s21, 2
	s_add_u32 s17, s17, 0x100
	s_addc_u32 s19, s19, 0
	s_add_u32 s8, s8, 0x100
	s_addc_u32 s9, s9, 0
	s_cmp_gt_u32 s21, 13
	s_barrier
	s_cbranch_scc0 .LBB0_507
	v_mbcnt_lo_u32_b32 v154, -1, 0
	v_mbcnt_hi_u32_b32 v154, -1, v154
	s_lshl_b32 s19, s16, 8
	v_and_b32_e32 v140, 15, v154
	v_ashrrev_i32_e32 v154, 1, v154
	s_cmp_lt_i32 s48, 8
	v_and_b32_e32 v170, -8, v154
	s_mov_b64 s[0:1], -1
	s_cbranch_scc0 .LBB0_552
	s_ashr_i32 s2, s48, 1
	s_mov_b32 s30, 0x3e38aa3b
	s_cmp_lt_u32 s48, 2
	s_mov_b64 s[8:9], s[24:25]
	s_cbranch_scc1 .LBB0_519
	s_cmp_lt_i32 s2, 2
	s_cbranch_scc1 .LBB0_514
	s_cmp_eq_u32 s2, 2
	s_cbranch_scc0 .LBB0_513
	s_mov_b64 s[0:1], 0
